# flat->global, pipelined EpiResid epilogues, prep S3 rewrite, scan step no longer drains its own output stores
# speedup vs baseline: 1.0077x; 1.0077x over previous
.Lrl_e_noproj:
	s_mov_b64 exec, s[28:29]
	v_add_u32_e32 v203, 256, v202
	v_mul_hi_u32 v204, v203, s26
	v_lshrrev_b32_e32 v204, 5, v204
	v_mul_u32_u24_e32 v220, 48, v204
	v_sub_u32_e32 v220, v203, v220
	v_lshrrev_b32_e32 v221, 4, v220
	v_mul_u32_u24_e32 v221, 0x700, v221
	v_lshl_add_u32 v221, v220, 4, v221
	v_lshl_add_u32 v221, v204, 13, v221
	global_load_dwordx4 v[194:197], v221, s[34:35]
	v_add_u32_e32 v203, 512, v202
	v_mul_hi_u32 v204, v203, s26
	v_lshrrev_b32_e32 v204, 5, v204
	v_mul_u32_u24_e32 v220, 48, v204
	v_sub_u32_e32 v220, v203, v220
	v_lshrrev_b32_e32 v221, 4, v220
	v_mul_u32_u24_e32 v221, 0x700, v221
	v_lshl_add_u32 v221, v220, 4, v221
	v_lshl_add_u32 v221, v204, 13, v221
	global_load_dwordx4 v[198:201], v221, s[34:35]
	v_add_u32_e32 v203, 768, v202
	v_mul_hi_u32 v204, v203, s26
	v_lshrrev_b32_e32 v204, 5, v204
	v_mul_u32_u24_e32 v220, 48, v204
	v_sub_u32_e32 v220, v203, v220
	v_lshrrev_b32_e32 v221, 4, v220
	v_mul_u32_u24_e32 v221, 0x700, v221
	v_lshl_add_u32 v221, v220, 4, v221
	v_lshl_add_u32 v221, v204, 13, v221
	global_load_dwordx4 v[206:209], v221, s[34:35]
	v_add_u32_e32 v203, 1024, v202
	v_mul_hi_u32 v204, v203, s26
	v_lshrrev_b32_e32 v204, 5, v204
	v_mul_u32_u24_e32 v220, 48, v204
	v_sub_u32_e32 v220, v203, v220
	v_lshrrev_b32_e32 v221, 4, v220
	v_mul_u32_u24_e32 v221, 0x700, v221
	v_lshl_add_u32 v221, v220, 4, v221
	v_lshl_add_u32 v221, v204, 13, v221
	global_load_dwordx4 v[210:213], v221, s[34:35]
	v_add_u32_e32 v203, 1280, v202
	v_mul_hi_u32 v204, v203, s26
	v_lshrrev_b32_e32 v204, 5, v204
	v_mul_u32_u24_e32 v220, 48, v204
	v_sub_u32_e32 v220, v203, v220
	v_lshrrev_b32_e32 v221, 4, v220
	v_mul_u32_u24_e32 v221, 0x700, v221
	v_lshl_add_u32 v221, v220, 4, v221
	v_lshl_add_u32 v221, v204, 13, v221
	global_load_dwordx4 v[214:217], v221, s[34:35]
	v_add_u32_e32 v203, 1536, v202
	v_mul_hi_u32 v204, v203, s26
	v_lshrrev_b32_e32 v204, 5, v204
	v_mul_u32_u24_e32 v220, 48, v204
	v_sub_u32_e32 v220, v203, v220
	v_lshrrev_b32_e32 v221, 4, v220
	v_mul_u32_u24_e32 v221, 0x700, v221
	v_lshl_add_u32 v221, v220, 4, v221
	v_lshl_add_u32 v221, v204, 13, v221
	global_load_dwordx4 v[238:241], v221, s[34:35]
	v_add_u32_e32 v203, 1792, v202
	v_mul_hi_u32 v204, v203, s26
	v_lshrrev_b32_e32 v204, 5, v204
	v_mul_u32_u24_e32 v220, 48, v204
	v_sub_u32_e32 v220, v203, v220
	v_lshrrev_b32_e32 v221, 4, v220
	v_mul_u32_u24_e32 v221, 0x700, v221
	v_lshl_add_u32 v221, v220, 4, v221
	v_lshl_add_u32 v221, v204, 13, v221
	global_load_dwordx4 v[242:245], v221, s[34:35]
	v_add_u32_e32 v203, 2048, v202
	v_mul_hi_u32 v204, v203, s26
	v_lshrrev_b32_e32 v204, 5, v204
	v_mul_u32_u24_e32 v220, 48, v204
	v_sub_u32_e32 v220, v203, v220
	v_lshrrev_b32_e32 v221, 4, v220
	v_mul_u32_u24_e32 v221, 0x700, v221
	v_lshl_add_u32 v221, v220, 4, v221
	v_lshl_add_u32 v221, v204, 13, v221
	global_load_dwordx4 v[246:249], v221, s[34:35]
	v_add_u32_e32 v203, 2304, v202
	v_mul_hi_u32 v204, v203, s26
	v_lshrrev_b32_e32 v204, 5, v204
	v_mul_u32_u24_e32 v220, 48, v204
	v_sub_u32_e32 v220, v203, v220
	v_lshrrev_b32_e32 v221, 4, v220
	v_mul_u32_u24_e32 v221, 0x700, v221
	v_lshl_add_u32 v221, v220, 4, v221
	v_lshl_add_u32 v221, v204, 13, v221
	global_load_dwordx4 v[88:91], v221, s[34:35]
	v_add_u32_e32 v203, 2560, v202
	v_mul_hi_u32 v204, v203, s26
	v_lshrrev_b32_e32 v204, 5, v204
	v_mul_u32_u24_e32 v220, 48, v204
	v_sub_u32_e32 v220, v203, v220
	v_lshrrev_b32_e32 v221, 4, v220
	v_mul_u32_u24_e32 v221, 0x700, v221
	v_lshl_add_u32 v221, v220, 4, v221
	v_lshl_add_u32 v221, v204, 13, v221
	global_load_dwordx4 v[92:95], v221, s[34:35]
	v_add_u32_e32 v203, 2816, v202
	v_mul_hi_u32 v204, v203, s26
	v_lshrrev_b32_e32 v204, 5, v204
	v_mul_u32_u24_e32 v220, 48, v204
	v_sub_u32_e32 v220, v203, v220
	v_lshrrev_b32_e32 v221, 4, v220
	v_mul_u32_u24_e32 v221, 0x700, v221
	v_lshl_add_u32 v221, v220, 4, v221
	v_lshl_add_u32 v221, v204, 13, v221
	global_load_dwordx4 v[96:99], v221, s[34:35]
	s_mov_b64 s[28:29], exec
	v_cmp_gt_u32_e32 vcc, 0x90, v202
	s_and_b64 exec, s[28:29], vcc
	s_cbranch_execz .Lrl_e_no12
	v_add_u32_e32 v203, 3072, v202
	v_mul_hi_u32 v204, v203, s26
	v_lshrrev_b32_e32 v204, 5, v204
	v_mul_u32_u24_e32 v220, 48, v204
	v_sub_u32_e32 v220, v203, v220
	v_lshrrev_b32_e32 v221, 4, v220
	v_mul_u32_u24_e32 v221, 0x700, v221
	v_lshl_add_u32 v221, v220, 4, v221
	v_lshl_add_u32 v221, v204, 13, v221
	global_load_dwordx4 v[100:103], v221, s[34:35]
.Lrl_e_no12:
	s_mov_b64 exec, s[28:29]
.Lrl_early_done:
	s_movk_i32 s0, 0x180
	v_cmp_gt_u32_e32 vcc, s0, v49
	v_add_u32_e32 v6, 0xffffff00, v49
	s_and_saveexec_b64 s[0:1], vcc
	s_cbranch_execz .LBB0_172
	v_readlane_b32 s18, v253, 38
	v_lshlrev_b64 v[2:3], 14, v[46:47]
	v_cmp_eq_u32_e32 vcc, 0, v6
	v_mov_b32_e32 v0, s18
	v_readlane_b32 s18, v254, 21
	v_readlane_b32 s19, v254, 22
	ds_read_b32 v7, v0
	s_nop 0
	v_lshl_add_u64 v[2:3], s[18:19], 0, v[2:3]
	v_readlane_b32 s18, v253, 31
	s_nop 1
	v_mov_b32_e32 v4, s18
	ds_read_b128 v[8:11], v4
	v_lshlrev_b32_e32 v0, 7, v6
	v_lshl_add_u64 v[2:3], v[2:3], 0, v[0:1]
	v_lshl_add_u32 v0, v6, 1, 0
	v_add_u32_e32 v0, 0x10d00, v0
	s_waitcnt lgkmcnt(0)
	v_sub_f32_e32 v4, v7, v8
	v_sub_f32_e32 v5, v7, v9
	ds_read_u16 v8, v0
	ds_read_u16 v9, v0 offset:272
	v_mul_f32_e32 v4, 0x3fb8aa3b, v4
	v_mul_f32_e32 v5, 0x3fb8aa3b, v5
	v_exp_f32_e32 v4, v4
	v_exp_f32_e32 v5, v5
	s_waitcnt lgkmcnt(0)
	v_lshlrev_b32_e32 v9, 16, v9
	v_lshlrev_b32_e32 v8, 16, v8
	v_readlane_b32 s18, v253, 39
	v_pk_mul_f32 v[4:5], v[4:5], v[8:9]
	v_sub_f32_e32 v8, v7, v10
	v_sub_f32_e32 v9, v7, v11
	ds_read_u16 v10, v0 offset:544
	ds_read_u16 v11, v0 offset:816
	v_mul_f32_e32 v8, 0x3fb8aa3b, v8
	v_mul_f32_e32 v9, 0x3fb8aa3b, v9
	v_exp_f32_e32 v8, v8
	v_exp_f32_e32 v9, v9
	s_waitcnt lgkmcnt(0)
	v_lshlrev_b32_e32 v11, 16, v11
	v_lshlrev_b32_e32 v10, 16, v10
	v_pk_mul_f32 v[12:13], v[8:9], v[10:11]
	v_mov_b32_e32 v8, s18
	ds_read_b128 v[8:11], v8
	ds_read_u16 v14, v0 offset:1088
	ds_read_u16 v15, v0 offset:1360
	v_readlane_b32 s18, v253, 40
	s_waitcnt lgkmcnt(0)
	v_sub_f32_e32 v8, v7, v8
	v_sub_f32_e32 v9, v7, v9
	v_mul_f32_e32 v8, 0x3fb8aa3b, v8
	v_mul_f32_e32 v9, 0x3fb8aa3b, v9
	v_exp_f32_e32 v8, v8
	v_exp_f32_e32 v9, v9
	v_lshlrev_b32_e32 v15, 16, v15
	v_lshlrev_b32_e32 v14, 16, v14
	v_pk_mul_f32 v[14:15], v[8:9], v[14:15]
	v_sub_f32_e32 v8, v7, v10
	v_sub_f32_e32 v9, v7, v11
	ds_read_u16 v10, v0 offset:1632
	ds_read_u16 v11, v0 offset:1904
	v_mul_f32_e32 v8, 0x3fb8aa3b, v8
	v_mul_f32_e32 v9, 0x3fb8aa3b, v9
	v_exp_f32_e32 v8, v8
	v_exp_f32_e32 v9, v9
	s_waitcnt lgkmcnt(0)
	v_lshlrev_b32_e32 v11, 16, v11
	v_lshlrev_b32_e32 v10, 16, v10
	v_pk_mul_f32 v[16:17], v[8:9], v[10:11]
	v_cvt_pk_bf16_f32 v8, v4, v5
	v_cvt_pk_bf16_f32 v9, v12, v13
	v_cvt_pk_bf16_f32 v10, v14, v15
	v_cvt_pk_bf16_f32 v11, v16, v17
	global_store_dwordx4 v[2:3], v[8:11], off
	v_mov_b32_e32 v4, s18
	ds_read_b128 v[8:11], v4
	v_readlane_b32 s18, v253, 41
	s_waitcnt lgkmcnt(0)
	v_sub_f32_e32 v4, v7, v8
	v_sub_f32_e32 v5, v7, v9
	ds_read_u16 v8, v0 offset:2176
	ds_read_u16 v9, v0 offset:2448
	v_mul_f32_e32 v4, 0x3fb8aa3b, v4
	v_mul_f32_e32 v5, 0x3fb8aa3b, v5
	v_exp_f32_e32 v4, v4
	v_exp_f32_e32 v5, v5
	s_waitcnt lgkmcnt(0)
	v_lshlrev_b32_e32 v9, 16, v9
	v_lshlrev_b32_e32 v8, 16, v8
	v_pk_mul_f32 v[4:5], v[4:5], v[8:9]
	v_sub_f32_e32 v8, v7, v10
	v_sub_f32_e32 v9, v7, v11
	ds_read_u16 v10, v0 offset:2720
	ds_read_u16 v11, v0 offset:2992
	v_mul_f32_e32 v8, 0x3fb8aa3b, v8
	v_mul_f32_e32 v9, 0x3fb8aa3b, v9
	v_exp_f32_e32 v8, v8
	v_exp_f32_e32 v9, v9
	s_waitcnt lgkmcnt(0)
	v_lshlrev_b32_e32 v11, 16, v11
	v_lshlrev_b32_e32 v10, 16, v10
	v_pk_mul_f32 v[8:9], v[8:9], v[10:11]
	v_mov_b32_e32 v10, s18
	ds_read_b128 v[10:13], v10
	ds_read_u16 v14, v0 offset:3264
	ds_read_u16 v15, v0 offset:3536
	v_readlane_b32 s18, v253, 42
	s_waitcnt lgkmcnt(0)
	v_sub_f32_e32 v10, v7, v10
	v_sub_f32_e32 v11, v7, v11
	v_mul_f32_e32 v10, 0x3fb8aa3b, v10
	v_mul_f32_e32 v11, 0x3fb8aa3b, v11
	v_exp_f32_e32 v10, v10
	v_exp_f32_e32 v11, v11
	v_lshlrev_b32_e32 v15, 16, v15
	v_lshlrev_b32_e32 v14, 16, v14
	v_pk_mul_f32 v[14:15], v[10:11], v[14:15]
	v_sub_f32_e32 v10, v7, v12
	v_sub_f32_e32 v11, v7, v13
	ds_read_u16 v12, v0 offset:3808
	ds_read_u16 v13, v0 offset:4080
	v_mul_f32_e32 v10, 0x3fb8aa3b, v10
	v_mul_f32_e32 v11, 0x3fb8aa3b, v11
	v_exp_f32_e32 v10, v10
	v_exp_f32_e32 v11, v11
	s_waitcnt lgkmcnt(0)
	v_lshlrev_b32_e32 v13, 16, v13
	v_lshlrev_b32_e32 v12, 16, v12
	v_pk_mul_f32 v[16:17], v[10:11], v[12:13]
	v_cvt_pk_bf16_f32 v10, v4, v5
	v_cvt_pk_bf16_f32 v11, v8, v9
	v_cvt_pk_bf16_f32 v12, v14, v15
	v_cvt_pk_bf16_f32 v13, v16, v17
	global_store_dwordx4 v[2:3], v[10:13], off offset:16
	v_mov_b32_e32 v4, s18
	ds_read_b128 v[8:11], v4
	v_readlane_b32 s18, v253, 43
	s_waitcnt lgkmcnt(0)
	v_sub_f32_e32 v4, v7, v8
	v_sub_f32_e32 v5, v7, v9
	ds_read_u16 v8, v0 offset:4352
	ds_read_u16 v9, v0 offset:4624
	v_mul_f32_e32 v4, 0x3fb8aa3b, v4
	v_mul_f32_e32 v5, 0x3fb8aa3b, v5
	v_exp_f32_e32 v4, v4
	v_exp_f32_e32 v5, v5
	s_waitcnt lgkmcnt(0)
	v_lshlrev_b32_e32 v9, 16, v9
	v_lshlrev_b32_e32 v8, 16, v8
	v_pk_mul_f32 v[4:5], v[4:5], v[8:9]
	v_sub_f32_e32 v8, v7, v10
	v_sub_f32_e32 v9, v7, v11
	ds_read_u16 v10, v0 offset:4896
	ds_read_u16 v11, v0 offset:5168
	v_mul_f32_e32 v8, 0x3fb8aa3b, v8
	v_mul_f32_e32 v9, 0x3fb8aa3b, v9
	v_exp_f32_e32 v8, v8
	v_exp_f32_e32 v9, v9
	s_waitcnt lgkmcnt(0)
	v_lshlrev_b32_e32 v11, 16, v11
	v_lshlrev_b32_e32 v10, 16, v10
	v_pk_mul_f32 v[8:9], v[8:9], v[10:11]
	v_mov_b32_e32 v10, s18
	ds_read_b128 v[10:13], v10
	ds_read_u16 v14, v0 offset:5440
	ds_read_u16 v15, v0 offset:5712
	v_readlane_b32 s18, v253, 44
	s_waitcnt lgkmcnt(0)
	v_sub_f32_e32 v10, v7, v10
	v_sub_f32_e32 v11, v7, v11
	v_mul_f32_e32 v10, 0x3fb8aa3b, v10
	v_mul_f32_e32 v11, 0x3fb8aa3b, v11
	v_exp_f32_e32 v10, v10
	v_exp_f32_e32 v11, v11
	v_lshlrev_b32_e32 v15, 16, v15
	v_lshlrev_b32_e32 v14, 16, v14
	v_pk_mul_f32 v[14:15], v[10:11], v[14:15]
	v_sub_f32_e32 v10, v7, v12
	v_sub_f32_e32 v11, v7, v13
	ds_read_u16 v12, v0 offset:5984
	ds_read_u16 v13, v0 offset:6256
	v_mul_f32_e32 v10, 0x3fb8aa3b, v10
	v_mul_f32_e32 v11, 0x3fb8aa3b, v11
	v_exp_f32_e32 v10, v10
	v_exp_f32_e32 v11, v11
	s_waitcnt lgkmcnt(0)
	v_lshlrev_b32_e32 v13, 16, v13
	v_lshlrev_b32_e32 v12, 16, v12
	v_pk_mul_f32 v[16:17], v[10:11], v[12:13]
	v_cvt_pk_bf16_f32 v10, v4, v5
	v_cvt_pk_bf16_f32 v11, v8, v9
	v_cvt_pk_bf16_f32 v12, v14, v15
	v_cvt_pk_bf16_f32 v13, v16, v17
	global_store_dwordx4 v[2:3], v[10:13], off offset:32
	v_mov_b32_e32 v4, s18
	ds_read_b128 v[8:11], v4
	v_readlane_b32 s18, v253, 45
	s_waitcnt lgkmcnt(0)
	v_sub_f32_e32 v4, v7, v8
	v_sub_f32_e32 v5, v7, v9
	ds_read_u16 v8, v0 offset:6528
	ds_read_u16 v9, v0 offset:6800
	v_mul_f32_e32 v4, 0x3fb8aa3b, v4
	v_mul_f32_e32 v5, 0x3fb8aa3b, v5
	v_exp_f32_e32 v4, v4
	v_exp_f32_e32 v5, v5
	s_waitcnt lgkmcnt(0)
	v_lshlrev_b32_e32 v9, 16, v9
	v_lshlrev_b32_e32 v8, 16, v8
	v_pk_mul_f32 v[4:5], v[4:5], v[8:9]
	v_sub_f32_e32 v8, v7, v10
	v_sub_f32_e32 v9, v7, v11
	ds_read_u16 v10, v0 offset:7072
	ds_read_u16 v11, v0 offset:7344
	v_mul_f32_e32 v8, 0x3fb8aa3b, v8
	v_mul_f32_e32 v9, 0x3fb8aa3b, v9
	v_exp_f32_e32 v8, v8
	v_exp_f32_e32 v9, v9
	s_waitcnt lgkmcnt(0)
	v_lshlrev_b32_e32 v11, 16, v11
	v_lshlrev_b32_e32 v10, 16, v10
	v_pk_mul_f32 v[8:9], v[8:9], v[10:11]
	v_mov_b32_e32 v10, s18
	ds_read_b128 v[10:13], v10
	ds_read_u16 v14, v0 offset:7616
	ds_read_u16 v15, v0 offset:7888
	v_readlane_b32 s18, v253, 46
	s_waitcnt lgkmcnt(0)
	v_sub_f32_e32 v10, v7, v10
	v_sub_f32_e32 v11, v7, v11
	v_mul_f32_e32 v10, 0x3fb8aa3b, v10
	v_mul_f32_e32 v11, 0x3fb8aa3b, v11
	v_exp_f32_e32 v10, v10
	v_exp_f32_e32 v11, v11
	v_lshlrev_b32_e32 v15, 16, v15
	v_lshlrev_b32_e32 v14, 16, v14
	v_pk_mul_f32 v[14:15], v[10:11], v[14:15]
	v_sub_f32_e32 v10, v7, v12
	v_sub_f32_e32 v11, v7, v13
	ds_read_u16 v12, v0 offset:8160
	ds_read_u16 v13, v0 offset:8432
	v_mul_f32_e32 v10, 0x3fb8aa3b, v10
	v_mul_f32_e32 v11, 0x3fb8aa3b, v11
	v_exp_f32_e32 v10, v10
	v_exp_f32_e32 v11, v11
	s_waitcnt lgkmcnt(0)
	v_lshlrev_b32_e32 v13, 16, v13
	v_lshlrev_b32_e32 v12, 16, v12
	v_pk_mul_f32 v[16:17], v[10:11], v[12:13]
	v_cvt_pk_bf16_f32 v10, v4, v5
	v_cvt_pk_bf16_f32 v11, v8, v9
	v_cvt_pk_bf16_f32 v12, v14, v15
	v_cvt_pk_bf16_f32 v13, v16, v17
	global_store_dwordx4 v[2:3], v[10:13], off offset:48
	v_mov_b32_e32 v4, s18
	ds_read_b128 v[8:11], v4
	v_readlane_b32 s18, v253, 47
	s_waitcnt lgkmcnt(0)
	v_sub_f32_e32 v4, v7, v8
	v_sub_f32_e32 v5, v7, v9
	ds_read_u16 v8, v0 offset:8704
	ds_read_u16 v9, v0 offset:8976
	v_mul_f32_e32 v4, 0x3fb8aa3b, v4
	v_mul_f32_e32 v5, 0x3fb8aa3b, v5
	v_exp_f32_e32 v4, v4
	v_exp_f32_e32 v5, v5
	s_waitcnt lgkmcnt(0)
	v_lshlrev_b32_e32 v9, 16, v9
	v_lshlrev_b32_e32 v8, 16, v8
	v_pk_mul_f32 v[4:5], v[4:5], v[8:9]
	v_sub_f32_e32 v8, v7, v10
	v_sub_f32_e32 v9, v7, v11
	ds_read_u16 v10, v0 offset:9248
	ds_read_u16 v11, v0 offset:9520
	v_mul_f32_e32 v8, 0x3fb8aa3b, v8
	v_mul_f32_e32 v9, 0x3fb8aa3b, v9
	v_exp_f32_e32 v8, v8
	v_exp_f32_e32 v9, v9
	s_waitcnt lgkmcnt(0)
	v_lshlrev_b32_e32 v11, 16, v11
	v_lshlrev_b32_e32 v10, 16, v10
	v_pk_mul_f32 v[8:9], v[8:9], v[10:11]
	v_mov_b32_e32 v10, s18
	ds_read_b128 v[10:13], v10
	ds_read_u16 v14, v0 offset:9792
	ds_read_u16 v15, v0 offset:10064
	v_readlane_b32 s18, v253, 48
	s_waitcnt lgkmcnt(0)
	v_sub_f32_e32 v10, v7, v10
	v_sub_f32_e32 v11, v7, v11
	v_mul_f32_e32 v10, 0x3fb8aa3b, v10
	v_mul_f32_e32 v11, 0x3fb8aa3b, v11
	v_exp_f32_e32 v10, v10
	v_exp_f32_e32 v11, v11
	v_lshlrev_b32_e32 v15, 16, v15
	v_lshlrev_b32_e32 v14, 16, v14
	v_pk_mul_f32 v[14:15], v[10:11], v[14:15]
	v_sub_f32_e32 v10, v7, v12
	v_sub_f32_e32 v11, v7, v13
	ds_read_u16 v12, v0 offset:10336
	ds_read_u16 v13, v0 offset:10608
	v_mul_f32_e32 v10, 0x3fb8aa3b, v10
	v_mul_f32_e32 v11, 0x3fb8aa3b, v11
	v_exp_f32_e32 v10, v10
	v_exp_f32_e32 v11, v11
	s_waitcnt lgkmcnt(0)
	v_lshlrev_b32_e32 v13, 16, v13
	v_lshlrev_b32_e32 v12, 16, v12
	v_pk_mul_f32 v[16:17], v[10:11], v[12:13]
	v_cvt_pk_bf16_f32 v10, v4, v5
	v_cvt_pk_bf16_f32 v11, v8, v9
	v_cvt_pk_bf16_f32 v12, v14, v15
	v_cvt_pk_bf16_f32 v13, v16, v17
	global_store_dwordx4 v[2:3], v[10:13], off offset:64
	v_mov_b32_e32 v4, s18
	ds_read_b128 v[8:11], v4
	v_readlane_b32 s18, v253, 49
	s_waitcnt lgkmcnt(0)
	v_sub_f32_e32 v4, v7, v8
	v_sub_f32_e32 v5, v7, v9
	ds_read_u16 v8, v0 offset:10880
	ds_read_u16 v9, v0 offset:11152
	v_mul_f32_e32 v4, 0x3fb8aa3b, v4
	v_mul_f32_e32 v5, 0x3fb8aa3b, v5
	v_exp_f32_e32 v4, v4
	v_exp_f32_e32 v5, v5
	s_waitcnt lgkmcnt(0)
	v_lshlrev_b32_e32 v9, 16, v9
	v_lshlrev_b32_e32 v8, 16, v8
	v_pk_mul_f32 v[4:5], v[4:5], v[8:9]
	v_sub_f32_e32 v8, v7, v10
	v_sub_f32_e32 v9, v7, v11
	ds_read_u16 v10, v0 offset:11424
	ds_read_u16 v11, v0 offset:11696
	v_mul_f32_e32 v8, 0x3fb8aa3b, v8
	v_mul_f32_e32 v9, 0x3fb8aa3b, v9
	v_exp_f32_e32 v8, v8
	v_exp_f32_e32 v9, v9
	s_waitcnt lgkmcnt(0)
	v_lshlrev_b32_e32 v11, 16, v11
	v_lshlrev_b32_e32 v10, 16, v10
	v_pk_mul_f32 v[8:9], v[8:9], v[10:11]
	v_mov_b32_e32 v10, s18
	ds_read_b128 v[10:13], v10
	ds_read_u16 v14, v0 offset:11968
	ds_read_u16 v15, v0 offset:12240
	v_readlane_b32 s18, v253, 50
	s_waitcnt lgkmcnt(0)
	v_sub_f32_e32 v10, v7, v10
	v_sub_f32_e32 v11, v7, v11
	v_mul_f32_e32 v10, 0x3fb8aa3b, v10
	v_mul_f32_e32 v11, 0x3fb8aa3b, v11
	v_exp_f32_e32 v10, v10
	v_exp_f32_e32 v11, v11
	v_lshlrev_b32_e32 v15, 16, v15
	v_lshlrev_b32_e32 v14, 16, v14
	v_pk_mul_f32 v[14:15], v[10:11], v[14:15]
	v_sub_f32_e32 v10, v7, v12
	v_sub_f32_e32 v11, v7, v13
	ds_read_u16 v12, v0 offset:12512
	ds_read_u16 v13, v0 offset:12784
	v_mul_f32_e32 v10, 0x3fb8aa3b, v10
	v_mul_f32_e32 v11, 0x3fb8aa3b, v11
	v_exp_f32_e32 v10, v10
	v_exp_f32_e32 v11, v11
	s_waitcnt lgkmcnt(0)
	v_lshlrev_b32_e32 v13, 16, v13
	v_lshlrev_b32_e32 v12, 16, v12
	v_pk_mul_f32 v[16:17], v[10:11], v[12:13]
	v_cvt_pk_bf16_f32 v10, v4, v5
	v_cvt_pk_bf16_f32 v11, v8, v9
	v_cvt_pk_bf16_f32 v12, v14, v15
	v_cvt_pk_bf16_f32 v13, v16, v17
	global_store_dwordx4 v[2:3], v[10:13], off offset:80
	v_mov_b32_e32 v4, s18
	ds_read_b128 v[8:11], v4
	v_readlane_b32 s18, v253, 51
	s_waitcnt lgkmcnt(0)
	v_sub_f32_e32 v4, v7, v8
	v_sub_f32_e32 v5, v7, v9
	ds_read_u16 v8, v0 offset:13056
	ds_read_u16 v9, v0 offset:13328
	v_mul_f32_e32 v4, 0x3fb8aa3b, v4
	v_mul_f32_e32 v5, 0x3fb8aa3b, v5
	v_exp_f32_e32 v4, v4
	v_exp_f32_e32 v5, v5
	s_waitcnt lgkmcnt(0)
	v_lshlrev_b32_e32 v9, 16, v9
	v_lshlrev_b32_e32 v8, 16, v8
	v_pk_mul_f32 v[4:5], v[4:5], v[8:9]
	v_sub_f32_e32 v8, v7, v10
	v_sub_f32_e32 v9, v7, v11
	ds_read_u16 v10, v0 offset:13600
	ds_read_u16 v11, v0 offset:13872
	v_mul_f32_e32 v8, 0x3fb8aa3b, v8
	v_mul_f32_e32 v9, 0x3fb8aa3b, v9
	v_exp_f32_e32 v8, v8
	v_exp_f32_e32 v9, v9
	s_waitcnt lgkmcnt(0)
	v_lshlrev_b32_e32 v11, 16, v11
	v_lshlrev_b32_e32 v10, 16, v10
	v_pk_mul_f32 v[8:9], v[8:9], v[10:11]
	v_mov_b32_e32 v10, s18
	ds_read_b128 v[10:13], v10
	ds_read_u16 v14, v0 offset:14144
	ds_read_u16 v15, v0 offset:14416
	v_readlane_b32 s18, v253, 52
	s_waitcnt lgkmcnt(0)
	v_sub_f32_e32 v10, v7, v10
	v_sub_f32_e32 v11, v7, v11
	v_mul_f32_e32 v10, 0x3fb8aa3b, v10
	v_mul_f32_e32 v11, 0x3fb8aa3b, v11
	v_exp_f32_e32 v10, v10
	v_exp_f32_e32 v11, v11
	v_lshlrev_b32_e32 v15, 16, v15
	v_lshlrev_b32_e32 v14, 16, v14
	v_pk_mul_f32 v[14:15], v[10:11], v[14:15]
	v_sub_f32_e32 v10, v7, v12
	v_sub_f32_e32 v11, v7, v13
	ds_read_u16 v12, v0 offset:14688
	ds_read_u16 v13, v0 offset:14960
	v_mul_f32_e32 v10, 0x3fb8aa3b, v10
	v_mul_f32_e32 v11, 0x3fb8aa3b, v11
	v_exp_f32_e32 v10, v10
	v_exp_f32_e32 v11, v11
	s_waitcnt lgkmcnt(0)
	v_lshlrev_b32_e32 v13, 16, v13
	v_lshlrev_b32_e32 v12, 16, v12
	v_pk_mul_f32 v[16:17], v[10:11], v[12:13]
	v_cvt_pk_bf16_f32 v10, v4, v5
	v_cvt_pk_bf16_f32 v11, v8, v9
	v_cvt_pk_bf16_f32 v12, v14, v15
	v_cvt_pk_bf16_f32 v13, v16, v17
	global_store_dwordx4 v[2:3], v[10:13], off offset:96
	v_mov_b32_e32 v4, s18
	ds_read_b128 v[8:11], v4
	v_readlane_b32 s18, v253, 53
	s_waitcnt lgkmcnt(0)
	v_sub_f32_e32 v4, v7, v8
	v_sub_f32_e32 v5, v7, v9
	ds_read_u16 v8, v0 offset:15232
	ds_read_u16 v9, v0 offset:15504
	v_mul_f32_e32 v4, 0x3fb8aa3b, v4
	v_mul_f32_e32 v5, 0x3fb8aa3b, v5
	v_exp_f32_e32 v4, v4
	v_exp_f32_e32 v5, v5
	s_waitcnt lgkmcnt(0)
	v_lshlrev_b32_e32 v9, 16, v9
	v_lshlrev_b32_e32 v8, 16, v8
	v_pk_mul_f32 v[4:5], v[4:5], v[8:9]
	v_sub_f32_e32 v8, v7, v10
	v_sub_f32_e32 v9, v7, v11
	ds_read_u16 v10, v0 offset:15776
	ds_read_u16 v11, v0 offset:16048
	v_mul_f32_e32 v8, 0x3fb8aa3b, v8
	v_mul_f32_e32 v9, 0x3fb8aa3b, v9
	v_exp_f32_e32 v8, v8
	v_exp_f32_e32 v9, v9
	s_waitcnt lgkmcnt(0)
	v_lshlrev_b32_e32 v11, 16, v11
	v_lshlrev_b32_e32 v10, 16, v10
	v_pk_mul_f32 v[8:9], v[8:9], v[10:11]
	v_mov_b32_e32 v10, s18
	ds_read_b128 v[10:13], v10
	ds_read_u16 v14, v0 offset:16320
	ds_read_u16 v15, v0 offset:16592
	s_waitcnt lgkmcnt(0)
	v_sub_f32_e32 v10, v7, v10
	v_sub_f32_e32 v11, v7, v11
	v_mul_f32_e32 v10, 0x3fb8aa3b, v10
	v_mul_f32_e32 v11, 0x3fb8aa3b, v11
	v_exp_f32_e32 v10, v10
	v_exp_f32_e32 v11, v11
	v_lshlrev_b32_e32 v15, 16, v15
	v_lshlrev_b32_e32 v14, 16, v14
	v_pk_mul_f32 v[14:15], v[10:11], v[14:15]
	v_sub_f32_e32 v10, v7, v12
	v_sub_f32_e32 v11, v7, v13
	ds_read_u16 v12, v0 offset:16864
	ds_read_u16 v0, v0 offset:17136
	v_mul_f32_e32 v10, 0x3fb8aa3b, v10
	v_mul_f32_e32 v11, 0x3fb8aa3b, v11
	v_exp_f32_e32 v10, v10
	v_exp_f32_e32 v11, v11
	s_waitcnt lgkmcnt(0)
	v_lshlrev_b32_e32 v13, 16, v0
	v_lshlrev_b32_e32 v12, 16, v12
	v_pk_mul_f32 v[16:17], v[10:11], v[12:13]
	v_cvt_pk_bf16_f32 v10, v4, v5
	v_cvt_pk_bf16_f32 v11, v8, v9
	v_cvt_pk_bf16_f32 v12, v14, v15
	v_cvt_pk_bf16_f32 v13, v16, v17
	global_store_dwordx4 v[2:3], v[10:13], off offset:112
	s_and_saveexec_b64 s[24:25], vcc
	s_cbranch_execz .LBB0_171
	v_mul_f32_e32 v0, 0x3fb8aa3b, v7
	v_exp_f32_e32 v0, v0
	v_lshl_add_u64 v[2:3], v[46:47], 2, s[40:41]
	v_mov_b32_e32 v6, 0
	global_store_dword v[2:3], v0, off

.LBB0_172:
	s_or_b64 exec, exec, s[0:1]
	v_lshlrev_b32_e32 v0, 4, v49
	v_and_b32_e32 v2, 0xf0, v0
	v_lshlrev_b32_e32 v0, 1, v84
	v_add_u32_e32 v4, 0, v2
	v_lshl_add_u64 v[8:9], s[74:75], 0, v[0:1]
	v_mov_b32_e32 v3, v1
	v_lshrrev_b32_e32 v0, 4, v6
	s_movk_i32 s19, 0x110
	v_readlane_b32 s18, v253, 31
	v_lshl_add_u64 v[2:3], v[8:9], 0, v[2:3]
	v_mad_u64_u32 v[8:9], s[0:1], v0, s19, v[4:5]
	v_lshl_add_u32 v5, v0, 2, s18
	ds_read_b128 v[8:11], v8 offset:51456
	ds_read_b32 v5, v5
	v_add_u32_e32 v46, s63, v46
	s_waitcnt lgkmcnt(0)
	v_lshlrev_b32_e32 v14, 16, v8
	v_mul_f32_e32 v5, 0x3fb8aa3b, v5
	v_exp_f32_e32 v12, v5
	v_and_b32_e32 v15, 0xffff0000, v8
	v_pk_mul_f32 v[14:15], v[12:13], v[14:15] op_sel_hi:[0,1]
	v_cvt_pk_bf16_f32 v8, v14, v15
	v_lshlrev_b32_e32 v14, 16, v9
	v_and_b32_e32 v15, 0xffff0000, v9
	v_pk_mul_f32 v[14:15], v[12:13], v[14:15] op_sel_hi:[0,1]
	v_cvt_pk_bf16_f32 v9, v14, v15
	v_lshlrev_b32_e32 v14, 16, v10
	v_and_b32_e32 v15, 0xffff0000, v10
	v_pk_mul_f32 v[14:15], v[12:13], v[14:15] op_sel_hi:[0,1]
	v_cvt_pk_bf16_f32 v10, v14, v15
	v_lshlrev_b32_e32 v14, 16, v11
	v_and_b32_e32 v15, 0xffff0000, v11
	v_pk_mul_f32 v[12:13], v[12:13], v[14:15] op_sel_hi:[0,1]
	v_cvt_pk_bf16_f32 v11, v12, v13
	v_lshl_add_u64 v[12:13], v[82:83], 0, v[0:1]
	v_lshlrev_b64 v[12:13], 13, v[12:13]
	v_lshl_add_u64 v[12:13], v[2:3], 0, v[12:13]
	v_lshrrev_b32_e32 v0, 4, v49
	global_store_dwordx4 v[12:13], v[8:11], off
	s_nop 1
	v_mad_u64_u32 v[8:9], s[0:1], v0, s19, v[4:5]
	v_lshl_add_u32 v5, v0, 2, s18
	ds_read_b128 v[8:11], v8 offset:51456
	ds_read_b32 v5, v5
	s_waitcnt lgkmcnt(0)
	v_lshlrev_b32_e32 v14, 16, v8
	v_mul_f32_e32 v5, 0x3fb8aa3b, v5
	v_exp_f32_e32 v12, v5
	v_and_b32_e32 v15, 0xffff0000, v8
	v_pk_mul_f32 v[14:15], v[12:13], v[14:15] op_sel_hi:[0,1]
	v_cvt_pk_bf16_f32 v8, v14, v15
	v_lshlrev_b32_e32 v14, 16, v9
	v_and_b32_e32 v15, 0xffff0000, v9
	v_pk_mul_f32 v[14:15], v[12:13], v[14:15] op_sel_hi:[0,1]
	v_cvt_pk_bf16_f32 v9, v14, v15
	v_lshlrev_b32_e32 v14, 16, v10
	v_and_b32_e32 v15, 0xffff0000, v10
	v_pk_mul_f32 v[14:15], v[12:13], v[14:15] op_sel_hi:[0,1]
	v_cvt_pk_bf16_f32 v10, v14, v15
	v_lshlrev_b32_e32 v14, 16, v11
	v_and_b32_e32 v15, 0xffff0000, v11
	v_pk_mul_f32 v[12:13], v[12:13], v[14:15] op_sel_hi:[0,1]
	v_cvt_pk_bf16_f32 v11, v12, v13
	v_lshl_add_u64 v[12:13], v[82:83], 0, v[0:1]
	v_lshlrev_b64 v[12:13], 13, v[12:13]
	v_add_u32_e32 v0, 0x100, v49
	v_lshl_add_u64 v[12:13], v[2:3], 0, v[12:13]
	v_lshrrev_b32_e32 v0, 4, v0
	global_store_dwordx4 v[12:13], v[8:11], off
	s_nop 1
	v_mad_u64_u32 v[8:9], s[0:1], v0, s19, v[4:5]
	v_lshl_add_u32 v5, v0, 2, s18
	ds_read_b128 v[8:11], v8 offset:51456
	ds_read_b32 v5, v5
	s_waitcnt lgkmcnt(0)
	v_lshlrev_b32_e32 v14, 16, v8
	v_mul_f32_e32 v5, 0x3fb8aa3b, v5
	v_exp_f32_e32 v12, v5
	v_and_b32_e32 v15, 0xffff0000, v8
	v_pk_mul_f32 v[14:15], v[12:13], v[14:15] op_sel_hi:[0,1]
	v_cvt_pk_bf16_f32 v8, v14, v15
	v_lshlrev_b32_e32 v14, 16, v9
	v_and_b32_e32 v15, 0xffff0000, v9
	v_pk_mul_f32 v[14:15], v[12:13], v[14:15] op_sel_hi:[0,1]
	v_cvt_pk_bf16_f32 v9, v14, v15
	v_lshlrev_b32_e32 v14, 16, v10
	v_and_b32_e32 v15, 0xffff0000, v10
	v_pk_mul_f32 v[14:15], v[12:13], v[14:15] op_sel_hi:[0,1]
	v_cvt_pk_bf16_f32 v10, v14, v15
	v_lshlrev_b32_e32 v14, 16, v11
	v_and_b32_e32 v15, 0xffff0000, v11
	v_pk_mul_f32 v[12:13], v[12:13], v[14:15] op_sel_hi:[0,1]
	v_cvt_pk_bf16_f32 v11, v12, v13
	v_lshl_add_u64 v[12:13], v[82:83], 0, v[0:1]
	v_lshlrev_b64 v[12:13], 13, v[12:13]
	v_add_u32_e32 v0, 0x200, v49
	v_lshl_add_u64 v[12:13], v[2:3], 0, v[12:13]
	v_lshrrev_b32_e32 v0, 4, v0
	global_store_dwordx4 v[12:13], v[8:11], off
	v_mad_u64_u32 v[4:5], s[0:1], v0, s19, v[4:5]
	ds_read_b128 v[8:11], v4 offset:51456
	v_lshl_add_u32 v4, v0, 2, s18
	ds_read_b32 v4, v4
	s_movk_i32 s0, 0x1000
	v_cmp_gt_i32_e32 vcc, s0, v46
	s_waitcnt lgkmcnt(0)
	v_lshlrev_b32_e32 v12, 16, v8
	v_and_b32_e32 v13, 0xffff0000, v8
	v_mul_f32_e32 v4, 0x3fb8aa3b, v4
	v_exp_f32_e32 v4, v4
	s_nop 0
	v_pk_mul_f32 v[12:13], v[4:5], v[12:13] op_sel_hi:[0,1]
	v_cvt_pk_bf16_f32 v8, v12, v13
	v_lshlrev_b32_e32 v12, 16, v9
	v_and_b32_e32 v13, 0xffff0000, v9
	v_pk_mul_f32 v[12:13], v[4:5], v[12:13] op_sel_hi:[0,1]
	v_cvt_pk_bf16_f32 v9, v12, v13
	v_lshlrev_b32_e32 v12, 16, v10
	v_and_b32_e32 v13, 0xffff0000, v10
	v_pk_mul_f32 v[12:13], v[4:5], v[12:13] op_sel_hi:[0,1]
	v_cvt_pk_bf16_f32 v10, v12, v13
	v_lshlrev_b32_e32 v12, 16, v11
	v_and_b32_e32 v13, 0xffff0000, v11
	v_pk_mul_f32 v[4:5], v[4:5], v[12:13] op_sel_hi:[0,1]
	v_cvt_pk_bf16_f32 v11, v4, v5
	v_lshl_add_u64 v[4:5], v[82:83], 0, v[0:1]
	v_lshlrev_b64 v[4:5], 13, v[4:5]
	v_lshl_add_u64 v[2:3], v[2:3], 0, v[4:5]
	global_store_dwordx4 v[2:3], v[8:11], off
	s_and_saveexec_b64 s[24:25], vcc
	s_cbranch_execz .LBB0_190
	v_add_u32_e32 v202, 0xffffff00, v49
	v_lshlrev_b32_e32 v227, 4, v202
	s_waitcnt vmcnt(4)
	ds_write_b128 v227, v[190:193]
	ds_write_b128 v227, v[194:197] offset:4096
	ds_write_b128 v227, v[198:201] offset:8192
	ds_write_b128 v227, v[206:209] offset:12288
	ds_write_b128 v227, v[210:213] offset:16384
	ds_write_b128 v227, v[214:217] offset:20480
	ds_write_b128 v227, v[238:241] offset:24576
	ds_write_b128 v227, v[242:245] offset:28672
	ds_write_b128 v227, v[246:249] offset:32768
	ds_write_b128 v227, v[88:91] offset:36864
	ds_write_b128 v227, v[92:95] offset:40960
	ds_write_b128 v227, v[96:99] offset:45056
	s_mov_b64 s[28:29], exec
	v_cmp_gt_u32_e32 vcc, 0x90, v202
	s_and_b64 exec, s[28:29], vcc
	s_cbranch_execz .Lrl_l_now12
	ds_write_b128 v227, v[100:103] offset:49152

.LBB0_191:
	s_andn2_saveexec_b64 s[20:21], s[20:21]
	s_cbranch_execz .LBB0_43
	s_movk_i32 s0, 0x7f
	v_cmp_lt_u32_e32 vcc, s0, v49
	s_movk_i32 s0, 0x80
	v_lshlrev_b32_e32 v0, 1, v49
	v_cmp_gt_u32_e64 s[0:1], s0, v49
	v_and_b32_e32 v47, 0x7f, v49
	v_and_b32_e32 v0, 0xffffff00, v0
	v_cndmask_b32_e64 v2, v232, v223, s[0:1]
	v_add_u32_e32 v0, 0x1d700, v0
	v_lshl_or_b32 v2, v47, 1, v2
	v_mov_b32_e32 v3, 0x19100
	v_cndmask_b32_e64 v55, v228, v229, s[0:1]
	v_add_u32_e32 v53, 0, v0
	v_add_u32_e32 v51, 0, v2
	v_add_u32_e32 v57, 0, v3
	v_mov_b32_e32 v85, v1
	v_mov_b32_e32 v0, 0
	v_mov_b32_e32 v2, 0
	v_mov_b32_e32 v3, 0
	v_mov_b32_e32 v4, 0
	v_mov_b32_e32 v5, 0
	v_mov_b32_e32 v6, 0
	v_mov_b32_e32 v7, 0
	v_mov_b32_e32 v8, 0
	v_mov_b32_e32 v9, 0
	v_mov_b32_e32 v10, 0
	v_mov_b32_e32 v11, 0
	v_mov_b32_e32 v12, 0
	v_mov_b32_e32 v13, 0
	v_mov_b32_e32 v14, 0
	v_mov_b32_e32 v15, 0
	v_mov_b32_e32 v16, 0
	v_mov_b32_e32 v17, 0
	v_mov_b32_e32 v18, 0
	v_mov_b32_e32 v19, 0
	v_mov_b32_e32 v20, 0
	v_mov_b32_e32 v21, 0
	v_mov_b32_e32 v22, 0
	v_mov_b32_e32 v23, 0
	v_mov_b32_e32 v24, 0
	v_mov_b32_e32 v25, 0
	v_mov_b32_e32 v26, 0
	v_mov_b32_e32 v27, 0
	v_mov_b32_e32 v28, 0
	v_mov_b32_e32 v29, 0
	v_mov_b32_e32 v30, 0
	v_mov_b32_e32 v31, 0
	v_mov_b32_e32 v32, 0
	v_mov_b32_e32 v33, 0
	v_mov_b32_e32 v34, 0
	v_mov_b32_e32 v35, 0
	v_mov_b32_e32 v36, 0
	v_mov_b32_e32 v37, 0
	v_mov_b32_e32 v86, 0
	v_mov_b32_e32 v87, 0
	v_mov_b32_e32 v88, 0
	v_mov_b32_e32 v89, 0
	v_mov_b32_e32 v90, 0
	v_mov_b32_e32 v91, 0
	v_mov_b32_e32 v92, 0
	v_mov_b32_e32 v93, 0
	v_mov_b32_e32 v94, 0
	v_mov_b32_e32 v95, 0
	v_mov_b32_e32 v96, 0
	v_mov_b32_e32 v97, 0
	v_mov_b32_e32 v98, 0
	v_mov_b32_e32 v99, 0
	v_mov_b32_e32 v100, 0
	v_mov_b32_e32 v101, 0
	v_mov_b32_e32 v102, 0
	v_mov_b32_e32 v103, 0
	v_mov_b32_e32 v104, 0
	v_mov_b32_e32 v105, 0
	v_mov_b32_e32 v106, 0
	v_mov_b32_e32 v107, 0
	v_mov_b32_e32 v108, 0
	v_mov_b32_e32 v109, 0
	v_mov_b32_e32 v110, 0
	v_mov_b32_e32 v111, 0
	v_mov_b32_e32 v112, 0
	v_mov_b32_e32 v113, 0
	ds_read_u16 v221, v51
	ds_read_b32 v220, v53
	ds_read_b128 v[174:177], v57 offset:272
	v_mad_u32_u24 v61, v55, 1, v51
	ds_read_u16 v227, v61
	ds_read_b32 v226, v53 offset:4
	ds_read_b128 v[178:181], v57 offset:544
	v_mad_u32_u24 v61, v55, 2, v51
	ds_read_u16 v59, v61
	ds_read_b32 v204, v53 offset:8
	ds_read_b128 v[182:185], v57 offset:816
	s_waitcnt lgkmcnt(5)
	v_lshlrev_b32_e32 v221, 16, v221
	v_mul_f32_e32 v0, v220, v221
	v_mov_b32_e32 v2, v0
	v_mad_u32_u24 v61, v55, 3, v51
	ds_read_u16 v221, v61
	ds_read_b32 v220, v53 offset:12
	ds_read_b128 v[186:189], v57 offset:1088
	v_pk_fma_f32 v[250:251], v[174:175], v[2:3], 0 op_sel_hi:[1,1,0]
	v_pk_fma_f32 v[202:203], v[176:177], v[4:5], 0 op_sel_hi:[1,1,0]
	v_add_f32_e32 v250, v250, v251
	v_add_f32_e32 v202, v202, v203
	s_waitcnt lgkmcnt(5)
	v_lshlrev_b32_e32 v227, 16, v227
	v_add_f32_e32 v250, v250, v202
	v_fma_f32 v3, v226, v227, -v250
	v_mad_u32_u24 v61, v55, 4, v51
	ds_read_u16 v227, v61
	ds_read_b32 v226, v53 offset:16
	ds_read_b128 v[190:193], v57 offset:1360
	ds_read_b128 v[194:197], v57 offset:1376
	v_pk_fma_f32 v[246:247], v[178:179], v[2:3], 0 op_sel_hi:[1,1,0]
	v_pk_fma_f32 v[248:249], v[180:181], v[4:5], 0 op_sel_hi:[1,1,0]
	v_add_f32_e32 v246, v246, v247
	v_add_f32_e32 v248, v248, v249
	s_waitcnt lgkmcnt(5)
	v_lshlrev_b32_e32 v59, 16, v59
	v_add_f32_e32 v246, v246, v248
	v_fma_f32 v4, v204, v59, -v246
	v_mad_u32_u24 v61, v55, 5, v51
	ds_read_u16 v59, v61
	ds_read_b32 v204, v53 offset:20
	ds_read_b128 v[198:201], v57 offset:1632
	ds_read_b128 v[206:209], v57 offset:1648
	v_pk_fma_f32 v[250:251], v[182:183], v[2:3], 0 op_sel_hi:[1,1,0]
	v_pk_fma_f32 v[202:203], v[184:185], v[4:5], 0 op_sel_hi:[1,1,0]
	v_add_f32_e32 v250, v250, v251
	v_add_f32_e32 v202, v202, v203
	v_lshlrev_b32_e32 v221, 16, v221
	v_add_f32_e32 v250, v250, v202
	v_fma_f32 v5, v220, v221, -v250
	v_mad_u32_u24 v61, v55, 6, v51
	ds_read_u16 v221, v61
	ds_read_b32 v220, v53 offset:24
	ds_read_b128 v[210:213], v57 offset:1904
	ds_read_b128 v[214:217], v57 offset:1920
	s_waitcnt lgkmcnt(5)
	v_pk_fma_f32 v[246:247], v[186:187], v[2:3], 0 op_sel_hi:[1,1,0]
	v_pk_fma_f32 v[248:249], v[188:189], v[4:5], 0 op_sel_hi:[1,1,0]
	v_pk_fma_f32 v[250:251], v[190:191], v[2:3], 0 op_sel_hi:[1,1,0]
	v_pk_fma_f32 v[202:203], v[192:193], v[4:5], 0 op_sel_hi:[1,1,0]
	v_add_f32_e32 v246, v246, v247
	v_add_f32_e32 v248, v248, v249
	v_lshlrev_b32_e32 v227, 16, v227
	v_add_f32_e32 v246, v246, v248
	v_fma_f32 v6, v226, v227, -v246
	v_mad_u32_u24 v61, v55, 7, v51
	ds_read_u16 v227, v61
	ds_read_b32 v226, v53 offset:28
	ds_read_b128 v[238:241], v57 offset:2176
	ds_read_b128 v[242:245], v57 offset:2192
	v_pk_fma_f32 v[250:251], v[194:195], v[6:7], v[250:251]
	v_pk_fma_f32 v[202:203], v[196:197], v[8:9], v[202:203]
	v_pk_fma_f32 v[246:247], v[198:199], v[2:3], 0 op_sel_hi:[1,1,0]
	v_pk_fma_f32 v[248:249], v[200:201], v[4:5], 0 op_sel_hi:[1,1,0]
	v_add_f32_e32 v250, v250, v251
	v_add_f32_e32 v202, v202, v203
	v_lshlrev_b32_e32 v59, 16, v59
	v_add_f32_e32 v250, v250, v202
	v_fma_f32 v7, v204, v59, -v250
	v_mad_u32_u24 v61, v55, 8, v51
	ds_read_u16 v59, v61
	ds_read_b32 v204, v53 offset:32
	ds_read_b128 v[174:177], v57 offset:2448
	ds_read_b128 v[178:181], v57 offset:2464
	s_waitcnt lgkmcnt(5)
	v_pk_fma_f32 v[246:247], v[206:207], v[6:7], v[246:247]
	v_pk_fma_f32 v[248:249], v[208:209], v[8:9], v[248:249]
	ds_read_b128 v[182:185], v57 offset:2480
	v_pk_fma_f32 v[250:251], v[210:211], v[2:3], 0 op_sel_hi:[1,1,0]
	v_pk_fma_f32 v[202:203], v[212:213], v[4:5], 0 op_sel_hi:[1,1,0]
	v_add_f32_e32 v246, v246, v247
	v_add_f32_e32 v248, v248, v249
	v_lshlrev_b32_e32 v221, 16, v221
	v_add_f32_e32 v246, v246, v248
	v_fma_f32 v8, v220, v221, -v246
	v_mad_u32_u24 v61, v55, 9, v51
	ds_read_u16 v221, v61
	ds_read_b32 v220, v53 offset:36
	ds_read_b128 v[186:189], v57 offset:2720
	ds_read_b128 v[190:193], v57 offset:2736
	ds_read_b128 v[194:197], v57 offset:2752
	v_pk_fma_f32 v[250:251], v[214:215], v[6:7], v[250:251]
	v_pk_fma_f32 v[202:203], v[216:217], v[8:9], v[202:203]
	v_pk_fma_f32 v[246:247], v[238:239], v[2:3], 0 op_sel_hi:[1,1,0]
	v_pk_fma_f32 v[248:249], v[240:241], v[4:5], 0 op_sel_hi:[1,1,0]
	v_add_f32_e32 v250, v250, v251
	v_add_f32_e32 v202, v202, v203
	v_lshlrev_b32_e32 v227, 16, v227
	v_add_f32_e32 v250, v250, v202
	v_fma_f32 v9, v226, v227, -v250
	v_mad_u32_u24 v61, v55, 10, v51
	ds_read_u16 v227, v61
	ds_read_b32 v226, v53 offset:40
	s_waitcnt lgkmcnt(5)
	v_pk_fma_f32 v[246:247], v[242:243], v[6:7], v[246:247]
	v_pk_fma_f32 v[248:249], v[244:245], v[8:9], v[248:249]
	ds_read_b128 v[198:201], v57 offset:2992
	ds_read_b128 v[206:209], v57 offset:3008
	ds_read_b128 v[210:213], v57 offset:3024
	v_pk_fma_f32 v[250:251], v[174:175], v[2:3], 0 op_sel_hi:[1,1,0]
	v_pk_fma_f32 v[202:203], v[176:177], v[4:5], 0 op_sel_hi:[1,1,0]
	v_add_f32_e32 v246, v246, v247
	v_pk_fma_f32 v[250:251], v[178:179], v[6:7], v[250:251]
	v_pk_fma_f32 v[202:203], v[180:181], v[8:9], v[202:203]
	v_add_f32_e32 v248, v248, v249
	v_lshlrev_b32_e32 v59, 16, v59
	v_add_f32_e32 v246, v246, v248
	v_fma_f32 v10, v204, v59, -v246
	v_mad_u32_u24 v61, v55, 11, v51
	ds_read_u16 v59, v61
	ds_read_b32 v204, v53 offset:44
	ds_read_b128 v[214:217], v57 offset:3264
	ds_read_b128 v[238:241], v57 offset:3280
	ds_read_b128 v[242:245], v57 offset:3296
	v_pk_fma_f32 v[250:251], v[182:183], v[10:11], v[250:251]
	v_pk_fma_f32 v[202:203], v[184:185], v[12:13], v[202:203]
	s_waitcnt lgkmcnt(5)
	v_pk_fma_f32 v[246:247], v[186:187], v[2:3], 0 op_sel_hi:[1,1,0]
	v_pk_fma_f32 v[248:249], v[188:189], v[4:5], 0 op_sel_hi:[1,1,0]
	v_add_f32_e32 v250, v250, v251
	v_pk_fma_f32 v[246:247], v[190:191], v[6:7], v[246:247]
	v_pk_fma_f32 v[248:249], v[192:193], v[8:9], v[248:249]
	v_add_f32_e32 v202, v202, v203
	v_lshlrev_b32_e32 v221, 16, v221
	v_add_f32_e32 v250, v250, v202
	v_fma_f32 v11, v220, v221, -v250
	v_mad_u32_u24 v61, v55, 12, v51
	ds_read_u16 v221, v61
	ds_read_b32 v220, v53 offset:48
	ds_read_b128 v[174:177], v57 offset:3536
	ds_read_b128 v[178:181], v57 offset:3552
	ds_read_b128 v[182:185], v57 offset:3568
	ds_read_b128 v[186:189], v57 offset:3584
	v_pk_fma_f32 v[246:247], v[194:195], v[10:11], v[246:247]
	v_pk_fma_f32 v[248:249], v[196:197], v[12:13], v[248:249]
	v_pk_fma_f32 v[250:251], v[198:199], v[2:3], 0 op_sel_hi:[1,1,0]
	v_pk_fma_f32 v[202:203], v[200:201], v[4:5], 0 op_sel_hi:[1,1,0]
	v_add_f32_e32 v246, v246, v247
	v_pk_fma_f32 v[250:251], v[206:207], v[6:7], v[250:251]
	v_pk_fma_f32 v[202:203], v[208:209], v[8:9], v[202:203]
	v_add_f32_e32 v248, v248, v249
	v_lshlrev_b32_e32 v227, 16, v227
	v_add_f32_e32 v246, v246, v248
	v_fma_f32 v12, v226, v227, -v246
	v_mad_u32_u24 v61, v55, 13, v51
	ds_read_u16 v227, v61
	ds_read_b32 v226, v53 offset:52
	v_pk_fma_f32 v[250:251], v[210:211], v[10:11], v[250:251]
	v_pk_fma_f32 v[202:203], v[212:213], v[12:13], v[202:203]
	s_waitcnt lgkmcnt(5)
	v_pk_fma_f32 v[246:247], v[214:215], v[2:3], 0 op_sel_hi:[1,1,0]
	v_pk_fma_f32 v[248:249], v[216:217], v[4:5], 0 op_sel_hi:[1,1,0]
	ds_read_b128 v[190:193], v57 offset:3808
	ds_read_b128 v[194:197], v57 offset:3824
	ds_read_b128 v[198:201], v57 offset:3840
	ds_read_b128 v[206:209], v57 offset:3856
	v_add_f32_e32 v250, v250, v251
	v_pk_fma_f32 v[246:247], v[238:239], v[6:7], v[246:247]
	v_pk_fma_f32 v[248:249], v[240:241], v[8:9], v[248:249]
	v_add_f32_e32 v202, v202, v203
	v_lshlrev_b32_e32 v59, 16, v59
	v_add_f32_e32 v250, v250, v202
	v_fma_f32 v13, v204, v59, -v250
	v_mad_u32_u24 v61, v55, 14, v51
	ds_read_u16 v59, v61
	ds_read_b32 v204, v53 offset:56
	ds_read_b128 v[210:213], v57 offset:4080
	ds_read_b128 v[214:217], v57 offset:4096
	v_pk_fma_f32 v[246:247], v[242:243], v[10:11], v[246:247]
	v_pk_fma_f32 v[248:249], v[244:245], v[12:13], v[248:249]
	v_pk_fma_f32 v[250:251], v[174:175], v[2:3], 0 op_sel_hi:[1,1,0]
	v_pk_fma_f32 v[202:203], v[176:177], v[4:5], 0 op_sel_hi:[1,1,0]
	v_add_f32_e32 v246, v246, v247
	s_waitcnt lgkmcnt(5)
	v_pk_fma_f32 v[250:251], v[178:179], v[6:7], v[250:251]
	v_pk_fma_f32 v[202:203], v[180:181], v[8:9], v[202:203]
	ds_read_b128 v[238:241], v57 offset:4112
	ds_read_b128 v[242:245], v57 offset:4128
	v_add_f32_e32 v248, v248, v249
	v_pk_fma_f32 v[250:251], v[182:183], v[10:11], v[250:251]
	v_pk_fma_f32 v[202:203], v[184:185], v[12:13], v[202:203]
	v_lshlrev_b32_e32 v221, 16, v221
	v_add_f32_e32 v246, v246, v248
	v_fma_f32 v14, v220, v221, -v246
	v_mad_u32_u24 v61, v55, 15, v51
	ds_read_u16 v221, v61
	ds_read_b32 v220, v53 offset:60
	ds_read_b128 v[174:177], v57 offset:4352
	ds_read_b128 v[178:181], v57 offset:4368
	ds_read_b128 v[182:185], v57 offset:4384
	v_pk_fma_f32 v[250:251], v[186:187], v[14:15], v[250:251]
	v_pk_fma_f32 v[202:203], v[188:189], v[16:17], v[202:203]
	ds_read_b128 v[186:189], v57 offset:4400
	v_pk_fma_f32 v[246:247], v[190:191], v[2:3], 0 op_sel_hi:[1,1,0]
	v_pk_fma_f32 v[248:249], v[192:193], v[4:5], 0 op_sel_hi:[1,1,0]
	v_add_f32_e32 v250, v250, v251
	v_pk_fma_f32 v[246:247], v[194:195], v[6:7], v[246:247]
	v_pk_fma_f32 v[248:249], v[196:197], v[8:9], v[248:249]
	v_add_f32_e32 v202, v202, v203
	v_pk_fma_f32 v[246:247], v[198:199], v[10:11], v[246:247]
	v_pk_fma_f32 v[248:249], v[200:201], v[12:13], v[248:249]
	v_lshlrev_b32_e32 v227, 16, v227
	v_add_f32_e32 v250, v250, v202
	v_fma_f32 v15, v226, v227, -v250
	s_waitcnt lgkmcnt(5)
	v_pk_fma_f32 v[246:247], v[206:207], v[14:15], v[246:247]
	v_pk_fma_f32 v[248:249], v[208:209], v[16:17], v[248:249]
	v_mad_u32_u24 v61, v55, 16, v51
	ds_read_u16 v227, v61
	ds_read_b32 v226, v53 offset:64
	ds_read_b128 v[190:193], v57 offset:4624
	ds_read_b128 v[194:197], v57 offset:4640
	ds_read_b128 v[198:201], v57 offset:4656
	ds_read_b128 v[206:209], v57 offset:4672
	v_pk_fma_f32 v[250:251], v[210:211], v[2:3], 0 op_sel_hi:[1,1,0]
	v_pk_fma_f32 v[202:203], v[212:213], v[4:5], 0 op_sel_hi:[1,1,0]
	ds_read_b128 v[210:213], v57 offset:4688
	v_add_f32_e32 v246, v246, v247
	v_pk_fma_f32 v[250:251], v[214:215], v[6:7], v[250:251]
	v_pk_fma_f32 v[202:203], v[216:217], v[8:9], v[202:203]
	v_add_f32_e32 v248, v248, v249
	v_pk_fma_f32 v[250:251], v[238:239], v[10:11], v[250:251]
	v_pk_fma_f32 v[202:203], v[240:241], v[12:13], v[202:203]
	v_lshlrev_b32_e32 v59, 16, v59
	v_add_f32_e32 v246, v246, v248
	v_fma_f32 v16, v204, v59, -v246
	v_pk_fma_f32 v[250:251], v[242:243], v[14:15], v[250:251]
	v_pk_fma_f32 v[202:203], v[244:245], v[16:17], v[202:203]
	s_waitcnt lgkmcnt(5)
	v_pk_fma_f32 v[246:247], v[174:175], v[2:3], 0 op_sel_hi:[1,1,0]
	v_pk_fma_f32 v[248:249], v[176:177], v[4:5], 0 op_sel_hi:[1,1,0]
	v_mad_u32_u24 v61, v55, 17, v51
	ds_read_u16 v59, v61
	ds_read_b32 v204, v53 offset:68
	ds_read_b128 v[214:217], v57 offset:4896
	ds_read_b128 v[238:241], v57 offset:4912
	ds_read_b128 v[242:245], v57 offset:4928
	ds_read_b128 v[174:177], v57 offset:4944
	v_add_f32_e32 v250, v250, v251
	v_pk_fma_f32 v[246:247], v[178:179], v[6:7], v[246:247]
	v_pk_fma_f32 v[248:249], v[180:181], v[8:9], v[248:249]
	ds_read_b128 v[178:181], v57 offset:4960
	v_add_f32_e32 v202, v202, v203
	v_pk_fma_f32 v[246:247], v[182:183], v[10:11], v[246:247]
	v_pk_fma_f32 v[248:249], v[184:185], v[12:13], v[248:249]
	v_lshlrev_b32_e32 v221, 16, v221
	v_add_f32_e32 v250, v250, v202
	v_fma_f32 v17, v220, v221, -v250
	v_pk_fma_f32 v[246:247], v[186:187], v[14:15], v[246:247]
	v_pk_fma_f32 v[248:249], v[188:189], v[16:17], v[248:249]
	s_waitcnt lgkmcnt(5)
	v_pk_fma_f32 v[250:251], v[190:191], v[2:3], 0 op_sel_hi:[1,1,0]
	v_pk_fma_f32 v[202:203], v[192:193], v[4:5], 0 op_sel_hi:[1,1,0]
	v_mad_u32_u24 v61, v55, 18, v51
	ds_read_u16 v221, v61
	ds_read_b32 v220, v53 offset:72
	ds_read_b128 v[182:185], v57 offset:5168
	ds_read_b128 v[186:189], v57 offset:5184
	ds_read_b128 v[190:193], v57 offset:5200
	v_add_f32_e32 v246, v246, v247
	v_pk_fma_f32 v[250:251], v[194:195], v[6:7], v[250:251]
	v_pk_fma_f32 v[202:203], v[196:197], v[8:9], v[202:203]
	ds_read_b128 v[194:197], v57 offset:5216
	v_add_f32_e32 v248, v248, v249
	v_pk_fma_f32 v[250:251], v[198:199], v[10:11], v[250:251]
	v_pk_fma_f32 v[202:203], v[200:201], v[12:13], v[202:203]
	ds_read_b128 v[198:201], v57 offset:5232
	v_lshlrev_b32_e32 v227, 16, v227
	v_pk_fma_f32 v[250:251], v[206:207], v[14:15], v[250:251]
	v_pk_fma_f32 v[202:203], v[208:209], v[16:17], v[202:203]
	v_add_f32_e32 v246, v246, v248
	v_fma_f32 v18, v226, v227, -v246
	v_pk_fma_f32 v[250:251], v[210:211], v[18:19], v[250:251]
	v_pk_fma_f32 v[202:203], v[212:213], v[20:21], v[202:203]
	s_waitcnt lgkmcnt(5)
	v_pk_fma_f32 v[246:247], v[214:215], v[2:3], 0 op_sel_hi:[1,1,0]
	v_pk_fma_f32 v[248:249], v[216:217], v[4:5], 0 op_sel_hi:[1,1,0]
	v_mad_u32_u24 v61, v55, 19, v51
	ds_read_u16 v227, v61
	ds_read_b32 v226, v53 offset:76
	ds_read_b128 v[206:209], v57 offset:5440
	ds_read_b128 v[210:213], v57 offset:5456
	ds_read_b128 v[214:217], v57 offset:5472
	v_add_f32_e32 v250, v250, v251
	v_pk_fma_f32 v[246:247], v[238:239], v[6:7], v[246:247]
	v_pk_fma_f32 v[248:249], v[240:241], v[8:9], v[248:249]
	ds_read_b128 v[238:241], v57 offset:5488
	v_add_f32_e32 v202, v202, v203
	v_pk_fma_f32 v[246:247], v[242:243], v[10:11], v[246:247]
	v_pk_fma_f32 v[248:249], v[244:245], v[12:13], v[248:249]
	ds_read_b128 v[242:245], v57 offset:5504
	v_lshlrev_b32_e32 v59, 16, v59
	v_pk_fma_f32 v[246:247], v[174:175], v[14:15], v[246:247]
	v_pk_fma_f32 v[248:249], v[176:177], v[16:17], v[248:249]
	v_add_f32_e32 v250, v250, v202
	v_fma_f32 v19, v204, v59, -v250
	v_pk_fma_f32 v[246:247], v[178:179], v[18:19], v[246:247]
	v_pk_fma_f32 v[248:249], v[180:181], v[20:21], v[248:249]
	s_waitcnt lgkmcnt(5)
	v_pk_fma_f32 v[250:251], v[182:183], v[2:3], 0 op_sel_hi:[1,1,0]
	v_pk_fma_f32 v[202:203], v[184:185], v[4:5], 0 op_sel_hi:[1,1,0]
	v_mad_u32_u24 v61, v55, 20, v51
	ds_read_u16 v59, v61
	ds_read_b32 v204, v53 offset:80
	ds_read_b128 v[174:177], v57 offset:5712
	ds_read_b128 v[178:181], v57 offset:5728
	ds_read_b128 v[182:185], v57 offset:5744
	v_add_f32_e32 v246, v246, v247
	v_pk_fma_f32 v[250:251], v[186:187], v[6:7], v[250:251]
	v_pk_fma_f32 v[202:203], v[188:189], v[8:9], v[202:203]
	ds_read_b128 v[186:189], v57 offset:5760
	v_add_f32_e32 v248, v248, v249
	v_pk_fma_f32 v[250:251], v[190:191], v[10:11], v[250:251]
	v_pk_fma_f32 v[202:203], v[192:193], v[12:13], v[202:203]
	ds_read_b128 v[190:193], v57 offset:5776
	v_lshlrev_b32_e32 v221, 16, v221
	v_pk_fma_f32 v[250:251], v[194:195], v[14:15], v[250:251]
	v_pk_fma_f32 v[202:203], v[196:197], v[16:17], v[202:203]
	ds_read_b128 v[194:197], v57 offset:5792
	v_add_f32_e32 v246, v246, v248
	v_fma_f32 v20, v220, v221, -v246
	v_pk_fma_f32 v[250:251], v[198:199], v[18:19], v[250:251]
	v_pk_fma_f32 v[202:203], v[200:201], v[20:21], v[202:203]
	s_waitcnt lgkmcnt(5)
	v_pk_fma_f32 v[246:247], v[206:207], v[2:3], 0 op_sel_hi:[1,1,0]
	v_pk_fma_f32 v[248:249], v[208:209], v[4:5], 0 op_sel_hi:[1,1,0]
	v_mad_u32_u24 v61, v55, 21, v51
	ds_read_u16 v221, v61
	ds_read_b32 v220, v53 offset:84
	ds_read_b128 v[198:201], v57 offset:5984
	ds_read_b128 v[206:209], v57 offset:6000
	v_add_f32_e32 v250, v250, v251
	v_pk_fma_f32 v[246:247], v[210:211], v[6:7], v[246:247]
	v_pk_fma_f32 v[248:249], v[212:213], v[8:9], v[248:249]
	ds_read_b128 v[210:213], v57 offset:6016
	v_add_f32_e32 v202, v202, v203
	v_pk_fma_f32 v[246:247], v[214:215], v[10:11], v[246:247]
	v_pk_fma_f32 v[248:249], v[216:217], v[12:13], v[248:249]
	ds_read_b128 v[214:217], v57 offset:6032
	v_lshlrev_b32_e32 v227, 16, v227
	v_pk_fma_f32 v[246:247], v[238:239], v[14:15], v[246:247]
	v_pk_fma_f32 v[248:249], v[240:241], v[16:17], v[248:249]
	ds_read_b128 v[238:241], v57 offset:6048
	v_add_f32_e32 v250, v250, v202
	v_fma_f32 v21, v226, v227, -v250
	v_pk_fma_f32 v[246:247], v[242:243], v[18:19], v[246:247]
	v_pk_fma_f32 v[248:249], v[244:245], v[20:21], v[248:249]
	ds_read_b128 v[242:245], v57 offset:6064
	v_pk_fma_f32 v[250:251], v[174:175], v[2:3], 0 op_sel_hi:[1,1,0]
	v_pk_fma_f32 v[202:203], v[176:177], v[4:5], 0 op_sel_hi:[1,1,0]
	v_add_f32_e32 v246, v246, v247
	s_waitcnt lgkmcnt(5)
	v_pk_fma_f32 v[250:251], v[178:179], v[6:7], v[250:251]
	v_pk_fma_f32 v[202:203], v[180:181], v[8:9], v[202:203]
	v_mad_u32_u24 v61, v55, 22, v51
	ds_read_u16 v227, v61
	ds_read_b32 v226, v53 offset:88
	ds_read_b128 v[174:177], v57 offset:6256
	ds_read_b128 v[178:181], v57 offset:6272
	v_add_f32_e32 v248, v248, v249
	v_pk_fma_f32 v[250:251], v[182:183], v[10:11], v[250:251]
	v_pk_fma_f32 v[202:203], v[184:185], v[12:13], v[202:203]
	ds_read_b128 v[182:185], v57 offset:6288
	v_lshlrev_b32_e32 v59, 16, v59
	v_pk_fma_f32 v[250:251], v[186:187], v[14:15], v[250:251]
	v_pk_fma_f32 v[202:203], v[188:189], v[16:17], v[202:203]
	ds_read_b128 v[186:189], v57 offset:6304
	v_add_f32_e32 v246, v246, v248
	v_pk_fma_f32 v[250:251], v[190:191], v[18:19], v[250:251]
	v_pk_fma_f32 v[202:203], v[192:193], v[20:21], v[202:203]
	ds_read_b128 v[190:193], v57 offset:6320
	v_fma_f32 v22, v204, v59, -v246
	v_pk_fma_f32 v[250:251], v[194:195], v[22:23], v[250:251]
	v_pk_fma_f32 v[202:203], v[196:197], v[24:25], v[202:203]
	ds_read_b128 v[194:197], v57 offset:6336
	v_pk_fma_f32 v[246:247], v[198:199], v[2:3], 0 op_sel_hi:[1,1,0]
	v_pk_fma_f32 v[248:249], v[200:201], v[4:5], 0 op_sel_hi:[1,1,0]
	v_add_f32_e32 v250, v250, v251
	s_waitcnt lgkmcnt(5)
	v_pk_fma_f32 v[246:247], v[206:207], v[6:7], v[246:247]
	v_pk_fma_f32 v[248:249], v[208:209], v[8:9], v[248:249]
	v_mad_u32_u24 v61, v55, 23, v51
	ds_read_u16 v59, v61
	ds_read_b32 v204, v53 offset:92
	ds_read_b128 v[198:201], v57 offset:6528
	ds_read_b128 v[206:209], v57 offset:6544
	v_add_f32_e32 v202, v202, v203
	v_pk_fma_f32 v[246:247], v[210:211], v[10:11], v[246:247]
	v_pk_fma_f32 v[248:249], v[212:213], v[12:13], v[248:249]
	ds_read_b128 v[210:213], v57 offset:6560
	v_lshlrev_b32_e32 v221, 16, v221
	v_pk_fma_f32 v[246:247], v[214:215], v[14:15], v[246:247]
	v_pk_fma_f32 v[248:249], v[216:217], v[16:17], v[248:249]
	ds_read_b128 v[214:217], v57 offset:6576
	v_add_f32_e32 v250, v250, v202
	v_pk_fma_f32 v[246:247], v[238:239], v[18:19], v[246:247]
	v_pk_fma_f32 v[248:249], v[240:241], v[20:21], v[248:249]
	ds_read_b128 v[238:241], v57 offset:6592
	v_fma_f32 v23, v220, v221, -v250
	v_pk_fma_f32 v[246:247], v[242:243], v[22:23], v[246:247]
	v_pk_fma_f32 v[248:249], v[244:245], v[24:25], v[248:249]
	ds_read_b128 v[242:245], v57 offset:6608
	v_pk_fma_f32 v[250:251], v[174:175], v[2:3], 0 op_sel_hi:[1,1,0]
	v_pk_fma_f32 v[202:203], v[176:177], v[4:5], 0 op_sel_hi:[1,1,0]
	v_add_f32_e32 v246, v246, v247
	s_waitcnt lgkmcnt(5)
	v_pk_fma_f32 v[250:251], v[178:179], v[6:7], v[250:251]
	v_pk_fma_f32 v[202:203], v[180:181], v[8:9], v[202:203]
	v_mad_u32_u24 v61, v55, 24, v51
	ds_read_u16 v221, v61
	ds_read_b32 v220, v53 offset:96
	ds_read_b128 v[174:177], v57 offset:6800
	ds_read_b128 v[178:181], v57 offset:6816
	v_add_f32_e32 v248, v248, v249
	v_pk_fma_f32 v[250:251], v[182:183], v[10:11], v[250:251]
	v_pk_fma_f32 v[202:203], v[184:185], v[12:13], v[202:203]
	ds_read_b128 v[182:185], v57 offset:6832
	v_lshlrev_b32_e32 v227, 16, v227
	v_pk_fma_f32 v[250:251], v[186:187], v[14:15], v[250:251]
	v_pk_fma_f32 v[202:203], v[188:189], v[16:17], v[202:203]
	ds_read_b128 v[186:189], v57 offset:6848
	v_add_f32_e32 v246, v246, v248
	v_pk_fma_f32 v[250:251], v[190:191], v[18:19], v[250:251]
	v_pk_fma_f32 v[202:203], v[192:193], v[20:21], v[202:203]
	ds_read_b128 v[190:193], v57 offset:6864
	v_fma_f32 v24, v226, v227, -v246
	v_pk_fma_f32 v[250:251], v[194:195], v[22:23], v[250:251]
	v_pk_fma_f32 v[202:203], v[196:197], v[24:25], v[202:203]
	ds_read_b128 v[194:197], v57 offset:6880
	v_pk_fma_f32 v[246:247], v[198:199], v[2:3], 0 op_sel_hi:[1,1,0]
	v_pk_fma_f32 v[248:249], v[200:201], v[4:5], 0 op_sel_hi:[1,1,0]
	v_add_f32_e32 v250, v250, v251
	s_waitcnt lgkmcnt(5)
	v_pk_fma_f32 v[246:247], v[206:207], v[6:7], v[246:247]
	v_pk_fma_f32 v[248:249], v[208:209], v[8:9], v[248:249]
	ds_read_b128 v[198:201], v57 offset:6896
	v_mad_u32_u24 v61, v55, 25, v51
	ds_read_u16 v227, v61
	ds_read_b32 v226, v53 offset:100
	ds_read_b128 v[206:209], v57 offset:7072
	v_add_f32_e32 v202, v202, v203
	v_pk_fma_f32 v[246:247], v[210:211], v[10:11], v[246:247]
	v_pk_fma_f32 v[248:249], v[212:213], v[12:13], v[248:249]
	ds_read_b128 v[210:213], v57 offset:7088
	v_lshlrev_b32_e32 v59, 16, v59
	v_pk_fma_f32 v[246:247], v[214:215], v[14:15], v[246:247]
	v_pk_fma_f32 v[248:249], v[216:217], v[16:17], v[248:249]
	ds_read_b128 v[214:217], v57 offset:7104
	v_add_f32_e32 v250, v250, v202
	v_pk_fma_f32 v[246:247], v[238:239], v[18:19], v[246:247]
	v_pk_fma_f32 v[248:249], v[240:241], v[20:21], v[248:249]
	ds_read_b128 v[238:241], v57 offset:7120
	v_fma_f32 v25, v204, v59, -v250
	v_pk_fma_f32 v[246:247], v[242:243], v[22:23], v[246:247]
	v_pk_fma_f32 v[248:249], v[244:245], v[24:25], v[248:249]
	ds_read_b128 v[242:245], v57 offset:7136
	v_pk_fma_f32 v[250:251], v[174:175], v[2:3], 0 op_sel_hi:[1,1,0]
	v_pk_fma_f32 v[202:203], v[176:177], v[4:5], 0 op_sel_hi:[1,1,0]
	v_add_f32_e32 v246, v246, v247
	s_waitcnt lgkmcnt(5)
	v_pk_fma_f32 v[250:251], v[178:179], v[6:7], v[250:251]
	v_pk_fma_f32 v[202:203], v[180:181], v[8:9], v[202:203]
	ds_read_b128 v[174:177], v57 offset:7152
	ds_read_b128 v[178:181], v57 offset:7168
	v_mad_u32_u24 v61, v55, 26, v51
	ds_read_u16 v59, v61
	ds_read_b32 v204, v53 offset:104
	v_add_f32_e32 v248, v248, v249
	v_pk_fma_f32 v[250:251], v[182:183], v[10:11], v[250:251]
	v_pk_fma_f32 v[202:203], v[184:185], v[12:13], v[202:203]
	ds_read_b128 v[182:185], v57 offset:7344
	v_lshlrev_b32_e32 v221, 16, v221
	v_pk_fma_f32 v[250:251], v[186:187], v[14:15], v[250:251]
	v_pk_fma_f32 v[202:203], v[188:189], v[16:17], v[202:203]
	ds_read_b128 v[186:189], v57 offset:7360
	v_add_f32_e32 v246, v246, v248
	v_pk_fma_f32 v[250:251], v[190:191], v[18:19], v[250:251]
	v_pk_fma_f32 v[202:203], v[192:193], v[20:21], v[202:203]
	ds_read_b128 v[190:193], v57 offset:7376
	v_fma_f32 v26, v220, v221, -v246
	v_pk_fma_f32 v[250:251], v[194:195], v[22:23], v[250:251]
	v_pk_fma_f32 v[202:203], v[196:197], v[24:25], v[202:203]
	ds_read_b128 v[194:197], v57 offset:7392
	v_pk_fma_f32 v[250:251], v[198:199], v[26:27], v[250:251]
	v_pk_fma_f32 v[202:203], v[200:201], v[28:29], v[202:203]
	s_waitcnt lgkmcnt(5)
	v_pk_fma_f32 v[246:247], v[206:207], v[2:3], 0 op_sel_hi:[1,1,0]
	v_pk_fma_f32 v[248:249], v[208:209], v[4:5], 0 op_sel_hi:[1,1,0]
	ds_read_b128 v[198:201], v57 offset:7408
	ds_read_b128 v[206:209], v57 offset:7424
	v_add_f32_e32 v250, v250, v251
	v_pk_fma_f32 v[246:247], v[210:211], v[6:7], v[246:247]
	v_pk_fma_f32 v[248:249], v[212:213], v[8:9], v[248:249]
	ds_read_b128 v[210:213], v57 offset:7440
	v_mad_u32_u24 v61, v55, 27, v51
	ds_read_u16 v221, v61
	ds_read_b32 v220, v53 offset:108
	v_add_f32_e32 v202, v202, v203
	v_pk_fma_f32 v[246:247], v[214:215], v[10:11], v[246:247]
	v_pk_fma_f32 v[248:249], v[216:217], v[12:13], v[248:249]
	ds_read_b128 v[214:217], v57 offset:7616
	v_lshlrev_b32_e32 v227, 16, v227
	v_pk_fma_f32 v[246:247], v[238:239], v[14:15], v[246:247]
	v_pk_fma_f32 v[248:249], v[240:241], v[16:17], v[248:249]
	ds_read_b128 v[238:241], v57 offset:7632
	v_add_f32_e32 v250, v250, v202
	v_pk_fma_f32 v[246:247], v[242:243], v[18:19], v[246:247]
	v_pk_fma_f32 v[248:249], v[244:245], v[20:21], v[248:249]
	ds_read_b128 v[242:245], v57 offset:7648
	v_fma_f32 v27, v226, v227, -v250
	v_pk_fma_f32 v[246:247], v[174:175], v[22:23], v[246:247]
	v_pk_fma_f32 v[248:249], v[176:177], v[24:25], v[248:249]
	v_pk_fma_f32 v[246:247], v[178:179], v[26:27], v[246:247]
	v_pk_fma_f32 v[248:249], v[180:181], v[28:29], v[248:249]
	s_waitcnt lgkmcnt(5)
	v_pk_fma_f32 v[250:251], v[182:183], v[2:3], 0 op_sel_hi:[1,1,0]
	v_pk_fma_f32 v[202:203], v[184:185], v[4:5], 0 op_sel_hi:[1,1,0]
	ds_read_b128 v[174:177], v57 offset:7664
	ds_read_b128 v[178:181], v57 offset:7680
	ds_read_b128 v[182:185], v57 offset:7696
	v_add_f32_e32 v246, v246, v247
	v_pk_fma_f32 v[250:251], v[186:187], v[6:7], v[250:251]
	v_pk_fma_f32 v[202:203], v[188:189], v[8:9], v[202:203]
	ds_read_b128 v[186:189], v57 offset:7712
	v_mad_u32_u24 v61, v55, 28, v51
	ds_read_u16 v227, v61
	ds_read_b32 v226, v53 offset:112
	v_add_f32_e32 v248, v248, v249
	v_pk_fma_f32 v[250:251], v[190:191], v[10:11], v[250:251]
	v_pk_fma_f32 v[202:203], v[192:193], v[12:13], v[202:203]
	ds_read_b128 v[190:193], v57 offset:7888
	v_lshlrev_b32_e32 v59, 16, v59
	v_pk_fma_f32 v[250:251], v[194:195], v[14:15], v[250:251]
	v_pk_fma_f32 v[202:203], v[196:197], v[16:17], v[202:203]
	ds_read_b128 v[194:197], v57 offset:7904
	v_add_f32_e32 v246, v246, v248
	v_pk_fma_f32 v[250:251], v[198:199], v[18:19], v[250:251]
	v_pk_fma_f32 v[202:203], v[200:201], v[20:21], v[202:203]
	v_fma_f32 v28, v204, v59, -v246
	v_pk_fma_f32 v[250:251], v[206:207], v[22:23], v[250:251]
	v_pk_fma_f32 v[202:203], v[208:209], v[24:25], v[202:203]
	v_pk_fma_f32 v[250:251], v[210:211], v[26:27], v[250:251]
	v_pk_fma_f32 v[202:203], v[212:213], v[28:29], v[202:203]
	s_waitcnt lgkmcnt(5)
	v_pk_fma_f32 v[246:247], v[214:215], v[2:3], 0 op_sel_hi:[1,1,0]
	v_pk_fma_f32 v[248:249], v[216:217], v[4:5], 0 op_sel_hi:[1,1,0]
	ds_read_b128 v[198:201], v57 offset:7920
	ds_read_b128 v[206:209], v57 offset:7936
	ds_read_b128 v[210:213], v57 offset:7952
	ds_read_b128 v[214:217], v57 offset:7968
	v_add_f32_e32 v250, v250, v251
	v_pk_fma_f32 v[246:247], v[238:239], v[6:7], v[246:247]
	v_pk_fma_f32 v[248:249], v[240:241], v[8:9], v[248:249]
	ds_read_b128 v[238:241], v57 offset:7984
	v_add_f32_e32 v202, v202, v203
	v_pk_fma_f32 v[246:247], v[242:243], v[10:11], v[246:247]
	v_pk_fma_f32 v[248:249], v[244:245], v[12:13], v[248:249]
	ds_read_b128 v[242:245], v57 offset:8000
	v_mad_u32_u24 v61, v55, 29, v51
	ds_read_u16 v59, v61
	ds_read_b32 v204, v53 offset:116
	v_lshlrev_b32_e32 v221, 16, v221
	v_pk_fma_f32 v[246:247], v[174:175], v[14:15], v[246:247]
	v_pk_fma_f32 v[248:249], v[176:177], v[16:17], v[248:249]
	v_add_f32_e32 v250, v250, v202
	v_pk_fma_f32 v[246:247], v[178:179], v[18:19], v[246:247]
	v_pk_fma_f32 v[248:249], v[180:181], v[20:21], v[248:249]
	v_fma_f32 v29, v220, v221, -v250
	v_pk_fma_f32 v[246:247], v[182:183], v[22:23], v[246:247]
	v_pk_fma_f32 v[248:249], v[184:185], v[24:25], v[248:249]
	s_waitcnt lgkmcnt(5)
	v_pk_fma_f32 v[246:247], v[186:187], v[26:27], v[246:247]
	v_pk_fma_f32 v[248:249], v[188:189], v[28:29], v[248:249]
	ds_read_b128 v[174:177], v57 offset:8160
	ds_read_b128 v[178:181], v57 offset:8176
	ds_read_b128 v[182:185], v57 offset:8192
	ds_read_b128 v[186:189], v57 offset:8208
	v_pk_fma_f32 v[250:251], v[190:191], v[2:3], 0 op_sel_hi:[1,1,0]
	v_pk_fma_f32 v[202:203], v[192:193], v[4:5], 0 op_sel_hi:[1,1,0]
	ds_read_b128 v[190:193], v57 offset:8224
	v_add_f32_e32 v246, v246, v247
	v_pk_fma_f32 v[250:251], v[194:195], v[6:7], v[250:251]
	v_pk_fma_f32 v[202:203], v[196:197], v[8:9], v[202:203]
	ds_read_b128 v[194:197], v57 offset:8240
	v_add_f32_e32 v248, v248, v249
	v_pk_fma_f32 v[250:251], v[198:199], v[10:11], v[250:251]
	v_pk_fma_f32 v[202:203], v[200:201], v[12:13], v[202:203]
	ds_read_b128 v[198:201], v57 offset:8256
	v_lshlrev_b32_e32 v227, 16, v227
	v_pk_fma_f32 v[250:251], v[206:207], v[14:15], v[250:251]
	v_pk_fma_f32 v[202:203], v[208:209], v[16:17], v[202:203]
	ds_read_b128 v[206:209], v57 offset:8272
	v_add_f32_e32 v246, v246, v248
	v_pk_fma_f32 v[250:251], v[210:211], v[18:19], v[250:251]
	v_pk_fma_f32 v[202:203], v[212:213], v[20:21], v[202:203]
	v_fma_f32 v30, v226, v227, -v246
	s_waitcnt lgkmcnt(5)
	v_pk_fma_f32 v[250:251], v[214:215], v[22:23], v[250:251]
	v_pk_fma_f32 v[202:203], v[216:217], v[24:25], v[202:203]
	v_mad_u32_u24 v61, v55, 30, v51
	ds_read_u16 v221, v61
	ds_read_b32 v220, v53 offset:120
	ds_read_b128 v[210:213], v57 offset:8432
	ds_read_b128 v[214:217], v57 offset:8448
	v_pk_fma_f32 v[250:251], v[238:239], v[26:27], v[250:251]
	v_pk_fma_f32 v[202:203], v[240:241], v[28:29], v[202:203]
	ds_read_b128 v[238:241], v57 offset:8464
	v_pk_fma_f32 v[250:251], v[242:243], v[30:31], v[250:251]
	v_pk_fma_f32 v[202:203], v[244:245], v[32:33], v[202:203]
	ds_read_b128 v[242:245], v57 offset:8480
	v_pk_fma_f32 v[246:247], v[174:175], v[2:3], 0 op_sel_hi:[1,1,0]
	v_pk_fma_f32 v[248:249], v[176:177], v[4:5], 0 op_sel_hi:[1,1,0]
	ds_read_b128 v[174:177], v57 offset:8496
	v_add_f32_e32 v250, v250, v251
	v_pk_fma_f32 v[246:247], v[178:179], v[6:7], v[246:247]
	v_pk_fma_f32 v[248:249], v[180:181], v[8:9], v[248:249]
	ds_read_b128 v[178:181], v57 offset:8512
	v_add_f32_e32 v202, v202, v203
	v_pk_fma_f32 v[246:247], v[182:183], v[10:11], v[246:247]
	v_pk_fma_f32 v[248:249], v[184:185], v[12:13], v[248:249]
	v_lshlrev_b32_e32 v59, 16, v59
	s_waitcnt lgkmcnt(5)
	v_pk_fma_f32 v[246:247], v[186:187], v[14:15], v[246:247]
	v_pk_fma_f32 v[248:249], v[188:189], v[16:17], v[248:249]
	ds_read_b128 v[182:185], v57 offset:8528
	ds_read_b128 v[186:189], v57 offset:8544
	v_mad_u32_u24 v61, v55, 31, v51
	ds_read_u16 v227, v61
	ds_read_b32 v226, v53 offset:124
	v_add_f32_e32 v250, v250, v202
	v_pk_fma_f32 v[246:247], v[190:191], v[18:19], v[246:247]
	v_pk_fma_f32 v[248:249], v[192:193], v[20:21], v[248:249]
	ds_read_b128 v[190:193], v57 offset:8704
	v_fma_f32 v31, v204, v59, -v250
	v_pk_fma_f32 v[246:247], v[194:195], v[22:23], v[246:247]
	v_pk_fma_f32 v[248:249], v[196:197], v[24:25], v[248:249]
	ds_read_b128 v[194:197], v57 offset:8720
	v_pk_fma_f32 v[246:247], v[198:199], v[26:27], v[246:247]
	v_pk_fma_f32 v[248:249], v[200:201], v[28:29], v[248:249]
	ds_read_b128 v[198:201], v57 offset:8736
	v_pk_fma_f32 v[246:247], v[206:207], v[30:31], v[246:247]
	v_pk_fma_f32 v[248:249], v[208:209], v[32:33], v[248:249]
	ds_read_b128 v[206:209], v57 offset:8752
	v_pk_fma_f32 v[250:251], v[210:211], v[2:3], 0 op_sel_hi:[1,1,0]
	v_pk_fma_f32 v[202:203], v[212:213], v[4:5], 0 op_sel_hi:[1,1,0]
	v_add_f32_e32 v246, v246, v247
	s_waitcnt lgkmcnt(5)
	v_pk_fma_f32 v[250:251], v[214:215], v[6:7], v[250:251]
	v_pk_fma_f32 v[202:203], v[216:217], v[8:9], v[202:203]
	ds_read_b128 v[210:213], v57 offset:8768
	ds_read_b128 v[214:217], v57 offset:8784
	v_add_f32_e32 v248, v248, v249
	v_pk_fma_f32 v[250:251], v[238:239], v[10:11], v[250:251]
	v_pk_fma_f32 v[202:203], v[240:241], v[12:13], v[202:203]
	ds_read_b128 v[238:241], v57 offset:8800
	v_lshlrev_b32_e32 v221, 16, v221
	v_pk_fma_f32 v[250:251], v[242:243], v[14:15], v[250:251]
	v_pk_fma_f32 v[202:203], v[244:245], v[16:17], v[202:203]
	ds_read_b128 v[242:245], v57 offset:8816
	v_mad_u32_u24 v61, v55, 32, v51
	ds_read_u16 v59, v61
	ds_read_b32 v204, v53 offset:128
	v_add_f32_e32 v246, v246, v248
	v_pk_fma_f32 v[250:251], v[174:175], v[18:19], v[250:251]
	v_pk_fma_f32 v[202:203], v[176:177], v[20:21], v[202:203]
	ds_read_b128 v[174:177], v57 offset:8976
	v_fma_f32 v32, v220, v221, -v246
	v_pk_fma_f32 v[250:251], v[178:179], v[22:23], v[250:251]
	v_pk_fma_f32 v[202:203], v[180:181], v[24:25], v[202:203]
	ds_read_b128 v[178:181], v57 offset:8992
	v_pk_fma_f32 v[250:251], v[182:183], v[26:27], v[250:251]
	v_pk_fma_f32 v[202:203], v[184:185], v[28:29], v[202:203]
	v_pk_fma_f32 v[250:251], v[186:187], v[30:31], v[250:251]
	v_pk_fma_f32 v[202:203], v[188:189], v[32:33], v[202:203]
	s_waitcnt lgkmcnt(5)
	v_pk_fma_f32 v[246:247], v[190:191], v[2:3], 0 op_sel_hi:[1,1,0]
	v_pk_fma_f32 v[248:249], v[192:193], v[4:5], 0 op_sel_hi:[1,1,0]
	ds_read_b128 v[182:185], v57 offset:9008
	ds_read_b128 v[186:189], v57 offset:9024
	ds_read_b128 v[190:193], v57 offset:9040
	v_add_f32_e32 v250, v250, v251
	v_pk_fma_f32 v[246:247], v[194:195], v[6:7], v[246:247]
	v_pk_fma_f32 v[248:249], v[196:197], v[8:9], v[248:249]
	ds_read_b128 v[194:197], v57 offset:9056
	v_add_f32_e32 v202, v202, v203
	v_pk_fma_f32 v[246:247], v[198:199], v[10:11], v[246:247]
	v_pk_fma_f32 v[248:249], v[200:201], v[12:13], v[248:249]
	ds_read_b128 v[198:201], v57 offset:9072
	v_lshlrev_b32_e32 v227, 16, v227
	v_pk_fma_f32 v[246:247], v[206:207], v[14:15], v[246:247]
	v_pk_fma_f32 v[248:249], v[208:209], v[16:17], v[248:249]
	ds_read_b128 v[206:209], v57 offset:9088
	v_add_f32_e32 v250, v250, v202
	v_pk_fma_f32 v[246:247], v[210:211], v[18:19], v[246:247]
	v_pk_fma_f32 v[248:249], v[212:213], v[20:21], v[248:249]
	ds_read_b128 v[210:213], v57 offset:9104
	v_fma_f32 v33, v226, v227, -v250
	v_pk_fma_f32 v[246:247], v[214:215], v[22:23], v[246:247]
	v_pk_fma_f32 v[248:249], v[216:217], v[24:25], v[248:249]
	v_pk_fma_f32 v[246:247], v[238:239], v[26:27], v[246:247]
	v_pk_fma_f32 v[248:249], v[240:241], v[28:29], v[248:249]
	s_waitcnt lgkmcnt(5)
	v_pk_fma_f32 v[246:247], v[242:243], v[30:31], v[246:247]
	v_pk_fma_f32 v[248:249], v[244:245], v[32:33], v[248:249]
	v_mad_u32_u24 v61, v55, 33, v51
	ds_read_u16 v221, v61
	ds_read_b32 v220, v53 offset:132
	ds_read_b128 v[214:217], v57 offset:9248
	ds_read_b128 v[238:241], v57 offset:9264
	ds_read_b128 v[242:245], v57 offset:9280
	v_pk_fma_f32 v[250:251], v[174:175], v[2:3], 0 op_sel_hi:[1,1,0]
	v_pk_fma_f32 v[202:203], v[176:177], v[4:5], 0 op_sel_hi:[1,1,0]
	ds_read_b128 v[174:177], v57 offset:9296
	v_add_f32_e32 v246, v246, v247
	v_pk_fma_f32 v[250:251], v[178:179], v[6:7], v[250:251]
	v_pk_fma_f32 v[202:203], v[180:181], v[8:9], v[202:203]
	ds_read_b128 v[178:181], v57 offset:9312
	v_add_f32_e32 v248, v248, v249
	v_pk_fma_f32 v[250:251], v[182:183], v[10:11], v[250:251]
	v_pk_fma_f32 v[202:203], v[184:185], v[12:13], v[202:203]
	ds_read_b128 v[182:185], v57 offset:9328
	v_lshlrev_b32_e32 v59, 16, v59
	v_pk_fma_f32 v[250:251], v[186:187], v[14:15], v[250:251]
	v_pk_fma_f32 v[202:203], v[188:189], v[16:17], v[202:203]
	v_add_f32_e32 v246, v246, v248
	s_waitcnt lgkmcnt(5)
	v_pk_fma_f32 v[250:251], v[190:191], v[18:19], v[250:251]
	v_pk_fma_f32 v[202:203], v[192:193], v[20:21], v[202:203]
	ds_read_b128 v[186:189], v57 offset:9344
	ds_read_b128 v[190:193], v57 offset:9360
	v_fma_f32 v34, v204, v59, -v246
	v_pk_fma_f32 v[250:251], v[194:195], v[22:23], v[250:251]
	v_pk_fma_f32 v[202:203], v[196:197], v[24:25], v[202:203]
	ds_read_b128 v[194:197], v57 offset:9376
	v_mad_u32_u24 v61, v55, 34, v51
	ds_read_u16 v227, v61
	ds_read_b32 v226, v53 offset:136
	v_pk_fma_f32 v[250:251], v[198:199], v[26:27], v[250:251]
	v_pk_fma_f32 v[202:203], v[200:201], v[28:29], v[202:203]
	ds_read_b128 v[198:201], v57 offset:9520
	v_pk_fma_f32 v[250:251], v[206:207], v[30:31], v[250:251]
	v_pk_fma_f32 v[202:203], v[208:209], v[32:33], v[202:203]
	ds_read_b128 v[206:209], v57 offset:9536
	v_pk_fma_f32 v[250:251], v[210:211], v[34:35], v[250:251]
	v_pk_fma_f32 v[202:203], v[212:213], v[36:37], v[202:203]
	ds_read_b128 v[210:213], v57 offset:9552
	v_pk_fma_f32 v[246:247], v[214:215], v[2:3], 0 op_sel_hi:[1,1,0]
	v_pk_fma_f32 v[248:249], v[216:217], v[4:5], 0 op_sel_hi:[1,1,0]
	v_add_f32_e32 v250, v250, v251
	s_waitcnt lgkmcnt(5)
	v_pk_fma_f32 v[246:247], v[238:239], v[6:7], v[246:247]
	v_pk_fma_f32 v[248:249], v[240:241], v[8:9], v[248:249]
	ds_read_b128 v[214:217], v57 offset:9568
	ds_read_b128 v[238:241], v57 offset:9584
	v_add_f32_e32 v202, v202, v203
	v_pk_fma_f32 v[246:247], v[242:243], v[10:11], v[246:247]
	v_pk_fma_f32 v[248:249], v[244:245], v[12:13], v[248:249]
	ds_read_b128 v[242:245], v57 offset:9600
	v_lshlrev_b32_e32 v221, 16, v221
	v_pk_fma_f32 v[246:247], v[174:175], v[14:15], v[246:247]
	v_pk_fma_f32 v[248:249], v[176:177], v[16:17], v[248:249]
	ds_read_b128 v[174:177], v57 offset:9616
	v_add_f32_e32 v250, v250, v202
	v_pk_fma_f32 v[246:247], v[178:179], v[18:19], v[246:247]
	v_pk_fma_f32 v[248:249], v[180:181], v[20:21], v[248:249]
	ds_read_b128 v[178:181], v57 offset:9632
	v_fma_f32 v35, v220, v221, -v250
	v_pk_fma_f32 v[246:247], v[182:183], v[22:23], v[246:247]
	v_pk_fma_f32 v[248:249], v[184:185], v[24:25], v[248:249]
	ds_read_b128 v[182:185], v57 offset:9648
	v_mad_u32_u24 v61, v55, 35, v51
	ds_read_u16 v59, v61
	ds_read_b32 v204, v53 offset:140
	v_pk_fma_f32 v[246:247], v[186:187], v[26:27], v[246:247]
	v_pk_fma_f32 v[248:249], v[188:189], v[28:29], v[248:249]
	v_pk_fma_f32 v[246:247], v[190:191], v[30:31], v[246:247]
	v_pk_fma_f32 v[248:249], v[192:193], v[32:33], v[248:249]
	v_pk_fma_f32 v[246:247], v[194:195], v[34:35], v[246:247]
	v_pk_fma_f32 v[248:249], v[196:197], v[36:37], v[248:249]
	s_waitcnt lgkmcnt(5)
	v_pk_fma_f32 v[250:251], v[198:199], v[2:3], 0 op_sel_hi:[1,1,0]
	v_pk_fma_f32 v[202:203], v[200:201], v[4:5], 0 op_sel_hi:[1,1,0]
	ds_read_b128 v[186:189], v57 offset:9792
	ds_read_b128 v[190:193], v57 offset:9808
	ds_read_b128 v[194:197], v57 offset:9824
	ds_read_b128 v[198:201], v57 offset:9840
	v_add_f32_e32 v246, v246, v247
	v_pk_fma_f32 v[250:251], v[206:207], v[6:7], v[250:251]
	v_pk_fma_f32 v[202:203], v[208:209], v[8:9], v[202:203]
	ds_read_b128 v[206:209], v57 offset:9856
	v_add_f32_e32 v248, v248, v249
	v_pk_fma_f32 v[250:251], v[210:211], v[10:11], v[250:251]
	v_pk_fma_f32 v[202:203], v[212:213], v[12:13], v[202:203]
	ds_read_b128 v[210:213], v57 offset:9872
	v_lshlrev_b32_e32 v227, 16, v227
	v_pk_fma_f32 v[250:251], v[214:215], v[14:15], v[250:251]
	v_pk_fma_f32 v[202:203], v[216:217], v[16:17], v[202:203]
	ds_read_b128 v[214:217], v57 offset:9888
	v_add_f32_e32 v246, v246, v248
	v_pk_fma_f32 v[250:251], v[238:239], v[18:19], v[250:251]
	v_pk_fma_f32 v[202:203], v[240:241], v[20:21], v[202:203]
	ds_read_b128 v[238:241], v57 offset:9904
	v_fma_f32 v36, v226, v227, -v246
	v_pk_fma_f32 v[250:251], v[242:243], v[22:23], v[250:251]
	v_pk_fma_f32 v[202:203], v[244:245], v[24:25], v[202:203]
	s_waitcnt lgkmcnt(5)
	v_pk_fma_f32 v[250:251], v[174:175], v[26:27], v[250:251]
	v_pk_fma_f32 v[202:203], v[176:177], v[28:29], v[202:203]
	ds_read_b128 v[242:245], v57 offset:9920
	v_mad_u32_u24 v61, v55, 36, v51
	ds_read_u16 v221, v61
	ds_read_b32 v220, v53 offset:144
	ds_read_b128 v[174:177], v57 offset:10064
	v_pk_fma_f32 v[250:251], v[178:179], v[30:31], v[250:251]
	v_pk_fma_f32 v[202:203], v[180:181], v[32:33], v[202:203]
	ds_read_b128 v[178:181], v57 offset:10080
	v_pk_fma_f32 v[250:251], v[182:183], v[34:35], v[250:251]
	v_pk_fma_f32 v[202:203], v[184:185], v[36:37], v[202:203]
	ds_read_b128 v[182:185], v57 offset:10096
	v_pk_fma_f32 v[246:247], v[186:187], v[2:3], 0 op_sel_hi:[1,1,0]
	v_pk_fma_f32 v[248:249], v[188:189], v[4:5], 0 op_sel_hi:[1,1,0]
	ds_read_b128 v[186:189], v57 offset:10112
	v_add_f32_e32 v250, v250, v251
	v_pk_fma_f32 v[246:247], v[190:191], v[6:7], v[246:247]
	v_pk_fma_f32 v[248:249], v[192:193], v[8:9], v[248:249]
	ds_read_b128 v[190:193], v57 offset:10128
	v_add_f32_e32 v202, v202, v203
	v_pk_fma_f32 v[246:247], v[194:195], v[10:11], v[246:247]
	v_pk_fma_f32 v[248:249], v[196:197], v[12:13], v[248:249]
	v_lshlrev_b32_e32 v59, 16, v59
	s_waitcnt lgkmcnt(5)
	v_pk_fma_f32 v[246:247], v[198:199], v[14:15], v[246:247]
	v_pk_fma_f32 v[248:249], v[200:201], v[16:17], v[248:249]
	ds_read_b128 v[194:197], v57 offset:10144
	ds_read_b128 v[198:201], v57 offset:10160
	v_add_f32_e32 v250, v250, v202
	v_pk_fma_f32 v[246:247], v[206:207], v[18:19], v[246:247]
	v_pk_fma_f32 v[248:249], v[208:209], v[20:21], v[248:249]
	ds_read_b128 v[206:209], v57 offset:10176
	v_fma_f32 v37, v204, v59, -v250
	v_pk_fma_f32 v[246:247], v[210:211], v[22:23], v[246:247]
	v_pk_fma_f32 v[248:249], v[212:213], v[24:25], v[248:249]
	ds_read_b128 v[210:213], v57 offset:10192
	v_pk_fma_f32 v[246:247], v[214:215], v[26:27], v[246:247]
	v_pk_fma_f32 v[248:249], v[216:217], v[28:29], v[248:249]
	ds_read_b128 v[214:217], v57 offset:10208
	v_mad_u32_u24 v61, v55, 37, v51
	ds_read_u16 v227, v61
	ds_read_b32 v226, v53 offset:148
	v_pk_fma_f32 v[246:247], v[238:239], v[30:31], v[246:247]
	v_pk_fma_f32 v[248:249], v[240:241], v[32:33], v[248:249]
	ds_read_b128 v[238:241], v57 offset:10336
	v_pk_fma_f32 v[246:247], v[242:243], v[34:35], v[246:247]
	v_pk_fma_f32 v[248:249], v[244:245], v[36:37], v[248:249]
	s_waitcnt lgkmcnt(5)
	v_pk_fma_f32 v[250:251], v[174:175], v[2:3], 0 op_sel_hi:[1,1,0]
	v_pk_fma_f32 v[202:203], v[176:177], v[4:5], 0 op_sel_hi:[1,1,0]
	ds_read_b128 v[242:245], v57 offset:10352
	ds_read_b128 v[174:177], v57 offset:10368
	v_add_f32_e32 v246, v246, v247
	v_pk_fma_f32 v[250:251], v[178:179], v[6:7], v[250:251]
	v_pk_fma_f32 v[202:203], v[180:181], v[8:9], v[202:203]
	ds_read_b128 v[178:181], v57 offset:10384
	v_add_f32_e32 v248, v248, v249
	v_pk_fma_f32 v[250:251], v[182:183], v[10:11], v[250:251]
	v_pk_fma_f32 v[202:203], v[184:185], v[12:13], v[202:203]
	ds_read_b128 v[182:185], v57 offset:10400
	v_lshlrev_b32_e32 v221, 16, v221
	v_pk_fma_f32 v[250:251], v[186:187], v[14:15], v[250:251]
	v_pk_fma_f32 v[202:203], v[188:189], v[16:17], v[202:203]
	ds_read_b128 v[186:189], v57 offset:10416
	v_add_f32_e32 v246, v246, v248
	v_pk_fma_f32 v[250:251], v[190:191], v[18:19], v[250:251]
	v_pk_fma_f32 v[202:203], v[192:193], v[20:21], v[202:203]
	ds_read_b128 v[190:193], v57 offset:10432
	v_fma_f32 v86, v220, v221, -v246
	v_pk_fma_f32 v[250:251], v[194:195], v[22:23], v[250:251]
	v_pk_fma_f32 v[202:203], v[196:197], v[24:25], v[202:203]
	ds_read_b128 v[194:197], v57 offset:10448
	v_pk_fma_f32 v[250:251], v[198:199], v[26:27], v[250:251]
	v_pk_fma_f32 v[202:203], v[200:201], v[28:29], v[202:203]
	ds_read_b128 v[198:201], v57 offset:10464
	v_pk_fma_f32 v[250:251], v[206:207], v[30:31], v[250:251]
	v_pk_fma_f32 v[202:203], v[208:209], v[32:33], v[202:203]
	s_waitcnt lgkmcnt(5)
	v_pk_fma_f32 v[250:251], v[210:211], v[34:35], v[250:251]
	v_pk_fma_f32 v[202:203], v[212:213], v[36:37], v[202:203]
	ds_read_b128 v[206:209], v57 offset:10480
	v_mad_u32_u24 v61, v55, 38, v51
	ds_read_u16 v59, v61
	ds_read_b32 v204, v53 offset:152
	ds_read_b128 v[210:213], v57 offset:10608
	v_pk_fma_f32 v[250:251], v[214:215], v[86:87], v[250:251]
	v_pk_fma_f32 v[202:203], v[216:217], v[88:89], v[202:203]
	ds_read_b128 v[214:217], v57 offset:10624
	v_pk_fma_f32 v[246:247], v[238:239], v[2:3], 0 op_sel_hi:[1,1,0]
	v_pk_fma_f32 v[248:249], v[240:241], v[4:5], 0 op_sel_hi:[1,1,0]
	ds_read_b128 v[238:241], v57 offset:10640
	v_add_f32_e32 v250, v250, v251
	v_pk_fma_f32 v[246:247], v[242:243], v[6:7], v[246:247]
	v_pk_fma_f32 v[248:249], v[244:245], v[8:9], v[248:249]
	ds_read_b128 v[242:245], v57 offset:10656
	v_add_f32_e32 v202, v202, v203
	v_pk_fma_f32 v[246:247], v[174:175], v[10:11], v[246:247]
	v_pk_fma_f32 v[248:249], v[176:177], v[12:13], v[248:249]
	ds_read_b128 v[174:177], v57 offset:10672
	v_lshlrev_b32_e32 v227, 16, v227
	v_pk_fma_f32 v[246:247], v[178:179], v[14:15], v[246:247]
	v_pk_fma_f32 v[248:249], v[180:181], v[16:17], v[248:249]
	v_add_f32_e32 v250, v250, v202
	s_waitcnt lgkmcnt(5)
	v_pk_fma_f32 v[246:247], v[182:183], v[18:19], v[246:247]
	v_pk_fma_f32 v[248:249], v[184:185], v[20:21], v[248:249]
	ds_read_b128 v[178:181], v57 offset:10688
	ds_read_b128 v[182:185], v57 offset:10704
	v_fma_f32 v87, v226, v227, -v250
	v_pk_fma_f32 v[246:247], v[186:187], v[22:23], v[246:247]
	v_pk_fma_f32 v[248:249], v[188:189], v[24:25], v[248:249]
	ds_read_b128 v[186:189], v57 offset:10720
	v_pk_fma_f32 v[246:247], v[190:191], v[26:27], v[246:247]
	v_pk_fma_f32 v[248:249], v[192:193], v[28:29], v[248:249]
	ds_read_b128 v[190:193], v57 offset:10736
	v_pk_fma_f32 v[246:247], v[194:195], v[30:31], v[246:247]
	v_pk_fma_f32 v[248:249], v[196:197], v[32:33], v[248:249]
	ds_read_b128 v[194:197], v57 offset:10752
	v_mad_u32_u24 v61, v55, 39, v51
	ds_read_u16 v221, v61
	ds_read_b32 v220, v53 offset:156
	v_pk_fma_f32 v[246:247], v[198:199], v[34:35], v[246:247]
	v_pk_fma_f32 v[248:249], v[200:201], v[36:37], v[248:249]
	ds_read_b128 v[198:201], v57 offset:10880
	v_pk_fma_f32 v[246:247], v[206:207], v[86:87], v[246:247]
	v_pk_fma_f32 v[248:249], v[208:209], v[88:89], v[248:249]
	s_waitcnt lgkmcnt(5)
	v_pk_fma_f32 v[250:251], v[210:211], v[2:3], 0 op_sel_hi:[1,1,0]
	v_pk_fma_f32 v[202:203], v[212:213], v[4:5], 0 op_sel_hi:[1,1,0]
	ds_read_b128 v[206:209], v57 offset:10896
	ds_read_b128 v[210:213], v57 offset:10912
	v_add_f32_e32 v246, v246, v247
	v_pk_fma_f32 v[250:251], v[214:215], v[6:7], v[250:251]
	v_pk_fma_f32 v[202:203], v[216:217], v[8:9], v[202:203]
	ds_read_b128 v[214:217], v57 offset:10928
	v_add_f32_e32 v248, v248, v249
	v_pk_fma_f32 v[250:251], v[238:239], v[10:11], v[250:251]
	v_pk_fma_f32 v[202:203], v[240:241], v[12:13], v[202:203]
	ds_read_b128 v[238:241], v57 offset:10944
	v_lshlrev_b32_e32 v59, 16, v59
	v_pk_fma_f32 v[250:251], v[242:243], v[14:15], v[250:251]
	v_pk_fma_f32 v[202:203], v[244:245], v[16:17], v[202:203]
	ds_read_b128 v[242:245], v57 offset:10960
	v_add_f32_e32 v246, v246, v248
	v_pk_fma_f32 v[250:251], v[174:175], v[18:19], v[250:251]
	v_pk_fma_f32 v[202:203], v[176:177], v[20:21], v[202:203]
	ds_read_b128 v[174:177], v57 offset:10976
	v_fma_f32 v88, v204, v59, -v246
	v_pk_fma_f32 v[250:251], v[178:179], v[22:23], v[250:251]
	v_pk_fma_f32 v[202:203], v[180:181], v[24:25], v[202:203]
	ds_read_b128 v[178:181], v57 offset:10992
	v_pk_fma_f32 v[250:251], v[182:183], v[26:27], v[250:251]
	v_pk_fma_f32 v[202:203], v[184:185], v[28:29], v[202:203]
	ds_read_b128 v[182:185], v57 offset:11008
	v_pk_fma_f32 v[250:251], v[186:187], v[30:31], v[250:251]
	v_pk_fma_f32 v[202:203], v[188:189], v[32:33], v[202:203]
	s_waitcnt lgkmcnt(5)
	v_pk_fma_f32 v[250:251], v[190:191], v[34:35], v[250:251]
	v_pk_fma_f32 v[202:203], v[192:193], v[36:37], v[202:203]
	ds_read_b128 v[186:189], v57 offset:11024
	v_mad_u32_u24 v61, v55, 40, v51
	ds_read_u16 v227, v61
	ds_read_b32 v226, v53 offset:160
	ds_read_b128 v[190:193], v57 offset:11152
	v_pk_fma_f32 v[250:251], v[194:195], v[86:87], v[250:251]
	v_pk_fma_f32 v[202:203], v[196:197], v[88:89], v[202:203]
	ds_read_b128 v[194:197], v57 offset:11168
	v_pk_fma_f32 v[246:247], v[198:199], v[2:3], 0 op_sel_hi:[1,1,0]
	v_pk_fma_f32 v[248:249], v[200:201], v[4:5], 0 op_sel_hi:[1,1,0]
	ds_read_b128 v[198:201], v57 offset:11184
	v_add_f32_e32 v250, v250, v251
	v_pk_fma_f32 v[246:247], v[206:207], v[6:7], v[246:247]
	v_pk_fma_f32 v[248:249], v[208:209], v[8:9], v[248:249]
	ds_read_b128 v[206:209], v57 offset:11200
	v_add_f32_e32 v202, v202, v203
	v_pk_fma_f32 v[246:247], v[210:211], v[10:11], v[246:247]
	v_pk_fma_f32 v[248:249], v[212:213], v[12:13], v[248:249]
	ds_read_b128 v[210:213], v57 offset:11216
	v_lshlrev_b32_e32 v221, 16, v221
	v_pk_fma_f32 v[246:247], v[214:215], v[14:15], v[246:247]
	v_pk_fma_f32 v[248:249], v[216:217], v[16:17], v[248:249]
	v_add_f32_e32 v250, v250, v202
	s_waitcnt lgkmcnt(5)
	v_pk_fma_f32 v[246:247], v[238:239], v[18:19], v[246:247]
	v_pk_fma_f32 v[248:249], v[240:241], v[20:21], v[248:249]
	ds_read_b128 v[214:217], v57 offset:11232
	ds_read_b128 v[238:241], v57 offset:11248
	v_fma_f32 v89, v220, v221, -v250
	v_pk_fma_f32 v[246:247], v[242:243], v[22:23], v[246:247]
	v_pk_fma_f32 v[248:249], v[244:245], v[24:25], v[248:249]
	ds_read_b128 v[242:245], v57 offset:11264
	v_pk_fma_f32 v[246:247], v[174:175], v[26:27], v[246:247]
	v_pk_fma_f32 v[248:249], v[176:177], v[28:29], v[248:249]
	ds_read_b128 v[174:177], v57 offset:11280
	v_pk_fma_f32 v[246:247], v[178:179], v[30:31], v[246:247]
	v_pk_fma_f32 v[248:249], v[180:181], v[32:33], v[248:249]
	ds_read_b128 v[178:181], v57 offset:11296
	v_pk_fma_f32 v[246:247], v[182:183], v[34:35], v[246:247]
	v_pk_fma_f32 v[248:249], v[184:185], v[36:37], v[248:249]
	ds_read_b128 v[182:185], v57 offset:11312
	v_mad_u32_u24 v61, v55, 41, v51
	ds_read_u16 v59, v61
	ds_read_b32 v204, v53 offset:164
	v_pk_fma_f32 v[246:247], v[186:187], v[86:87], v[246:247]
	v_pk_fma_f32 v[248:249], v[188:189], v[88:89], v[248:249]
	s_waitcnt lgkmcnt(5)
	v_pk_fma_f32 v[250:251], v[190:191], v[2:3], 0 op_sel_hi:[1,1,0]
	v_pk_fma_f32 v[202:203], v[192:193], v[4:5], 0 op_sel_hi:[1,1,0]
	ds_read_b128 v[186:189], v57 offset:11424
	ds_read_b128 v[190:193], v57 offset:11440
	v_add_f32_e32 v246, v246, v247
	v_pk_fma_f32 v[250:251], v[194:195], v[6:7], v[250:251]
	v_pk_fma_f32 v[202:203], v[196:197], v[8:9], v[202:203]
	ds_read_b128 v[194:197], v57 offset:11456
	v_add_f32_e32 v248, v248, v249
	v_pk_fma_f32 v[250:251], v[198:199], v[10:11], v[250:251]
	v_pk_fma_f32 v[202:203], v[200:201], v[12:13], v[202:203]
	ds_read_b128 v[198:201], v57 offset:11472
	v_lshlrev_b32_e32 v227, 16, v227
	v_pk_fma_f32 v[250:251], v[206:207], v[14:15], v[250:251]
	v_pk_fma_f32 v[202:203], v[208:209], v[16:17], v[202:203]
	ds_read_b128 v[206:209], v57 offset:11488
	v_add_f32_e32 v246, v246, v248
	v_pk_fma_f32 v[250:251], v[210:211], v[18:19], v[250:251]
	v_pk_fma_f32 v[202:203], v[212:213], v[20:21], v[202:203]
	ds_read_b128 v[210:213], v57 offset:11504
	v_fma_f32 v90, v226, v227, -v246
	v_pk_fma_f32 v[250:251], v[214:215], v[22:23], v[250:251]
	v_pk_fma_f32 v[202:203], v[216:217], v[24:25], v[202:203]
	ds_read_b128 v[214:217], v57 offset:11520
	v_pk_fma_f32 v[250:251], v[238:239], v[26:27], v[250:251]
	v_pk_fma_f32 v[202:203], v[240:241], v[28:29], v[202:203]
	ds_read_b128 v[238:241], v57 offset:11536
	v_pk_fma_f32 v[250:251], v[242:243], v[30:31], v[250:251]
	v_pk_fma_f32 v[202:203], v[244:245], v[32:33], v[202:203]
	s_waitcnt lgkmcnt(5)
	v_pk_fma_f32 v[250:251], v[174:175], v[34:35], v[250:251]
	v_pk_fma_f32 v[202:203], v[176:177], v[36:37], v[202:203]
	ds_read_b128 v[242:245], v57 offset:11552
	ds_read_b128 v[174:177], v57 offset:11568
	v_pk_fma_f32 v[250:251], v[178:179], v[86:87], v[250:251]
	v_pk_fma_f32 v[202:203], v[180:181], v[88:89], v[202:203]
	ds_read_b128 v[178:181], v57 offset:11584
	v_mad_u32_u24 v61, v55, 42, v51
	ds_read_u16 v221, v61
	ds_read_b32 v220, v53 offset:168
	v_pk_fma_f32 v[250:251], v[182:183], v[90:91], v[250:251]
	v_pk_fma_f32 v[202:203], v[184:185], v[92:93], v[202:203]
	ds_read_b128 v[182:185], v57 offset:11696
	v_pk_fma_f32 v[246:247], v[186:187], v[2:3], 0 op_sel_hi:[1,1,0]
	v_pk_fma_f32 v[248:249], v[188:189], v[4:5], 0 op_sel_hi:[1,1,0]
	ds_read_b128 v[186:189], v57 offset:11712
	v_add_f32_e32 v250, v250, v251
	v_pk_fma_f32 v[246:247], v[190:191], v[6:7], v[246:247]
	v_pk_fma_f32 v[248:249], v[192:193], v[8:9], v[248:249]
	ds_read_b128 v[190:193], v57 offset:11728
	v_add_f32_e32 v202, v202, v203
	v_pk_fma_f32 v[246:247], v[194:195], v[10:11], v[246:247]
	v_pk_fma_f32 v[248:249], v[196:197], v[12:13], v[248:249]
	v_lshlrev_b32_e32 v59, 16, v59
	s_waitcnt lgkmcnt(5)
	v_pk_fma_f32 v[246:247], v[198:199], v[14:15], v[246:247]
	v_pk_fma_f32 v[248:249], v[200:201], v[16:17], v[248:249]
	ds_read_b128 v[194:197], v57 offset:11744
	ds_read_b128 v[198:201], v57 offset:11760
	v_add_f32_e32 v250, v250, v202
	v_pk_fma_f32 v[246:247], v[206:207], v[18:19], v[246:247]
	v_pk_fma_f32 v[248:249], v[208:209], v[20:21], v[248:249]
	ds_read_b128 v[206:209], v57 offset:11776
	v_fma_f32 v91, v204, v59, -v250
	v_pk_fma_f32 v[246:247], v[210:211], v[22:23], v[246:247]
	v_pk_fma_f32 v[248:249], v[212:213], v[24:25], v[248:249]
	ds_read_b128 v[210:213], v57 offset:11792
	v_pk_fma_f32 v[246:247], v[214:215], v[26:27], v[246:247]
	v_pk_fma_f32 v[248:249], v[216:217], v[28:29], v[248:249]
	ds_read_b128 v[214:217], v57 offset:11808
	v_pk_fma_f32 v[246:247], v[238:239], v[30:31], v[246:247]
	v_pk_fma_f32 v[248:249], v[240:241], v[32:33], v[248:249]
	ds_read_b128 v[238:241], v57 offset:11824
	v_pk_fma_f32 v[246:247], v[242:243], v[34:35], v[246:247]
	v_pk_fma_f32 v[248:249], v[244:245], v[36:37], v[248:249]
	ds_read_b128 v[242:245], v57 offset:11840
	v_pk_fma_f32 v[246:247], v[174:175], v[86:87], v[246:247]
	v_pk_fma_f32 v[248:249], v[176:177], v[88:89], v[248:249]
	ds_read_b128 v[174:177], v57 offset:11856
	v_pk_fma_f32 v[246:247], v[178:179], v[90:91], v[246:247]
	v_pk_fma_f32 v[248:249], v[180:181], v[92:93], v[248:249]
	s_waitcnt lgkmcnt(5)
	v_pk_fma_f32 v[250:251], v[182:183], v[2:3], 0 op_sel_hi:[1,1,0]
	v_pk_fma_f32 v[202:203], v[184:185], v[4:5], 0 op_sel_hi:[1,1,0]
	v_mad_u32_u24 v61, v55, 43, v51
	ds_read_u16 v227, v61
	ds_read_b32 v226, v53 offset:172
	ds_read_b128 v[178:181], v57 offset:11968
	ds_read_b128 v[182:185], v57 offset:11984
	v_add_f32_e32 v246, v246, v247
	v_pk_fma_f32 v[250:251], v[186:187], v[6:7], v[250:251]
	v_pk_fma_f32 v[202:203], v[188:189], v[8:9], v[202:203]
	ds_read_b128 v[186:189], v57 offset:12000
	v_add_f32_e32 v248, v248, v249
	v_pk_fma_f32 v[250:251], v[190:191], v[10:11], v[250:251]
	v_pk_fma_f32 v[202:203], v[192:193], v[12:13], v[202:203]
	ds_read_b128 v[190:193], v57 offset:12016
	v_lshlrev_b32_e32 v221, 16, v221
	v_pk_fma_f32 v[250:251], v[194:195], v[14:15], v[250:251]
	v_pk_fma_f32 v[202:203], v[196:197], v[16:17], v[202:203]
	ds_read_b128 v[194:197], v57 offset:12032
	v_add_f32_e32 v246, v246, v248
	v_pk_fma_f32 v[250:251], v[198:199], v[18:19], v[250:251]
	v_pk_fma_f32 v[202:203], v[200:201], v[20:21], v[202:203]
	ds_read_b128 v[198:201], v57 offset:12048
	v_fma_f32 v92, v220, v221, -v246
	v_pk_fma_f32 v[250:251], v[206:207], v[22:23], v[250:251]
	v_pk_fma_f32 v[202:203], v[208:209], v[24:25], v[202:203]
	s_waitcnt lgkmcnt(5)
	v_pk_fma_f32 v[250:251], v[210:211], v[26:27], v[250:251]
	v_pk_fma_f32 v[202:203], v[212:213], v[28:29], v[202:203]
	ds_read_b128 v[206:209], v57 offset:12064
	ds_read_b128 v[210:213], v57 offset:12080
	v_pk_fma_f32 v[250:251], v[214:215], v[30:31], v[250:251]
	v_pk_fma_f32 v[202:203], v[216:217], v[32:33], v[202:203]
	ds_read_b128 v[214:217], v57 offset:12096
	v_pk_fma_f32 v[250:251], v[238:239], v[34:35], v[250:251]
	v_pk_fma_f32 v[202:203], v[240:241], v[36:37], v[202:203]
	ds_read_b128 v[238:241], v57 offset:12112
	v_pk_fma_f32 v[250:251], v[242:243], v[86:87], v[250:251]
	v_pk_fma_f32 v[202:203], v[244:245], v[88:89], v[202:203]
	ds_read_b128 v[242:245], v57 offset:12128
	v_mad_u32_u24 v61, v55, 44, v51
	ds_read_u16 v59, v61
	ds_read_b32 v204, v53 offset:176
	v_pk_fma_f32 v[250:251], v[174:175], v[90:91], v[250:251]
	v_pk_fma_f32 v[202:203], v[176:177], v[92:93], v[202:203]
	ds_read_b128 v[174:177], v57 offset:12240
	v_pk_fma_f32 v[246:247], v[178:179], v[2:3], 0 op_sel_hi:[1,1,0]
	v_pk_fma_f32 v[248:249], v[180:181], v[4:5], 0 op_sel_hi:[1,1,0]
	v_add_f32_e32 v250, v250, v251
	s_waitcnt lgkmcnt(5)
	v_pk_fma_f32 v[246:247], v[182:183], v[6:7], v[246:247]
	v_pk_fma_f32 v[248:249], v[184:185], v[8:9], v[248:249]
	ds_read_b128 v[178:181], v57 offset:12256
	ds_read_b128 v[182:185], v57 offset:12272
	v_add_f32_e32 v202, v202, v203
	v_pk_fma_f32 v[246:247], v[186:187], v[10:11], v[246:247]
	v_pk_fma_f32 v[248:249], v[188:189], v[12:13], v[248:249]
	ds_read_b128 v[186:189], v57 offset:12288
	v_lshlrev_b32_e32 v227, 16, v227
	v_pk_fma_f32 v[246:247], v[190:191], v[14:15], v[246:247]
	v_pk_fma_f32 v[248:249], v[192:193], v[16:17], v[248:249]
	ds_read_b128 v[190:193], v57 offset:12304
	v_add_f32_e32 v250, v250, v202
	v_pk_fma_f32 v[246:247], v[194:195], v[18:19], v[246:247]
	v_pk_fma_f32 v[248:249], v[196:197], v[20:21], v[248:249]
	ds_read_b128 v[194:197], v57 offset:12320
	v_fma_f32 v93, v226, v227, -v250
	v_pk_fma_f32 v[246:247], v[198:199], v[22:23], v[246:247]
	v_pk_fma_f32 v[248:249], v[200:201], v[24:25], v[248:249]
	ds_read_b128 v[198:201], v57 offset:12336
	v_pk_fma_f32 v[246:247], v[206:207], v[26:27], v[246:247]
	v_pk_fma_f32 v[248:249], v[208:209], v[28:29], v[248:249]
	ds_read_b128 v[206:209], v57 offset:12352
	v_pk_fma_f32 v[246:247], v[210:211], v[30:31], v[246:247]
	v_pk_fma_f32 v[248:249], v[212:213], v[32:33], v[248:249]
	ds_read_b128 v[210:213], v57 offset:12368
	v_pk_fma_f32 v[246:247], v[214:215], v[34:35], v[246:247]
	v_pk_fma_f32 v[248:249], v[216:217], v[36:37], v[248:249]
	s_waitcnt lgkmcnt(5)
	v_pk_fma_f32 v[246:247], v[238:239], v[86:87], v[246:247]
	v_pk_fma_f32 v[248:249], v[240:241], v[88:89], v[248:249]
	ds_read_b128 v[214:217], v57 offset:12384
	ds_read_b128 v[238:241], v57 offset:12400
	v_pk_fma_f32 v[246:247], v[242:243], v[90:91], v[246:247]
	v_pk_fma_f32 v[248:249], v[244:245], v[92:93], v[248:249]
	ds_read_b128 v[242:245], v57 offset:12416
	v_mad_u32_u24 v61, v55, 45, v51
	ds_read_u16 v221, v61
	ds_read_b32 v220, v53 offset:180
	v_pk_fma_f32 v[250:251], v[174:175], v[2:3], 0 op_sel_hi:[1,1,0]
	v_pk_fma_f32 v[202:203], v[176:177], v[4:5], 0 op_sel_hi:[1,1,0]
	ds_read_b128 v[174:177], v57 offset:12512
	v_add_f32_e32 v246, v246, v247
	v_pk_fma_f32 v[250:251], v[178:179], v[6:7], v[250:251]
	v_pk_fma_f32 v[202:203], v[180:181], v[8:9], v[202:203]
	ds_read_b128 v[178:181], v57 offset:12528
	v_add_f32_e32 v248, v248, v249
	v_pk_fma_f32 v[250:251], v[182:183], v[10:11], v[250:251]
	v_pk_fma_f32 v[202:203], v[184:185], v[12:13], v[202:203]
	ds_read_b128 v[182:185], v57 offset:12544
	v_lshlrev_b32_e32 v59, 16, v59
	v_pk_fma_f32 v[250:251], v[186:187], v[14:15], v[250:251]
	v_pk_fma_f32 v[202:203], v[188:189], v[16:17], v[202:203]
	v_add_f32_e32 v246, v246, v248
	s_waitcnt lgkmcnt(5)
	v_pk_fma_f32 v[250:251], v[190:191], v[18:19], v[250:251]
	v_pk_fma_f32 v[202:203], v[192:193], v[20:21], v[202:203]
	ds_read_b128 v[186:189], v57 offset:12560
	ds_read_b128 v[190:193], v57 offset:12576
	v_fma_f32 v94, v204, v59, -v246
	v_pk_fma_f32 v[250:251], v[194:195], v[22:23], v[250:251]
	v_pk_fma_f32 v[202:203], v[196:197], v[24:25], v[202:203]
	ds_read_b128 v[194:197], v57 offset:12592
	v_pk_fma_f32 v[250:251], v[198:199], v[26:27], v[250:251]
	v_pk_fma_f32 v[202:203], v[200:201], v[28:29], v[202:203]
	ds_read_b128 v[198:201], v57 offset:12608
	v_pk_fma_f32 v[250:251], v[206:207], v[30:31], v[250:251]
	v_pk_fma_f32 v[202:203], v[208:209], v[32:33], v[202:203]
	ds_read_b128 v[206:209], v57 offset:12624
	v_pk_fma_f32 v[250:251], v[210:211], v[34:35], v[250:251]
	v_pk_fma_f32 v[202:203], v[212:213], v[36:37], v[202:203]
	ds_read_b128 v[210:213], v57 offset:12640
	v_pk_fma_f32 v[250:251], v[214:215], v[86:87], v[250:251]
	v_pk_fma_f32 v[202:203], v[216:217], v[88:89], v[202:203]
	ds_read_b128 v[214:217], v57 offset:12656
	v_pk_fma_f32 v[250:251], v[238:239], v[90:91], v[250:251]
	v_pk_fma_f32 v[202:203], v[240:241], v[92:93], v[202:203]
	ds_read_b128 v[238:241], v57 offset:12672
	v_pk_fma_f32 v[250:251], v[242:243], v[94:95], v[250:251]
	v_pk_fma_f32 v[202:203], v[244:245], v[96:97], v[202:203]
	s_waitcnt lgkmcnt(5)
	v_pk_fma_f32 v[246:247], v[174:175], v[2:3], 0 op_sel_hi:[1,1,0]
	v_pk_fma_f32 v[248:249], v[176:177], v[4:5], 0 op_sel_hi:[1,1,0]
	ds_read_b128 v[242:245], v57 offset:12688
	v_mad_u32_u24 v61, v55, 46, v51
	ds_read_u16 v227, v61
	ds_read_b32 v226, v53 offset:184
	ds_read_b128 v[174:177], v57 offset:12784
	v_add_f32_e32 v250, v250, v251
	v_pk_fma_f32 v[246:247], v[178:179], v[6:7], v[246:247]
	v_pk_fma_f32 v[248:249], v[180:181], v[8:9], v[248:249]
	ds_read_b128 v[178:181], v57 offset:12800
	v_add_f32_e32 v202, v202, v203
	v_pk_fma_f32 v[246:247], v[182:183], v[10:11], v[246:247]
	v_pk_fma_f32 v[248:249], v[184:185], v[12:13], v[248:249]
	ds_read_b128 v[182:185], v57 offset:12816
	v_lshlrev_b32_e32 v221, 16, v221
	v_pk_fma_f32 v[246:247], v[186:187], v[14:15], v[246:247]
	v_pk_fma_f32 v[248:249], v[188:189], v[16:17], v[248:249]
	ds_read_b128 v[186:189], v57 offset:12832
	v_add_f32_e32 v250, v250, v202
	v_pk_fma_f32 v[246:247], v[190:191], v[18:19], v[246:247]
	v_pk_fma_f32 v[248:249], v[192:193], v[20:21], v[248:249]
	ds_read_b128 v[190:193], v57 offset:12848
	v_fma_f32 v95, v220, v221, -v250
	v_pk_fma_f32 v[246:247], v[194:195], v[22:23], v[246:247]
	v_pk_fma_f32 v[248:249], v[196:197], v[24:25], v[248:249]
	s_waitcnt lgkmcnt(5)
	v_pk_fma_f32 v[246:247], v[198:199], v[26:27], v[246:247]
	v_pk_fma_f32 v[248:249], v[200:201], v[28:29], v[248:249]
	ds_read_b128 v[194:197], v57 offset:12864
	ds_read_b128 v[198:201], v57 offset:12880
	v_pk_fma_f32 v[246:247], v[206:207], v[30:31], v[246:247]
	v_pk_fma_f32 v[248:249], v[208:209], v[32:33], v[248:249]
	ds_read_b128 v[206:209], v57 offset:12896
	v_pk_fma_f32 v[246:247], v[210:211], v[34:35], v[246:247]
	v_pk_fma_f32 v[248:249], v[212:213], v[36:37], v[248:249]
	ds_read_b128 v[210:213], v57 offset:12912
	v_pk_fma_f32 v[246:247], v[214:215], v[86:87], v[246:247]
	v_pk_fma_f32 v[248:249], v[216:217], v[88:89], v[248:249]
	ds_read_b128 v[214:217], v57 offset:12928
	v_pk_fma_f32 v[246:247], v[238:239], v[90:91], v[246:247]
	v_pk_fma_f32 v[248:249], v[240:241], v[92:93], v[248:249]
	ds_read_b128 v[238:241], v57 offset:12944
	v_pk_fma_f32 v[246:247], v[242:243], v[94:95], v[246:247]
	v_pk_fma_f32 v[248:249], v[244:245], v[96:97], v[248:249]
	ds_read_b128 v[242:245], v57 offset:12960
	s_waitcnt lgkmcnt(5)
	v_pk_fma_f32 v[250:251], v[174:175], v[2:3], 0 op_sel_hi:[1,1,0]
	v_pk_fma_f32 v[202:203], v[176:177], v[4:5], 0 op_sel_hi:[1,1,0]
	v_mad_u32_u24 v61, v55, 47, v51
	ds_read_u16 v59, v61
	ds_read_b32 v204, v53 offset:188
	ds_read_b128 v[174:177], v57 offset:13056
	v_add_f32_e32 v246, v246, v247
	v_pk_fma_f32 v[250:251], v[178:179], v[6:7], v[250:251]
	v_pk_fma_f32 v[202:203], v[180:181], v[8:9], v[202:203]
	ds_read_b128 v[178:181], v57 offset:13072
	v_add_f32_e32 v248, v248, v249
	v_pk_fma_f32 v[250:251], v[182:183], v[10:11], v[250:251]
	v_pk_fma_f32 v[202:203], v[184:185], v[12:13], v[202:203]
	ds_read_b128 v[182:185], v57 offset:13088
	v_lshlrev_b32_e32 v227, 16, v227
	v_pk_fma_f32 v[250:251], v[186:187], v[14:15], v[250:251]
	v_pk_fma_f32 v[202:203], v[188:189], v[16:17], v[202:203]
	ds_read_b128 v[186:189], v57 offset:13104
	v_add_f32_e32 v246, v246, v248
	v_pk_fma_f32 v[250:251], v[190:191], v[18:19], v[250:251]
	v_pk_fma_f32 v[202:203], v[192:193], v[20:21], v[202:203]
	ds_read_b128 v[190:193], v57 offset:13120
	v_fma_f32 v96, v226, v227, -v246
	v_pk_fma_f32 v[250:251], v[194:195], v[22:23], v[250:251]
	v_pk_fma_f32 v[202:203], v[196:197], v[24:25], v[202:203]
	ds_read_b128 v[194:197], v57 offset:13136
	v_pk_fma_f32 v[250:251], v[198:199], v[26:27], v[250:251]
	v_pk_fma_f32 v[202:203], v[200:201], v[28:29], v[202:203]
	s_waitcnt lgkmcnt(5)
	v_pk_fma_f32 v[250:251], v[206:207], v[30:31], v[250:251]
	v_pk_fma_f32 v[202:203], v[208:209], v[32:33], v[202:203]
	ds_read_b128 v[198:201], v57 offset:13152
	ds_read_b128 v[206:209], v57 offset:13168
	v_pk_fma_f32 v[250:251], v[210:211], v[34:35], v[250:251]
	v_pk_fma_f32 v[202:203], v[212:213], v[36:37], v[202:203]
	ds_read_b128 v[210:213], v57 offset:13184
	v_pk_fma_f32 v[250:251], v[214:215], v[86:87], v[250:251]
	v_pk_fma_f32 v[202:203], v[216:217], v[88:89], v[202:203]
	ds_read_b128 v[214:217], v57 offset:13200
	v_pk_fma_f32 v[250:251], v[238:239], v[90:91], v[250:251]
	v_pk_fma_f32 v[202:203], v[240:241], v[92:93], v[202:203]
	ds_read_b128 v[238:241], v57 offset:13216
	v_pk_fma_f32 v[250:251], v[242:243], v[94:95], v[250:251]
	v_pk_fma_f32 v[202:203], v[244:245], v[96:97], v[202:203]
	ds_read_b128 v[242:245], v57 offset:13232
	v_mad_u32_u24 v61, v55, 48, v51
	ds_read_u16 v221, v61
	ds_read_b32 v220, v53 offset:192
	v_pk_fma_f32 v[246:247], v[174:175], v[2:3], 0 op_sel_hi:[1,1,0]
	v_pk_fma_f32 v[248:249], v[176:177], v[4:5], 0 op_sel_hi:[1,1,0]
	v_add_f32_e32 v250, v250, v251
	s_waitcnt lgkmcnt(5)
	v_pk_fma_f32 v[246:247], v[178:179], v[6:7], v[246:247]
	v_pk_fma_f32 v[248:249], v[180:181], v[8:9], v[248:249]
	ds_read_b128 v[174:177], v57 offset:13328
	ds_read_b128 v[178:181], v57 offset:13344
	v_add_f32_e32 v202, v202, v203
	v_pk_fma_f32 v[246:247], v[182:183], v[10:11], v[246:247]
	v_pk_fma_f32 v[248:249], v[184:185], v[12:13], v[248:249]
	ds_read_b128 v[182:185], v57 offset:13360
	v_lshlrev_b32_e32 v59, 16, v59
	v_pk_fma_f32 v[246:247], v[186:187], v[14:15], v[246:247]
	v_pk_fma_f32 v[248:249], v[188:189], v[16:17], v[248:249]
	ds_read_b128 v[186:189], v57 offset:13376
	v_add_f32_e32 v250, v250, v202
	v_pk_fma_f32 v[246:247], v[190:191], v[18:19], v[246:247]
	v_pk_fma_f32 v[248:249], v[192:193], v[20:21], v[248:249]
	ds_read_b128 v[190:193], v57 offset:13392
	v_fma_f32 v97, v204, v59, -v250
	v_pk_fma_f32 v[246:247], v[194:195], v[22:23], v[246:247]
	v_pk_fma_f32 v[248:249], v[196:197], v[24:25], v[248:249]
	ds_read_b128 v[194:197], v57 offset:13408
	v_pk_fma_f32 v[246:247], v[198:199], v[26:27], v[246:247]
	v_pk_fma_f32 v[248:249], v[200:201], v[28:29], v[248:249]
	ds_read_b128 v[198:201], v57 offset:13424
	v_pk_fma_f32 v[246:247], v[206:207], v[30:31], v[246:247]
	v_pk_fma_f32 v[248:249], v[208:209], v[32:33], v[248:249]
	ds_read_b128 v[206:209], v57 offset:13440
	v_pk_fma_f32 v[246:247], v[210:211], v[34:35], v[246:247]
	v_pk_fma_f32 v[248:249], v[212:213], v[36:37], v[248:249]
	s_waitcnt lgkmcnt(5)
	v_pk_fma_f32 v[246:247], v[214:215], v[86:87], v[246:247]
	v_pk_fma_f32 v[248:249], v[216:217], v[88:89], v[248:249]
	ds_read_b128 v[210:213], v57 offset:13456
	ds_read_b128 v[214:217], v57 offset:13472
	v_pk_fma_f32 v[246:247], v[238:239], v[90:91], v[246:247]
	v_pk_fma_f32 v[248:249], v[240:241], v[92:93], v[248:249]
	ds_read_b128 v[238:241], v57 offset:13488
	v_pk_fma_f32 v[246:247], v[242:243], v[94:95], v[246:247]
	v_pk_fma_f32 v[248:249], v[244:245], v[96:97], v[248:249]
	ds_read_b128 v[242:245], v57 offset:13504
	v_pk_fma_f32 v[250:251], v[174:175], v[2:3], 0 op_sel_hi:[1,1,0]
	v_pk_fma_f32 v[202:203], v[176:177], v[4:5], 0 op_sel_hi:[1,1,0]
	ds_read_b128 v[174:177], v57 offset:13520
	v_mad_u32_u24 v61, v55, 49, v51
	ds_read_u16 v227, v61
	ds_read_b32 v226, v53 offset:196
	v_add_f32_e32 v246, v246, v247
	v_pk_fma_f32 v[250:251], v[178:179], v[6:7], v[250:251]
	v_pk_fma_f32 v[202:203], v[180:181], v[8:9], v[202:203]
	ds_read_b128 v[178:181], v57 offset:13600
	v_add_f32_e32 v248, v248, v249
	v_pk_fma_f32 v[250:251], v[182:183], v[10:11], v[250:251]
	v_pk_fma_f32 v[202:203], v[184:185], v[12:13], v[202:203]
	v_lshlrev_b32_e32 v221, 16, v221
	s_waitcnt lgkmcnt(5)
	v_pk_fma_f32 v[250:251], v[186:187], v[14:15], v[250:251]
	v_pk_fma_f32 v[202:203], v[188:189], v[16:17], v[202:203]
	ds_read_b128 v[182:185], v57 offset:13616
	ds_read_b128 v[186:189], v57 offset:13632
	v_add_f32_e32 v246, v246, v248
	v_pk_fma_f32 v[250:251], v[190:191], v[18:19], v[250:251]
	v_pk_fma_f32 v[202:203], v[192:193], v[20:21], v[202:203]
	ds_read_b128 v[190:193], v57 offset:13648
	v_fma_f32 v98, v220, v221, -v246
	v_pk_fma_f32 v[250:251], v[194:195], v[22:23], v[250:251]
	v_pk_fma_f32 v[202:203], v[196:197], v[24:25], v[202:203]
	ds_read_b128 v[194:197], v57 offset:13664
	v_pk_fma_f32 v[250:251], v[198:199], v[26:27], v[250:251]
	v_pk_fma_f32 v[202:203], v[200:201], v[28:29], v[202:203]
	ds_read_b128 v[198:201], v57 offset:13680
	v_pk_fma_f32 v[250:251], v[206:207], v[30:31], v[250:251]
	v_pk_fma_f32 v[202:203], v[208:209], v[32:33], v[202:203]
	ds_read_b128 v[206:209], v57 offset:13696
	v_pk_fma_f32 v[250:251], v[210:211], v[34:35], v[250:251]
	v_pk_fma_f32 v[202:203], v[212:213], v[36:37], v[202:203]
	ds_read_b128 v[210:213], v57 offset:13712
	v_pk_fma_f32 v[250:251], v[214:215], v[86:87], v[250:251]
	v_pk_fma_f32 v[202:203], v[216:217], v[88:89], v[202:203]
	ds_read_b128 v[214:217], v57 offset:13728
	v_pk_fma_f32 v[250:251], v[238:239], v[90:91], v[250:251]
	v_pk_fma_f32 v[202:203], v[240:241], v[92:93], v[202:203]
	s_waitcnt lgkmcnt(5)
	v_pk_fma_f32 v[250:251], v[242:243], v[94:95], v[250:251]
	v_pk_fma_f32 v[202:203], v[244:245], v[96:97], v[202:203]
	ds_read_b128 v[238:241], v57 offset:13744
	ds_read_b128 v[242:245], v57 offset:13760
	v_pk_fma_f32 v[250:251], v[174:175], v[98:99], v[250:251]
	v_pk_fma_f32 v[202:203], v[176:177], v[100:101], v[202:203]
	ds_read_b128 v[174:177], v57 offset:13776
	v_pk_fma_f32 v[246:247], v[178:179], v[2:3], 0 op_sel_hi:[1,1,0]
	v_pk_fma_f32 v[248:249], v[180:181], v[4:5], 0 op_sel_hi:[1,1,0]
	ds_read_b128 v[178:181], v57 offset:13792
	v_mad_u32_u24 v61, v55, 50, v51
	ds_read_u16 v59, v61
	ds_read_b32 v204, v53 offset:200
	v_add_f32_e32 v250, v250, v251
	v_pk_fma_f32 v[246:247], v[182:183], v[6:7], v[246:247]
	v_pk_fma_f32 v[248:249], v[184:185], v[8:9], v[248:249]
	ds_read_b128 v[182:185], v57 offset:13872
	v_add_f32_e32 v202, v202, v203
	v_pk_fma_f32 v[246:247], v[186:187], v[10:11], v[246:247]
	v_pk_fma_f32 v[248:249], v[188:189], v[12:13], v[248:249]
	ds_read_b128 v[186:189], v57 offset:13888
	v_lshlrev_b32_e32 v227, 16, v227
	v_pk_fma_f32 v[246:247], v[190:191], v[14:15], v[246:247]
	v_pk_fma_f32 v[248:249], v[192:193], v[16:17], v[248:249]
	v_add_f32_e32 v250, v250, v202
	s_waitcnt lgkmcnt(5)
	v_pk_fma_f32 v[246:247], v[194:195], v[18:19], v[246:247]
	v_pk_fma_f32 v[248:249], v[196:197], v[20:21], v[248:249]
	ds_read_b128 v[190:193], v57 offset:13904
	ds_read_b128 v[194:197], v57 offset:13920
	v_fma_f32 v99, v226, v227, -v250
	v_pk_fma_f32 v[246:247], v[198:199], v[22:23], v[246:247]
	v_pk_fma_f32 v[248:249], v[200:201], v[24:25], v[248:249]
	ds_read_b128 v[198:201], v57 offset:13936
	v_pk_fma_f32 v[246:247], v[206:207], v[26:27], v[246:247]
	v_pk_fma_f32 v[248:249], v[208:209], v[28:29], v[248:249]
	ds_read_b128 v[206:209], v57 offset:13952
	v_pk_fma_f32 v[246:247], v[210:211], v[30:31], v[246:247]
	v_pk_fma_f32 v[248:249], v[212:213], v[32:33], v[248:249]
	ds_read_b128 v[210:213], v57 offset:13968
	v_pk_fma_f32 v[246:247], v[214:215], v[34:35], v[246:247]
	v_pk_fma_f32 v[248:249], v[216:217], v[36:37], v[248:249]
	ds_read_b128 v[214:217], v57 offset:13984
	v_pk_fma_f32 v[246:247], v[238:239], v[86:87], v[246:247]
	v_pk_fma_f32 v[248:249], v[240:241], v[88:89], v[248:249]
	ds_read_b128 v[238:241], v57 offset:14000
	v_pk_fma_f32 v[246:247], v[242:243], v[90:91], v[246:247]
	v_pk_fma_f32 v[248:249], v[244:245], v[92:93], v[248:249]
	ds_read_b128 v[242:245], v57 offset:14016
	v_pk_fma_f32 v[246:247], v[174:175], v[94:95], v[246:247]
	v_pk_fma_f32 v[248:249], v[176:177], v[96:97], v[248:249]
	s_waitcnt lgkmcnt(5)
	v_pk_fma_f32 v[246:247], v[178:179], v[98:99], v[246:247]
	v_pk_fma_f32 v[248:249], v[180:181], v[100:101], v[248:249]
	ds_read_b128 v[174:177], v57 offset:14032
	ds_read_b128 v[178:181], v57 offset:14048
	v_pk_fma_f32 v[250:251], v[182:183], v[2:3], 0 op_sel_hi:[1,1,0]
	v_pk_fma_f32 v[202:203], v[184:185], v[4:5], 0 op_sel_hi:[1,1,0]
	ds_read_b128 v[182:185], v57 offset:14064
	v_mad_u32_u24 v61, v55, 51, v51
	ds_read_u16 v221, v61
	ds_read_b32 v220, v53 offset:204
	v_add_f32_e32 v246, v246, v247
	v_pk_fma_f32 v[250:251], v[186:187], v[6:7], v[250:251]
	v_pk_fma_f32 v[202:203], v[188:189], v[8:9], v[202:203]
	ds_read_b128 v[186:189], v57 offset:14144
	v_add_f32_e32 v248, v248, v249
	v_pk_fma_f32 v[250:251], v[190:191], v[10:11], v[250:251]
	v_pk_fma_f32 v[202:203], v[192:193], v[12:13], v[202:203]
	ds_read_b128 v[190:193], v57 offset:14160
	v_lshlrev_b32_e32 v59, 16, v59
	v_pk_fma_f32 v[250:251], v[194:195], v[14:15], v[250:251]
	v_pk_fma_f32 v[202:203], v[196:197], v[16:17], v[202:203]
	ds_read_b128 v[194:197], v57 offset:14176
	v_add_f32_e32 v246, v246, v248
	v_pk_fma_f32 v[250:251], v[198:199], v[18:19], v[250:251]
	v_pk_fma_f32 v[202:203], v[200:201], v[20:21], v[202:203]
	v_fma_f32 v100, v204, v59, -v246
	s_waitcnt lgkmcnt(5)
	v_pk_fma_f32 v[250:251], v[206:207], v[22:23], v[250:251]
	v_pk_fma_f32 v[202:203], v[208:209], v[24:25], v[202:203]
	ds_read_b128 v[198:201], v57 offset:14192
	ds_read_b128 v[206:209], v57 offset:14208
	v_pk_fma_f32 v[250:251], v[210:211], v[26:27], v[250:251]
	v_pk_fma_f32 v[202:203], v[212:213], v[28:29], v[202:203]
	ds_read_b128 v[210:213], v57 offset:14224
	v_pk_fma_f32 v[250:251], v[214:215], v[30:31], v[250:251]
	v_pk_fma_f32 v[202:203], v[216:217], v[32:33], v[202:203]
	ds_read_b128 v[214:217], v57 offset:14240
	v_pk_fma_f32 v[250:251], v[238:239], v[34:35], v[250:251]
	v_pk_fma_f32 v[202:203], v[240:241], v[36:37], v[202:203]
	ds_read_b128 v[238:241], v57 offset:14256
	v_pk_fma_f32 v[250:251], v[242:243], v[86:87], v[250:251]
	v_pk_fma_f32 v[202:203], v[244:245], v[88:89], v[202:203]
	ds_read_b128 v[242:245], v57 offset:14272
	v_pk_fma_f32 v[250:251], v[174:175], v[90:91], v[250:251]
	v_pk_fma_f32 v[202:203], v[176:177], v[92:93], v[202:203]
	ds_read_b128 v[174:177], v57 offset:14288
	v_pk_fma_f32 v[250:251], v[178:179], v[94:95], v[250:251]
	v_pk_fma_f32 v[202:203], v[180:181], v[96:97], v[202:203]
	ds_read_b128 v[178:181], v57 offset:14304
	v_pk_fma_f32 v[250:251], v[182:183], v[98:99], v[250:251]
	v_pk_fma_f32 v[202:203], v[184:185], v[100:101], v[202:203]
	s_waitcnt lgkmcnt(5)
	v_pk_fma_f32 v[246:247], v[186:187], v[2:3], 0 op_sel_hi:[1,1,0]
	v_pk_fma_f32 v[248:249], v[188:189], v[4:5], 0 op_sel_hi:[1,1,0]
	ds_read_b128 v[182:185], v57 offset:14320
	ds_read_b128 v[186:189], v57 offset:14336
	v_mad_u32_u24 v61, v55, 52, v51
	ds_read_u16 v227, v61
	ds_read_b32 v226, v53 offset:208
	v_add_f32_e32 v250, v250, v251
	v_pk_fma_f32 v[246:247], v[190:191], v[6:7], v[246:247]
	v_pk_fma_f32 v[248:249], v[192:193], v[8:9], v[248:249]
	ds_read_b128 v[190:193], v57 offset:14416
	v_add_f32_e32 v202, v202, v203
	v_pk_fma_f32 v[246:247], v[194:195], v[10:11], v[246:247]
	v_pk_fma_f32 v[248:249], v[196:197], v[12:13], v[248:249]
	ds_read_b128 v[194:197], v57 offset:14432
	v_lshlrev_b32_e32 v221, 16, v221
	v_pk_fma_f32 v[246:247], v[198:199], v[14:15], v[246:247]
	v_pk_fma_f32 v[248:249], v[200:201], v[16:17], v[248:249]
	ds_read_b128 v[198:201], v57 offset:14448
	v_add_f32_e32 v250, v250, v202
	v_pk_fma_f32 v[246:247], v[206:207], v[18:19], v[246:247]
	v_pk_fma_f32 v[248:249], v[208:209], v[20:21], v[248:249]
	ds_read_b128 v[206:209], v57 offset:14464
	v_fma_f32 v101, v220, v221, -v250
	v_pk_fma_f32 v[246:247], v[210:211], v[22:23], v[246:247]
	v_pk_fma_f32 v[248:249], v[212:213], v[24:25], v[248:249]
	s_waitcnt lgkmcnt(5)
	v_pk_fma_f32 v[246:247], v[214:215], v[26:27], v[246:247]
	v_pk_fma_f32 v[248:249], v[216:217], v[28:29], v[248:249]
	ds_read_b128 v[210:213], v57 offset:14480
	ds_read_b128 v[214:217], v57 offset:14496
	v_pk_fma_f32 v[246:247], v[238:239], v[30:31], v[246:247]
	v_pk_fma_f32 v[248:249], v[240:241], v[32:33], v[248:249]
	ds_read_b128 v[238:241], v57 offset:14512
	v_pk_fma_f32 v[246:247], v[242:243], v[34:35], v[246:247]
	v_pk_fma_f32 v[248:249], v[244:245], v[36:37], v[248:249]
	ds_read_b128 v[242:245], v57 offset:14528
	v_pk_fma_f32 v[246:247], v[174:175], v[86:87], v[246:247]
	v_pk_fma_f32 v[248:249], v[176:177], v[88:89], v[248:249]
	ds_read_b128 v[174:177], v57 offset:14544
	v_pk_fma_f32 v[246:247], v[178:179], v[90:91], v[246:247]
	v_pk_fma_f32 v[248:249], v[180:181], v[92:93], v[248:249]
	ds_read_b128 v[178:181], v57 offset:14560
	v_pk_fma_f32 v[246:247], v[182:183], v[94:95], v[246:247]
	v_pk_fma_f32 v[248:249], v[184:185], v[96:97], v[248:249]
	ds_read_b128 v[182:185], v57 offset:14576
	v_pk_fma_f32 v[246:247], v[186:187], v[98:99], v[246:247]
	v_pk_fma_f32 v[248:249], v[188:189], v[100:101], v[248:249]
	ds_read_b128 v[186:189], v57 offset:14592
	s_waitcnt lgkmcnt(5)
	v_pk_fma_f32 v[250:251], v[190:191], v[2:3], 0 op_sel_hi:[1,1,0]
	v_pk_fma_f32 v[202:203], v[192:193], v[4:5], 0 op_sel_hi:[1,1,0]
	ds_read_b128 v[190:193], v57 offset:14608
	v_add_f32_e32 v246, v246, v247
	v_pk_fma_f32 v[250:251], v[194:195], v[6:7], v[250:251]
	v_pk_fma_f32 v[202:203], v[196:197], v[8:9], v[202:203]
	ds_read_b128 v[194:197], v57 offset:14624
	v_mad_u32_u24 v61, v55, 53, v51
	ds_read_u16 v59, v61
	ds_read_b32 v204, v53 offset:212
	v_add_f32_e32 v248, v248, v249
	v_pk_fma_f32 v[250:251], v[198:199], v[10:11], v[250:251]
	v_pk_fma_f32 v[202:203], v[200:201], v[12:13], v[202:203]
	ds_read_b128 v[198:201], v57 offset:14688
	v_lshlrev_b32_e32 v227, 16, v227
	v_pk_fma_f32 v[250:251], v[206:207], v[14:15], v[250:251]
	v_pk_fma_f32 v[202:203], v[208:209], v[16:17], v[202:203]
	ds_read_b128 v[206:209], v57 offset:14704
	v_add_f32_e32 v246, v246, v248
	v_pk_fma_f32 v[250:251], v[210:211], v[18:19], v[250:251]
	v_pk_fma_f32 v[202:203], v[212:213], v[20:21], v[202:203]
	ds_read_b128 v[210:213], v57 offset:14720
	v_fma_f32 v102, v226, v227, -v246
	v_pk_fma_f32 v[250:251], v[214:215], v[22:23], v[250:251]
	v_pk_fma_f32 v[202:203], v[216:217], v[24:25], v[202:203]
	ds_read_b128 v[214:217], v57 offset:14736
	v_pk_fma_f32 v[250:251], v[238:239], v[26:27], v[250:251]
	v_pk_fma_f32 v[202:203], v[240:241], v[28:29], v[202:203]
	s_waitcnt lgkmcnt(5)
	v_pk_fma_f32 v[250:251], v[242:243], v[30:31], v[250:251]
	v_pk_fma_f32 v[202:203], v[244:245], v[32:33], v[202:203]
	ds_read_b128 v[238:241], v57 offset:14752
	ds_read_b128 v[242:245], v57 offset:14768
	v_pk_fma_f32 v[250:251], v[174:175], v[34:35], v[250:251]
	v_pk_fma_f32 v[202:203], v[176:177], v[36:37], v[202:203]
	ds_read_b128 v[174:177], v57 offset:14784
	v_pk_fma_f32 v[250:251], v[178:179], v[86:87], v[250:251]
	v_pk_fma_f32 v[202:203], v[180:181], v[88:89], v[202:203]
	ds_read_b128 v[178:181], v57 offset:14800
	v_pk_fma_f32 v[250:251], v[182:183], v[90:91], v[250:251]
	v_pk_fma_f32 v[202:203], v[184:185], v[92:93], v[202:203]
	ds_read_b128 v[182:185], v57 offset:14816
	v_pk_fma_f32 v[250:251], v[186:187], v[94:95], v[250:251]
	v_pk_fma_f32 v[202:203], v[188:189], v[96:97], v[202:203]
	ds_read_b128 v[186:189], v57 offset:14832
	v_pk_fma_f32 v[250:251], v[190:191], v[98:99], v[250:251]
	v_pk_fma_f32 v[202:203], v[192:193], v[100:101], v[202:203]
	ds_read_b128 v[190:193], v57 offset:14848
	v_pk_fma_f32 v[250:251], v[194:195], v[102:103], v[250:251]
	v_pk_fma_f32 v[202:203], v[196:197], v[104:105], v[202:203]
	ds_read_b128 v[194:197], v57 offset:14864
	s_waitcnt lgkmcnt(5)
	v_pk_fma_f32 v[246:247], v[198:199], v[2:3], 0 op_sel_hi:[1,1,0]
	v_pk_fma_f32 v[248:249], v[200:201], v[4:5], 0 op_sel_hi:[1,1,0]
	ds_read_b128 v[198:201], v57 offset:14880
	v_add_f32_e32 v250, v250, v251
	v_pk_fma_f32 v[246:247], v[206:207], v[6:7], v[246:247]
	v_pk_fma_f32 v[248:249], v[208:209], v[8:9], v[248:249]
	ds_read_b128 v[206:209], v57 offset:14896
	v_mad_u32_u24 v61, v55, 54, v51
	ds_read_u16 v221, v61
	ds_read_b32 v220, v53 offset:216
	v_add_f32_e32 v202, v202, v203
	v_pk_fma_f32 v[246:247], v[210:211], v[10:11], v[246:247]
	v_pk_fma_f32 v[248:249], v[212:213], v[12:13], v[248:249]
	ds_read_b128 v[210:213], v57 offset:14960
	v_lshlrev_b32_e32 v59, 16, v59
	v_pk_fma_f32 v[246:247], v[214:215], v[14:15], v[246:247]
	v_pk_fma_f32 v[248:249], v[216:217], v[16:17], v[248:249]
	ds_read_b128 v[214:217], v57 offset:14976
	v_add_f32_e32 v250, v250, v202
	v_pk_fma_f32 v[246:247], v[238:239], v[18:19], v[246:247]
	v_pk_fma_f32 v[248:249], v[240:241], v[20:21], v[248:249]
	ds_read_b128 v[238:241], v57 offset:14992
	v_fma_f32 v103, v204, v59, -v250
	v_pk_fma_f32 v[246:247], v[242:243], v[22:23], v[246:247]
	v_pk_fma_f32 v[248:249], v[244:245], v[24:25], v[248:249]
	ds_read_b128 v[242:245], v57 offset:15008
	v_pk_fma_f32 v[246:247], v[174:175], v[26:27], v[246:247]
	v_pk_fma_f32 v[248:249], v[176:177], v[28:29], v[248:249]
	s_waitcnt lgkmcnt(5)
	v_pk_fma_f32 v[246:247], v[178:179], v[30:31], v[246:247]
	v_pk_fma_f32 v[248:249], v[180:181], v[32:33], v[248:249]
	ds_read_b128 v[174:177], v57 offset:15024
	ds_read_b128 v[178:181], v57 offset:15040
	v_pk_fma_f32 v[246:247], v[182:183], v[34:35], v[246:247]
	v_pk_fma_f32 v[248:249], v[184:185], v[36:37], v[248:249]
	ds_read_b128 v[182:185], v57 offset:15056
	v_pk_fma_f32 v[246:247], v[186:187], v[86:87], v[246:247]
	v_pk_fma_f32 v[248:249], v[188:189], v[88:89], v[248:249]
	ds_read_b128 v[186:189], v57 offset:15072
	v_pk_fma_f32 v[246:247], v[190:191], v[90:91], v[246:247]
	v_pk_fma_f32 v[248:249], v[192:193], v[92:93], v[248:249]
	ds_read_b128 v[190:193], v57 offset:15088
	v_pk_fma_f32 v[246:247], v[194:195], v[94:95], v[246:247]
	v_pk_fma_f32 v[248:249], v[196:197], v[96:97], v[248:249]
	ds_read_b128 v[194:197], v57 offset:15104
	v_pk_fma_f32 v[246:247], v[198:199], v[98:99], v[246:247]
	v_pk_fma_f32 v[248:249], v[200:201], v[100:101], v[248:249]
	ds_read_b128 v[198:201], v57 offset:15120
	v_pk_fma_f32 v[246:247], v[206:207], v[102:103], v[246:247]
	v_pk_fma_f32 v[248:249], v[208:209], v[104:105], v[248:249]
	ds_read_b128 v[206:209], v57 offset:15136
	s_waitcnt lgkmcnt(5)
	v_pk_fma_f32 v[250:251], v[210:211], v[2:3], 0 op_sel_hi:[1,1,0]
	v_pk_fma_f32 v[202:203], v[212:213], v[4:5], 0 op_sel_hi:[1,1,0]
	ds_read_b128 v[210:213], v57 offset:15152
	v_add_f32_e32 v246, v246, v247
	v_pk_fma_f32 v[250:251], v[214:215], v[6:7], v[250:251]
	v_pk_fma_f32 v[202:203], v[216:217], v[8:9], v[202:203]
	ds_read_b128 v[214:217], v57 offset:15168
	v_mad_u32_u24 v61, v55, 55, v51
	ds_read_u16 v227, v61
	ds_read_b32 v226, v53 offset:220
	v_add_f32_e32 v248, v248, v249
	v_pk_fma_f32 v[250:251], v[238:239], v[10:11], v[250:251]
	v_pk_fma_f32 v[202:203], v[240:241], v[12:13], v[202:203]
	ds_read_b128 v[238:241], v57 offset:15232
	v_lshlrev_b32_e32 v221, 16, v221
	v_pk_fma_f32 v[250:251], v[242:243], v[14:15], v[250:251]
	v_pk_fma_f32 v[202:203], v[244:245], v[16:17], v[202:203]
	ds_read_b128 v[242:245], v57 offset:15248
	v_add_f32_e32 v246, v246, v248
	v_pk_fma_f32 v[250:251], v[174:175], v[18:19], v[250:251]
	v_pk_fma_f32 v[202:203], v[176:177], v[20:21], v[202:203]
	ds_read_b128 v[174:177], v57 offset:15264
	v_fma_f32 v104, v220, v221, -v246
	v_pk_fma_f32 v[250:251], v[178:179], v[22:23], v[250:251]
	v_pk_fma_f32 v[202:203], v[180:181], v[24:25], v[202:203]
	ds_read_b128 v[178:181], v57 offset:15280
	v_pk_fma_f32 v[250:251], v[182:183], v[26:27], v[250:251]
	v_pk_fma_f32 v[202:203], v[184:185], v[28:29], v[202:203]
	s_waitcnt lgkmcnt(5)
	v_pk_fma_f32 v[250:251], v[186:187], v[30:31], v[250:251]
	v_pk_fma_f32 v[202:203], v[188:189], v[32:33], v[202:203]
	ds_read_b128 v[182:185], v57 offset:15296
	ds_read_b128 v[186:189], v57 offset:15312
	v_pk_fma_f32 v[250:251], v[190:191], v[34:35], v[250:251]
	v_pk_fma_f32 v[202:203], v[192:193], v[36:37], v[202:203]
	ds_read_b128 v[190:193], v57 offset:15328
	v_pk_fma_f32 v[250:251], v[194:195], v[86:87], v[250:251]
	v_pk_fma_f32 v[202:203], v[196:197], v[88:89], v[202:203]
	ds_read_b128 v[194:197], v57 offset:15344
	v_pk_fma_f32 v[250:251], v[198:199], v[90:91], v[250:251]
	v_pk_fma_f32 v[202:203], v[200:201], v[92:93], v[202:203]
	ds_read_b128 v[198:201], v57 offset:15360
	v_pk_fma_f32 v[250:251], v[206:207], v[94:95], v[250:251]
	v_pk_fma_f32 v[202:203], v[208:209], v[96:97], v[202:203]
	ds_read_b128 v[206:209], v57 offset:15376
	v_pk_fma_f32 v[250:251], v[210:211], v[98:99], v[250:251]
	v_pk_fma_f32 v[202:203], v[212:213], v[100:101], v[202:203]
	ds_read_b128 v[210:213], v57 offset:15392
	v_pk_fma_f32 v[250:251], v[214:215], v[102:103], v[250:251]
	v_pk_fma_f32 v[202:203], v[216:217], v[104:105], v[202:203]
	ds_read_b128 v[214:217], v57 offset:15408
	s_waitcnt lgkmcnt(5)
	v_pk_fma_f32 v[246:247], v[238:239], v[2:3], 0 op_sel_hi:[1,1,0]
	v_pk_fma_f32 v[248:249], v[240:241], v[4:5], 0 op_sel_hi:[1,1,0]
	ds_read_b128 v[238:241], v57 offset:15424
	v_add_f32_e32 v250, v250, v251
	v_pk_fma_f32 v[246:247], v[242:243], v[6:7], v[246:247]
	v_pk_fma_f32 v[248:249], v[244:245], v[8:9], v[248:249]
	ds_read_b128 v[242:245], v57 offset:15440
	v_mad_u32_u24 v61, v55, 56, v51
	ds_read_u16 v59, v61
	ds_read_b32 v204, v53 offset:224
	v_add_f32_e32 v202, v202, v203
	v_pk_fma_f32 v[246:247], v[174:175], v[10:11], v[246:247]
	v_pk_fma_f32 v[248:249], v[176:177], v[12:13], v[248:249]
	ds_read_b128 v[174:177], v57 offset:15504
	v_lshlrev_b32_e32 v227, 16, v227
	v_pk_fma_f32 v[246:247], v[178:179], v[14:15], v[246:247]
	v_pk_fma_f32 v[248:249], v[180:181], v[16:17], v[248:249]
	ds_read_b128 v[178:181], v57 offset:15520
	v_add_f32_e32 v250, v250, v202
	v_pk_fma_f32 v[246:247], v[182:183], v[18:19], v[246:247]
	v_pk_fma_f32 v[248:249], v[184:185], v[20:21], v[248:249]
	ds_read_b128 v[182:185], v57 offset:15536
	v_fma_f32 v105, v226, v227, -v250
	v_pk_fma_f32 v[246:247], v[186:187], v[22:23], v[246:247]
	v_pk_fma_f32 v[248:249], v[188:189], v[24:25], v[248:249]
	ds_read_b128 v[186:189], v57 offset:15552
	v_pk_fma_f32 v[246:247], v[190:191], v[26:27], v[246:247]
	v_pk_fma_f32 v[248:249], v[192:193], v[28:29], v[248:249]
	s_waitcnt lgkmcnt(5)
	v_pk_fma_f32 v[246:247], v[194:195], v[30:31], v[246:247]
	v_pk_fma_f32 v[248:249], v[196:197], v[32:33], v[248:249]
	ds_read_b128 v[190:193], v57 offset:15568
	ds_read_b128 v[194:197], v57 offset:15584
	v_pk_fma_f32 v[246:247], v[198:199], v[34:35], v[246:247]
	v_pk_fma_f32 v[248:249], v[200:201], v[36:37], v[248:249]
	ds_read_b128 v[198:201], v57 offset:15600
	v_pk_fma_f32 v[246:247], v[206:207], v[86:87], v[246:247]
	v_pk_fma_f32 v[248:249], v[208:209], v[88:89], v[248:249]
	ds_read_b128 v[206:209], v57 offset:15616
	v_pk_fma_f32 v[246:247], v[210:211], v[90:91], v[246:247]
	v_pk_fma_f32 v[248:249], v[212:213], v[92:93], v[248:249]
	ds_read_b128 v[210:213], v57 offset:15632
	v_pk_fma_f32 v[246:247], v[214:215], v[94:95], v[246:247]
	v_pk_fma_f32 v[248:249], v[216:217], v[96:97], v[248:249]
	ds_read_b128 v[214:217], v57 offset:15648
	v_pk_fma_f32 v[246:247], v[238:239], v[98:99], v[246:247]
	v_pk_fma_f32 v[248:249], v[240:241], v[100:101], v[248:249]
	ds_read_b128 v[238:241], v57 offset:15664
	v_pk_fma_f32 v[246:247], v[242:243], v[102:103], v[246:247]
	v_pk_fma_f32 v[248:249], v[244:245], v[104:105], v[248:249]
	ds_read_b128 v[242:245], v57 offset:15680
	s_waitcnt lgkmcnt(5)
	v_pk_fma_f32 v[250:251], v[174:175], v[2:3], 0 op_sel_hi:[1,1,0]
	v_pk_fma_f32 v[202:203], v[176:177], v[4:5], 0 op_sel_hi:[1,1,0]
	ds_read_b128 v[174:177], v57 offset:15696
	v_add_f32_e32 v246, v246, v247
	v_pk_fma_f32 v[250:251], v[178:179], v[6:7], v[250:251]
	v_pk_fma_f32 v[202:203], v[180:181], v[8:9], v[202:203]
	ds_read_b128 v[178:181], v57 offset:15712
	v_add_f32_e32 v248, v248, v249
	v_pk_fma_f32 v[250:251], v[182:183], v[10:11], v[250:251]
	v_pk_fma_f32 v[202:203], v[184:185], v[12:13], v[202:203]
	ds_read_b128 v[182:185], v57 offset:15728
	v_mad_u32_u24 v61, v55, 57, v51
	ds_read_u16 v221, v61
	ds_read_b32 v220, v53 offset:228
	v_lshlrev_b32_e32 v59, 16, v59
	v_pk_fma_f32 v[250:251], v[186:187], v[14:15], v[250:251]
	v_pk_fma_f32 v[202:203], v[188:189], v[16:17], v[202:203]
	ds_read_b128 v[186:189], v57 offset:15776
	v_add_f32_e32 v246, v246, v248
	v_pk_fma_f32 v[250:251], v[190:191], v[18:19], v[250:251]
	v_pk_fma_f32 v[202:203], v[192:193], v[20:21], v[202:203]
	ds_read_b128 v[190:193], v57 offset:15792
	v_fma_f32 v106, v204, v59, -v246
	v_pk_fma_f32 v[250:251], v[194:195], v[22:23], v[250:251]
	v_pk_fma_f32 v[202:203], v[196:197], v[24:25], v[202:203]
	ds_read_b128 v[194:197], v57 offset:15808
	v_pk_fma_f32 v[250:251], v[198:199], v[26:27], v[250:251]
	v_pk_fma_f32 v[202:203], v[200:201], v[28:29], v[202:203]
	s_waitcnt lgkmcnt(5)
	v_pk_fma_f32 v[250:251], v[206:207], v[30:31], v[250:251]
	v_pk_fma_f32 v[202:203], v[208:209], v[32:33], v[202:203]
	ds_read_b128 v[198:201], v57 offset:15824
	ds_read_b128 v[206:209], v57 offset:15840
	v_pk_fma_f32 v[250:251], v[210:211], v[34:35], v[250:251]
	v_pk_fma_f32 v[202:203], v[212:213], v[36:37], v[202:203]
	ds_read_b128 v[210:213], v57 offset:15856
	v_pk_fma_f32 v[250:251], v[214:215], v[86:87], v[250:251]
	v_pk_fma_f32 v[202:203], v[216:217], v[88:89], v[202:203]
	ds_read_b128 v[214:217], v57 offset:15872
	v_pk_fma_f32 v[250:251], v[238:239], v[90:91], v[250:251]
	v_pk_fma_f32 v[202:203], v[240:241], v[92:93], v[202:203]
	ds_read_b128 v[238:241], v57 offset:15888
	v_pk_fma_f32 v[250:251], v[242:243], v[94:95], v[250:251]
	v_pk_fma_f32 v[202:203], v[244:245], v[96:97], v[202:203]
	ds_read_b128 v[242:245], v57 offset:15904
	v_pk_fma_f32 v[250:251], v[174:175], v[98:99], v[250:251]
	v_pk_fma_f32 v[202:203], v[176:177], v[100:101], v[202:203]
	ds_read_b128 v[174:177], v57 offset:15920
	v_pk_fma_f32 v[250:251], v[178:179], v[102:103], v[250:251]
	v_pk_fma_f32 v[202:203], v[180:181], v[104:105], v[202:203]
	ds_read_b128 v[178:181], v57 offset:15936
	v_pk_fma_f32 v[250:251], v[182:183], v[106:107], v[250:251]
	v_pk_fma_f32 v[202:203], v[184:185], v[108:109], v[202:203]
	s_waitcnt lgkmcnt(5)
	v_pk_fma_f32 v[246:247], v[186:187], v[2:3], 0 op_sel_hi:[1,1,0]
	v_pk_fma_f32 v[248:249], v[188:189], v[4:5], 0 op_sel_hi:[1,1,0]
	ds_read_b128 v[182:185], v57 offset:15952
	ds_read_b128 v[186:189], v57 offset:15968
	v_add_f32_e32 v250, v250, v251
	v_pk_fma_f32 v[246:247], v[190:191], v[6:7], v[246:247]
	v_pk_fma_f32 v[248:249], v[192:193], v[8:9], v[248:249]
	ds_read_b128 v[190:193], v57 offset:15984
	v_add_f32_e32 v202, v202, v203
	v_pk_fma_f32 v[246:247], v[194:195], v[10:11], v[246:247]
	v_pk_fma_f32 v[248:249], v[196:197], v[12:13], v[248:249]
	ds_read_b128 v[194:197], v57 offset:16000
	v_mad_u32_u24 v61, v55, 58, v51
	ds_read_u16 v227, v61
	ds_read_b32 v226, v53 offset:232
	v_lshlrev_b32_e32 v221, 16, v221
	v_pk_fma_f32 v[246:247], v[198:199], v[14:15], v[246:247]
	v_pk_fma_f32 v[248:249], v[200:201], v[16:17], v[248:249]
	ds_read_b128 v[198:201], v57 offset:16048
	v_add_f32_e32 v250, v250, v202
	v_pk_fma_f32 v[246:247], v[206:207], v[18:19], v[246:247]
	v_pk_fma_f32 v[248:249], v[208:209], v[20:21], v[248:249]
	ds_read_b128 v[206:209], v57 offset:16064
	v_fma_f32 v107, v220, v221, -v250
	v_pk_fma_f32 v[246:247], v[210:211], v[22:23], v[246:247]
	v_pk_fma_f32 v[248:249], v[212:213], v[24:25], v[248:249]
	s_waitcnt lgkmcnt(5)
	v_pk_fma_f32 v[246:247], v[214:215], v[26:27], v[246:247]
	v_pk_fma_f32 v[248:249], v[216:217], v[28:29], v[248:249]
	ds_read_b128 v[210:213], v57 offset:16080
	ds_read_b128 v[214:217], v57 offset:16096
	v_pk_fma_f32 v[246:247], v[238:239], v[30:31], v[246:247]
	v_pk_fma_f32 v[248:249], v[240:241], v[32:33], v[248:249]
	ds_read_b128 v[238:241], v57 offset:16112
	v_pk_fma_f32 v[246:247], v[242:243], v[34:35], v[246:247]
	v_pk_fma_f32 v[248:249], v[244:245], v[36:37], v[248:249]
	ds_read_b128 v[242:245], v57 offset:16128
	v_pk_fma_f32 v[246:247], v[174:175], v[86:87], v[246:247]
	v_pk_fma_f32 v[248:249], v[176:177], v[88:89], v[248:249]
	ds_read_b128 v[174:177], v57 offset:16144
	v_pk_fma_f32 v[246:247], v[178:179], v[90:91], v[246:247]
	v_pk_fma_f32 v[248:249], v[180:181], v[92:93], v[248:249]
	ds_read_b128 v[178:181], v57 offset:16160
	v_pk_fma_f32 v[246:247], v[182:183], v[94:95], v[246:247]
	v_pk_fma_f32 v[248:249], v[184:185], v[96:97], v[248:249]
	ds_read_b128 v[182:185], v57 offset:16176
	v_pk_fma_f32 v[246:247], v[186:187], v[98:99], v[246:247]
	v_pk_fma_f32 v[248:249], v[188:189], v[100:101], v[248:249]
	ds_read_b128 v[186:189], v57 offset:16192
	v_pk_fma_f32 v[246:247], v[190:191], v[102:103], v[246:247]
	v_pk_fma_f32 v[248:249], v[192:193], v[104:105], v[248:249]
	s_waitcnt lgkmcnt(5)
	v_pk_fma_f32 v[246:247], v[194:195], v[106:107], v[246:247]
	v_pk_fma_f32 v[248:249], v[196:197], v[108:109], v[248:249]
	ds_read_b128 v[190:193], v57 offset:16208
	ds_read_b128 v[194:197], v57 offset:16224
	v_pk_fma_f32 v[250:251], v[198:199], v[2:3], 0 op_sel_hi:[1,1,0]
	v_pk_fma_f32 v[202:203], v[200:201], v[4:5], 0 op_sel_hi:[1,1,0]
	ds_read_b128 v[198:201], v57 offset:16240
	v_add_f32_e32 v246, v246, v247
	v_pk_fma_f32 v[250:251], v[206:207], v[6:7], v[250:251]
	v_pk_fma_f32 v[202:203], v[208:209], v[8:9], v[202:203]
	ds_read_b128 v[206:209], v57 offset:16256
	v_add_f32_e32 v248, v248, v249
	v_pk_fma_f32 v[250:251], v[210:211], v[10:11], v[250:251]
	v_pk_fma_f32 v[202:203], v[212:213], v[12:13], v[202:203]
	ds_read_b128 v[210:213], v57 offset:16272
	v_mad_u32_u24 v61, v55, 59, v51
	ds_read_u16 v59, v61
	ds_read_b32 v204, v53 offset:236
	v_lshlrev_b32_e32 v227, 16, v227
	v_pk_fma_f32 v[250:251], v[214:215], v[14:15], v[250:251]
	v_pk_fma_f32 v[202:203], v[216:217], v[16:17], v[202:203]
	ds_read_b128 v[214:217], v57 offset:16320
	v_add_f32_e32 v246, v246, v248
	v_pk_fma_f32 v[250:251], v[238:239], v[18:19], v[250:251]
	v_pk_fma_f32 v[202:203], v[240:241], v[20:21], v[202:203]
	v_fma_f32 v108, v226, v227, -v246
	s_waitcnt lgkmcnt(5)
	v_pk_fma_f32 v[250:251], v[242:243], v[22:23], v[250:251]
	v_pk_fma_f32 v[202:203], v[244:245], v[24:25], v[202:203]
	ds_read_b128 v[238:241], v57 offset:16336
	ds_read_b128 v[242:245], v57 offset:16352
	v_pk_fma_f32 v[250:251], v[174:175], v[26:27], v[250:251]
	v_pk_fma_f32 v[202:203], v[176:177], v[28:29], v[202:203]
	ds_read_b128 v[174:177], v57 offset:16368
	v_pk_fma_f32 v[250:251], v[178:179], v[30:31], v[250:251]
	v_pk_fma_f32 v[202:203], v[180:181], v[32:33], v[202:203]
	ds_read_b128 v[178:181], v57 offset:16384
	v_pk_fma_f32 v[250:251], v[182:183], v[34:35], v[250:251]
	v_pk_fma_f32 v[202:203], v[184:185], v[36:37], v[202:203]
	ds_read_b128 v[182:185], v57 offset:16400
	v_pk_fma_f32 v[250:251], v[186:187], v[86:87], v[250:251]
	v_pk_fma_f32 v[202:203], v[188:189], v[88:89], v[202:203]
	ds_read_b128 v[186:189], v57 offset:16416
	v_pk_fma_f32 v[250:251], v[190:191], v[90:91], v[250:251]
	v_pk_fma_f32 v[202:203], v[192:193], v[92:93], v[202:203]
	ds_read_b128 v[190:193], v57 offset:16432
	v_pk_fma_f32 v[250:251], v[194:195], v[94:95], v[250:251]
	v_pk_fma_f32 v[202:203], v[196:197], v[96:97], v[202:203]
	ds_read_b128 v[194:197], v57 offset:16448
	v_pk_fma_f32 v[250:251], v[198:199], v[98:99], v[250:251]
	v_pk_fma_f32 v[202:203], v[200:201], v[100:101], v[202:203]
	s_waitcnt lgkmcnt(5)
	v_pk_fma_f32 v[250:251], v[206:207], v[102:103], v[250:251]
	v_pk_fma_f32 v[202:203], v[208:209], v[104:105], v[202:203]
	ds_read_b128 v[198:201], v57 offset:16464
	ds_read_b128 v[206:209], v57 offset:16480
	v_pk_fma_f32 v[250:251], v[210:211], v[106:107], v[250:251]
	v_pk_fma_f32 v[202:203], v[212:213], v[108:109], v[202:203]
	ds_read_b128 v[210:213], v57 offset:16496
	v_pk_fma_f32 v[246:247], v[214:215], v[2:3], 0 op_sel_hi:[1,1,0]
	v_pk_fma_f32 v[248:249], v[216:217], v[4:5], 0 op_sel_hi:[1,1,0]
	ds_read_b128 v[214:217], v57 offset:16512
	v_add_f32_e32 v250, v250, v251
	v_pk_fma_f32 v[246:247], v[238:239], v[6:7], v[246:247]
	v_pk_fma_f32 v[248:249], v[240:241], v[8:9], v[248:249]
	ds_read_b128 v[238:241], v57 offset:16528
	v_add_f32_e32 v202, v202, v203
	v_pk_fma_f32 v[246:247], v[242:243], v[10:11], v[246:247]
	v_pk_fma_f32 v[248:249], v[244:245], v[12:13], v[248:249]
	ds_read_b128 v[242:245], v57 offset:16544
	v_mad_u32_u24 v61, v55, 60, v51
	ds_read_u16 v221, v61
	ds_read_b32 v220, v53 offset:240
	v_lshlrev_b32_e32 v59, 16, v59
	v_pk_fma_f32 v[246:247], v[174:175], v[14:15], v[246:247]
	v_pk_fma_f32 v[248:249], v[176:177], v[16:17], v[248:249]
	v_add_f32_e32 v250, v250, v202
	s_waitcnt lgkmcnt(5)
	v_pk_fma_f32 v[246:247], v[178:179], v[18:19], v[246:247]
	v_pk_fma_f32 v[248:249], v[180:181], v[20:21], v[248:249]
	ds_read_b128 v[174:177], v57 offset:16592
	ds_read_b128 v[178:181], v57 offset:16608
	v_fma_f32 v109, v204, v59, -v250
	v_pk_fma_f32 v[246:247], v[182:183], v[22:23], v[246:247]
	v_pk_fma_f32 v[248:249], v[184:185], v[24:25], v[248:249]
	ds_read_b128 v[182:185], v57 offset:16624
	v_pk_fma_f32 v[246:247], v[186:187], v[26:27], v[246:247]
	v_pk_fma_f32 v[248:249], v[188:189], v[28:29], v[248:249]
	ds_read_b128 v[186:189], v57 offset:16640
	v_pk_fma_f32 v[246:247], v[190:191], v[30:31], v[246:247]
	v_pk_fma_f32 v[248:249], v[192:193], v[32:33], v[248:249]
	ds_read_b128 v[190:193], v57 offset:16656
	v_pk_fma_f32 v[246:247], v[194:195], v[34:35], v[246:247]
	v_pk_fma_f32 v[248:249], v[196:197], v[36:37], v[248:249]
	ds_read_b128 v[194:197], v57 offset:16672
	v_pk_fma_f32 v[246:247], v[198:199], v[86:87], v[246:247]
	v_pk_fma_f32 v[248:249], v[200:201], v[88:89], v[248:249]
	ds_read_b128 v[198:201], v57 offset:16688
	v_pk_fma_f32 v[246:247], v[206:207], v[90:91], v[246:247]
	v_pk_fma_f32 v[248:249], v[208:209], v[92:93], v[248:249]
	ds_read_b128 v[206:209], v57 offset:16704
	v_pk_fma_f32 v[246:247], v[210:211], v[94:95], v[246:247]
	v_pk_fma_f32 v[248:249], v[212:213], v[96:97], v[248:249]
	s_waitcnt lgkmcnt(5)
	v_pk_fma_f32 v[246:247], v[214:215], v[98:99], v[246:247]
	v_pk_fma_f32 v[248:249], v[216:217], v[100:101], v[248:249]
	ds_read_b128 v[210:213], v57 offset:16720
	ds_read_b128 v[214:217], v57 offset:16736
	v_pk_fma_f32 v[246:247], v[238:239], v[102:103], v[246:247]
	v_pk_fma_f32 v[248:249], v[240:241], v[104:105], v[248:249]
	ds_read_b128 v[238:241], v57 offset:16752
	v_pk_fma_f32 v[246:247], v[242:243], v[106:107], v[246:247]
	v_pk_fma_f32 v[248:249], v[244:245], v[108:109], v[248:249]
	ds_read_b128 v[242:245], v57 offset:16768
	v_pk_fma_f32 v[250:251], v[174:175], v[2:3], 0 op_sel_hi:[1,1,0]
	v_pk_fma_f32 v[202:203], v[176:177], v[4:5], 0 op_sel_hi:[1,1,0]
	ds_read_b128 v[174:177], v57 offset:16784
	v_add_f32_e32 v246, v246, v247
	v_pk_fma_f32 v[250:251], v[178:179], v[6:7], v[250:251]
	v_pk_fma_f32 v[202:203], v[180:181], v[8:9], v[202:203]
	ds_read_b128 v[178:181], v57 offset:16800
	v_add_f32_e32 v248, v248, v249
	v_pk_fma_f32 v[250:251], v[182:183], v[10:11], v[250:251]
	v_pk_fma_f32 v[202:203], v[184:185], v[12:13], v[202:203]
	ds_read_b128 v[182:185], v57 offset:16816
	v_lshlrev_b32_e32 v221, 16, v221
	s_waitcnt lgkmcnt(5)
	v_pk_fma_f32 v[250:251], v[186:187], v[14:15], v[250:251]
	v_pk_fma_f32 v[202:203], v[188:189], v[16:17], v[202:203]
	ds_read_b128 v[186:189], v57 offset:16832
	v_mad_u32_u24 v61, v55, 61, v51
	ds_read_u16 v227, v61
	ds_read_b32 v226, v53 offset:244
	v_add_f32_e32 v246, v246, v248
	v_pk_fma_f32 v[250:251], v[190:191], v[18:19], v[250:251]
	v_pk_fma_f32 v[202:203], v[192:193], v[20:21], v[202:203]
	ds_read_b128 v[190:193], v57 offset:16864
	v_fma_f32 v110, v220, v221, -v246
	v_pk_fma_f32 v[250:251], v[194:195], v[22:23], v[250:251]
	v_pk_fma_f32 v[202:203], v[196:197], v[24:25], v[202:203]
	ds_read_b128 v[194:197], v57 offset:16880
	v_pk_fma_f32 v[250:251], v[198:199], v[26:27], v[250:251]
	v_pk_fma_f32 v[202:203], v[200:201], v[28:29], v[202:203]
	ds_read_b128 v[198:201], v57 offset:16896
	v_pk_fma_f32 v[250:251], v[206:207], v[30:31], v[250:251]
	v_pk_fma_f32 v[202:203], v[208:209], v[32:33], v[202:203]
	ds_read_b128 v[206:209], v57 offset:16912
	v_pk_fma_f32 v[250:251], v[210:211], v[34:35], v[250:251]
	v_pk_fma_f32 v[202:203], v[212:213], v[36:37], v[202:203]
	ds_read_b128 v[210:213], v57 offset:16928
	v_pk_fma_f32 v[250:251], v[214:215], v[86:87], v[250:251]
	v_pk_fma_f32 v[202:203], v[216:217], v[88:89], v[202:203]
	s_waitcnt lgkmcnt(5)
	v_pk_fma_f32 v[250:251], v[238:239], v[90:91], v[250:251]
	v_pk_fma_f32 v[202:203], v[240:241], v[92:93], v[202:203]
	ds_read_b128 v[214:217], v57 offset:16944
	ds_read_b128 v[238:241], v57 offset:16960
	v_pk_fma_f32 v[250:251], v[242:243], v[94:95], v[250:251]
	v_pk_fma_f32 v[202:203], v[244:245], v[96:97], v[202:203]
	ds_read_b128 v[242:245], v57 offset:16976
	v_pk_fma_f32 v[250:251], v[174:175], v[98:99], v[250:251]
	v_pk_fma_f32 v[202:203], v[176:177], v[100:101], v[202:203]
	ds_read_b128 v[174:177], v57 offset:16992
	v_pk_fma_f32 v[250:251], v[178:179], v[102:103], v[250:251]
	v_pk_fma_f32 v[202:203], v[180:181], v[104:105], v[202:203]
	ds_read_b128 v[178:181], v57 offset:17008
	v_pk_fma_f32 v[250:251], v[182:183], v[106:107], v[250:251]
	v_pk_fma_f32 v[202:203], v[184:185], v[108:109], v[202:203]
	ds_read_b128 v[182:185], v57 offset:17024
	v_pk_fma_f32 v[250:251], v[186:187], v[110:111], v[250:251]
	v_pk_fma_f32 v[202:203], v[188:189], v[112:113], v[202:203]
	ds_read_b128 v[186:189], v57 offset:17040
	s_waitcnt lgkmcnt(5)
	v_pk_fma_f32 v[246:247], v[190:191], v[2:3], 0 op_sel_hi:[1,1,0]
	v_pk_fma_f32 v[248:249], v[192:193], v[4:5], 0 op_sel_hi:[1,1,0]
	ds_read_b128 v[190:193], v57 offset:17056
	v_add_f32_e32 v250, v250, v251
	v_pk_fma_f32 v[246:247], v[194:195], v[6:7], v[246:247]
	v_pk_fma_f32 v[248:249], v[196:197], v[8:9], v[248:249]
	ds_read_b128 v[194:197], v57 offset:17072
	v_add_f32_e32 v202, v202, v203
	v_pk_fma_f32 v[246:247], v[198:199], v[10:11], v[246:247]
	v_pk_fma_f32 v[248:249], v[200:201], v[12:13], v[248:249]
	ds_read_b128 v[198:201], v57 offset:17088
	v_lshlrev_b32_e32 v227, 16, v227
	v_pk_fma_f32 v[246:247], v[206:207], v[14:15], v[246:247]
	v_pk_fma_f32 v[248:249], v[208:209], v[16:17], v[248:249]
	ds_read_b128 v[206:209], v57 offset:17104
	v_mad_u32_u24 v61, v55, 62, v51
	ds_read_u16 v59, v61
	ds_read_b32 v204, v53 offset:248
	v_add_f32_e32 v250, v250, v202
	v_pk_fma_f32 v[246:247], v[210:211], v[18:19], v[246:247]
	v_pk_fma_f32 v[248:249], v[212:213], v[20:21], v[248:249]
	ds_read_b128 v[210:213], v57 offset:17136
	v_fma_f32 v111, v226, v227, -v250
	v_pk_fma_f32 v[246:247], v[214:215], v[22:23], v[246:247]
	v_pk_fma_f32 v[248:249], v[216:217], v[24:25], v[248:249]
	ds_read_b128 v[214:217], v57 offset:17152
	v_pk_fma_f32 v[246:247], v[238:239], v[26:27], v[246:247]
	v_pk_fma_f32 v[248:249], v[240:241], v[28:29], v[248:249]
	s_waitcnt lgkmcnt(5)
	v_pk_fma_f32 v[246:247], v[242:243], v[30:31], v[246:247]
	v_pk_fma_f32 v[248:249], v[244:245], v[32:33], v[248:249]
	ds_read_b128 v[238:241], v57 offset:17168
	ds_read_b128 v[242:245], v57 offset:17184
	v_pk_fma_f32 v[246:247], v[174:175], v[34:35], v[246:247]
	v_pk_fma_f32 v[248:249], v[176:177], v[36:37], v[248:249]
	ds_read_b128 v[174:177], v57 offset:17200
	v_pk_fma_f32 v[246:247], v[178:179], v[86:87], v[246:247]
	v_pk_fma_f32 v[248:249], v[180:181], v[88:89], v[248:249]
	ds_read_b128 v[178:181], v57 offset:17216
	v_pk_fma_f32 v[246:247], v[182:183], v[90:91], v[246:247]
	v_pk_fma_f32 v[248:249], v[184:185], v[92:93], v[248:249]
	ds_read_b128 v[182:185], v57 offset:17232
	v_pk_fma_f32 v[246:247], v[186:187], v[94:95], v[246:247]
	v_pk_fma_f32 v[248:249], v[188:189], v[96:97], v[248:249]
	ds_read_b128 v[186:189], v57 offset:17248
	v_pk_fma_f32 v[246:247], v[190:191], v[98:99], v[246:247]
	v_pk_fma_f32 v[248:249], v[192:193], v[100:101], v[248:249]
	ds_read_b128 v[190:193], v57 offset:17264
	v_pk_fma_f32 v[246:247], v[194:195], v[102:103], v[246:247]
	v_pk_fma_f32 v[248:249], v[196:197], v[104:105], v[248:249]
	ds_read_b128 v[194:197], v57 offset:17280
	v_pk_fma_f32 v[246:247], v[198:199], v[106:107], v[246:247]
	v_pk_fma_f32 v[248:249], v[200:201], v[108:109], v[248:249]
	s_waitcnt lgkmcnt(5)
	v_pk_fma_f32 v[246:247], v[206:207], v[110:111], v[246:247]
	v_pk_fma_f32 v[248:249], v[208:209], v[112:113], v[248:249]
	ds_read_b128 v[198:201], v57 offset:17296
	ds_read_b128 v[206:209], v57 offset:17312
	v_pk_fma_f32 v[250:251], v[210:211], v[2:3], 0 op_sel_hi:[1,1,0]
	v_pk_fma_f32 v[202:203], v[212:213], v[4:5], 0 op_sel_hi:[1,1,0]
	ds_read_b128 v[210:213], v57 offset:17328
	v_add_f32_e32 v246, v246, v247
	v_pk_fma_f32 v[250:251], v[214:215], v[6:7], v[250:251]
	v_pk_fma_f32 v[202:203], v[216:217], v[8:9], v[202:203]
	ds_read_b128 v[214:217], v57 offset:17344
	v_add_f32_e32 v248, v248, v249
	v_pk_fma_f32 v[250:251], v[238:239], v[10:11], v[250:251]
	v_pk_fma_f32 v[202:203], v[240:241], v[12:13], v[202:203]
	ds_read_b128 v[238:241], v57 offset:17360
	v_lshlrev_b32_e32 v59, 16, v59
	v_pk_fma_f32 v[250:251], v[242:243], v[14:15], v[250:251]
	v_pk_fma_f32 v[202:203], v[244:245], v[16:17], v[202:203]
	ds_read_b128 v[242:245], v57 offset:17376
	v_mad_u32_u24 v61, v55, 63, v51
	ds_read_u16 v221, v61
	ds_read_b32 v220, v53 offset:252
	v_add_f32_e32 v246, v246, v248
	v_pk_fma_f32 v[250:251], v[174:175], v[18:19], v[250:251]
	v_pk_fma_f32 v[202:203], v[176:177], v[20:21], v[202:203]
	v_fma_f32 v112, v204, v59, -v246
	s_waitcnt lgkmcnt(5)
	v_pk_fma_f32 v[250:251], v[178:179], v[22:23], v[250:251]
	v_pk_fma_f32 v[202:203], v[180:181], v[24:25], v[202:203]
	v_pk_fma_f32 v[250:251], v[182:183], v[26:27], v[250:251]
	v_pk_fma_f32 v[202:203], v[184:185], v[28:29], v[202:203]
	v_pk_fma_f32 v[250:251], v[186:187], v[30:31], v[250:251]
	v_pk_fma_f32 v[202:203], v[188:189], v[32:33], v[202:203]
	v_pk_fma_f32 v[250:251], v[190:191], v[34:35], v[250:251]
	v_pk_fma_f32 v[202:203], v[192:193], v[36:37], v[202:203]
	v_pk_fma_f32 v[250:251], v[194:195], v[86:87], v[250:251]
	v_pk_fma_f32 v[202:203], v[196:197], v[88:89], v[202:203]
	v_pk_fma_f32 v[250:251], v[198:199], v[90:91], v[250:251]
	v_pk_fma_f32 v[202:203], v[200:201], v[92:93], v[202:203]
	v_pk_fma_f32 v[250:251], v[206:207], v[94:95], v[250:251]
	v_pk_fma_f32 v[202:203], v[208:209], v[96:97], v[202:203]
	v_pk_fma_f32 v[250:251], v[210:211], v[98:99], v[250:251]
	v_pk_fma_f32 v[202:203], v[212:213], v[100:101], v[202:203]
	s_waitcnt lgkmcnt(4)
	v_pk_fma_f32 v[250:251], v[214:215], v[102:103], v[250:251]
	v_pk_fma_f32 v[202:203], v[216:217], v[104:105], v[202:203]
	s_waitcnt lgkmcnt(3)
	v_pk_fma_f32 v[250:251], v[238:239], v[106:107], v[250:251]
	v_pk_fma_f32 v[202:203], v[240:241], v[108:109], v[202:203]
	s_waitcnt lgkmcnt(2)
	v_pk_fma_f32 v[250:251], v[242:243], v[110:111], v[250:251]
	v_pk_fma_f32 v[202:203], v[244:245], v[112:113], v[202:203]
	v_add_f32_e32 v250, v250, v251
	v_add_f32_e32 v202, v202, v203
	s_waitcnt lgkmcnt(0)
	v_lshlrev_b32_e32 v221, 16, v221
	v_add_f32_e32 v250, v250, v202
	v_fma_f32 v2, v220, v221, -v250
	s_and_saveexec_b64 s[0:1], vcc
	s_xor_b64 s[0:1], exec, s[0:1]
	s_cbranch_execz .LBB0_194
	v_lshl_add_u32 v47, v47, 1, 0
	v_bfe_u32 v49, v0, 16, 1
	v_add_u32_e32 v47, 0x1d900, v47
	v_add3_u32 v0, v0, v49, s33
	ds_write_b16_d16_hi v47, v0
	v_bfe_u32 v0, v3, 16, 1
	v_add3_u32 v0, v3, v0, s33
	ds_write_b16_d16_hi v47, v0 offset:256
	v_bfe_u32 v0, v4, 16, 1
	v_add3_u32 v0, v4, v0, s33
	ds_write_b16_d16_hi v47, v0 offset:512
	v_bfe_u32 v0, v5, 16, 1
	v_add3_u32 v0, v5, v0, s33
	ds_write_b16_d16_hi v47, v0 offset:768
	v_bfe_u32 v0, v6, 16, 1
	v_add3_u32 v0, v6, v0, s33
	ds_write_b16_d16_hi v47, v0 offset:1024
	v_bfe_u32 v0, v7, 16, 1
	v_add3_u32 v0, v7, v0, s33
	ds_write_b16_d16_hi v47, v0 offset:1280
	v_bfe_u32 v0, v8, 16, 1
	v_add3_u32 v0, v8, v0, s33
	ds_write_b16_d16_hi v47, v0 offset:1536
	v_bfe_u32 v0, v9, 16, 1
	v_add3_u32 v0, v9, v0, s33
	ds_write_b16_d16_hi v47, v0 offset:1792
	v_bfe_u32 v0, v10, 16, 1
	v_add3_u32 v0, v10, v0, s33
	ds_write_b16_d16_hi v47, v0 offset:2048
	v_bfe_u32 v0, v11, 16, 1
	v_add3_u32 v0, v11, v0, s33
	ds_write_b16_d16_hi v47, v0 offset:2304
	v_bfe_u32 v0, v12, 16, 1
	v_add3_u32 v0, v12, v0, s33
	ds_write_b16_d16_hi v47, v0 offset:2560
	v_bfe_u32 v0, v13, 16, 1
	v_add3_u32 v0, v13, v0, s33
	ds_write_b16_d16_hi v47, v0 offset:2816
	v_bfe_u32 v0, v14, 16, 1
	v_add3_u32 v0, v14, v0, s33
	ds_write_b16_d16_hi v47, v0 offset:3072
	v_bfe_u32 v0, v15, 16, 1
	v_add3_u32 v0, v15, v0, s33
	ds_write_b16_d16_hi v47, v0 offset:3328
	v_bfe_u32 v0, v16, 16, 1
	v_add3_u32 v0, v16, v0, s33
	ds_write_b16_d16_hi v47, v0 offset:3584
	v_bfe_u32 v0, v17, 16, 1
	v_add3_u32 v0, v17, v0, s33
	ds_write_b16_d16_hi v47, v0 offset:3840
	v_bfe_u32 v0, v18, 16, 1
	v_add3_u32 v0, v18, v0, s33
	ds_write_b16_d16_hi v47, v0 offset:4096
	v_bfe_u32 v0, v19, 16, 1
	v_add3_u32 v0, v19, v0, s33
	ds_write_b16_d16_hi v47, v0 offset:4352
	v_bfe_u32 v0, v20, 16, 1
	v_add3_u32 v0, v20, v0, s33
	ds_write_b16_d16_hi v47, v0 offset:4608
	v_bfe_u32 v0, v21, 16, 1
	v_add3_u32 v0, v21, v0, s33
	ds_write_b16_d16_hi v47, v0 offset:4864
	v_bfe_u32 v0, v22, 16, 1
	v_add3_u32 v0, v22, v0, s33
	ds_write_b16_d16_hi v47, v0 offset:5120
	v_bfe_u32 v0, v23, 16, 1
	v_add3_u32 v0, v23, v0, s33
	ds_write_b16_d16_hi v47, v0 offset:5376
	v_bfe_u32 v0, v24, 16, 1
	v_add3_u32 v0, v24, v0, s33
	ds_write_b16_d16_hi v47, v0 offset:5632
	v_bfe_u32 v0, v25, 16, 1
	v_add3_u32 v0, v25, v0, s33
	ds_write_b16_d16_hi v47, v0 offset:5888
	v_bfe_u32 v0, v26, 16, 1
	v_add3_u32 v0, v26, v0, s33
	ds_write_b16_d16_hi v47, v0 offset:6144
	v_bfe_u32 v0, v27, 16, 1
	v_add3_u32 v0, v27, v0, s33
	ds_write_b16_d16_hi v47, v0 offset:6400
	v_bfe_u32 v0, v28, 16, 1
	v_add3_u32 v0, v28, v0, s33
	ds_write_b16_d16_hi v47, v0 offset:6656
	v_bfe_u32 v0, v29, 16, 1
	v_add3_u32 v0, v29, v0, s33
	ds_write_b16_d16_hi v47, v0 offset:6912
	v_bfe_u32 v0, v30, 16, 1
	v_add3_u32 v0, v30, v0, s33
	ds_write_b16_d16_hi v47, v0 offset:7168
	v_bfe_u32 v0, v31, 16, 1
	v_add3_u32 v0, v31, v0, s33
	ds_write_b16_d16_hi v47, v0 offset:7424
	v_bfe_u32 v0, v32, 16, 1
	v_add3_u32 v0, v32, v0, s33
	ds_write_b16_d16_hi v47, v0 offset:7680
	v_bfe_u32 v0, v33, 16, 1
	v_add3_u32 v0, v33, v0, s33
	ds_write_b16_d16_hi v47, v0 offset:7936
	v_bfe_u32 v0, v34, 16, 1
	v_add3_u32 v0, v34, v0, s33
	ds_write_b16_d16_hi v47, v0 offset:8192
	v_bfe_u32 v0, v35, 16, 1
	v_add3_u32 v0, v35, v0, s33
	ds_write_b16_d16_hi v47, v0 offset:8448
	v_bfe_u32 v0, v36, 16, 1
	v_add3_u32 v0, v36, v0, s33
	ds_write_b16_d16_hi v47, v0 offset:8704
	v_bfe_u32 v0, v37, 16, 1
	v_add3_u32 v0, v37, v0, s33
	ds_write_b16_d16_hi v47, v0 offset:8960
	v_bfe_u32 v0, v86, 16, 1
	v_add3_u32 v0, v86, v0, s33
	ds_write_b16_d16_hi v47, v0 offset:9216
	v_bfe_u32 v0, v87, 16, 1
	v_add3_u32 v0, v87, v0, s33
	ds_write_b16_d16_hi v47, v0 offset:9472
	v_bfe_u32 v0, v88, 16, 1
	v_add3_u32 v0, v88, v0, s33
	ds_write_b16_d16_hi v47, v0 offset:9728
	v_bfe_u32 v0, v89, 16, 1
	v_add3_u32 v0, v89, v0, s33
	ds_write_b16_d16_hi v47, v0 offset:9984
	v_bfe_u32 v0, v90, 16, 1
	v_add3_u32 v0, v90, v0, s33
	ds_write_b16_d16_hi v47, v0 offset:10240
	v_bfe_u32 v0, v91, 16, 1
	v_add3_u32 v0, v91, v0, s33
	ds_write_b16_d16_hi v47, v0 offset:10496
	v_bfe_u32 v0, v92, 16, 1
	v_add3_u32 v0, v92, v0, s33
	ds_write_b16_d16_hi v47, v0 offset:10752
	v_bfe_u32 v0, v93, 16, 1
	v_add3_u32 v0, v93, v0, s33
	ds_write_b16_d16_hi v47, v0 offset:11008
	v_bfe_u32 v0, v94, 16, 1
	v_add3_u32 v0, v94, v0, s33
	ds_write_b16_d16_hi v47, v0 offset:11264
	v_bfe_u32 v0, v95, 16, 1
	v_add3_u32 v0, v95, v0, s33
	ds_write_b16_d16_hi v47, v0 offset:11520
	v_bfe_u32 v0, v96, 16, 1
	v_add3_u32 v0, v96, v0, s33
	ds_write_b16_d16_hi v47, v0 offset:11776
	v_bfe_u32 v0, v97, 16, 1
	v_add3_u32 v0, v97, v0, s33
	ds_write_b16_d16_hi v47, v0 offset:12032
	v_bfe_u32 v0, v98, 16, 1
	v_add3_u32 v0, v98, v0, s33
	ds_write_b16_d16_hi v47, v0 offset:12288
	v_bfe_u32 v0, v99, 16, 1
	v_add3_u32 v0, v99, v0, s33
	ds_write_b16_d16_hi v47, v0 offset:12544
	v_bfe_u32 v0, v100, 16, 1
	v_add3_u32 v0, v100, v0, s33
	ds_write_b16_d16_hi v47, v0 offset:12800
	v_bfe_u32 v0, v101, 16, 1
	v_add3_u32 v0, v101, v0, s33
	ds_write_b16_d16_hi v47, v0 offset:13056
	v_bfe_u32 v0, v102, 16, 1
	v_add3_u32 v0, v102, v0, s33
	ds_write_b16_d16_hi v47, v0 offset:13312
	v_bfe_u32 v0, v103, 16, 1
	v_add3_u32 v0, v103, v0, s33
	ds_write_b16_d16_hi v47, v0 offset:13568
	v_bfe_u32 v0, v104, 16, 1
	v_add3_u32 v0, v104, v0, s33
	ds_write_b16_d16_hi v47, v0 offset:13824
	v_bfe_u32 v0, v105, 16, 1
	v_add3_u32 v0, v105, v0, s33
	ds_write_b16_d16_hi v47, v0 offset:14080
	v_bfe_u32 v0, v106, 16, 1
	v_add3_u32 v0, v106, v0, s33
	ds_write_b16_d16_hi v47, v0 offset:14336
	v_bfe_u32 v0, v107, 16, 1
	v_add3_u32 v0, v107, v0, s33
	ds_write_b16_d16_hi v47, v0 offset:14592
	v_bfe_u32 v0, v108, 16, 1
	v_add3_u32 v0, v108, v0, s33
	ds_write_b16_d16_hi v47, v0 offset:14848
	v_bfe_u32 v0, v109, 16, 1
	v_add3_u32 v0, v109, v0, s33
	ds_write_b16_d16_hi v47, v0 offset:15104
	v_bfe_u32 v0, v110, 16, 1
	v_add3_u32 v0, v110, v0, s33
	ds_write_b16_d16_hi v47, v0 offset:15360
	v_bfe_u32 v0, v111, 16, 1
	v_add3_u32 v0, v111, v0, s33
	ds_write_b16_d16_hi v47, v0 offset:15616
	v_bfe_u32 v0, v112, 16, 1
	v_add3_u32 v0, v112, v0, s33
	ds_write_b16_d16_hi v47, v0 offset:15872
	v_bfe_u32 v0, v2, 16, 1
	v_add3_u32 v0, v2, v0, s33
	ds_write_b16_d16_hi v47, v0 offset:16128

.LBB0_516:
	s_waitcnt lgkmcnt(0)
	s_and_b32 vcc_lo, s31, 6
	s_cmp_eq_u32 vcc_lo, 2
	s_cbranch_scc1 .Lscan_owave
	s_waitcnt vmcnt(0)
	s_branch .Lscan_waited
.Lscan_owave:
	s_waitcnt vmcnt(2)
.Lscan_waited:
	v_mov_b64_e32 v[116:117], v[80:81]
	v_mov_b64_e32 v[120:121], v[76:77]
	v_mov_b64_e32 v[124:125], v[72:73]
	v_mov_b64_e32 v[128:129], v[68:69]
	v_mov_b64_e32 v[132:133], v[64:65]
	v_mov_b64_e32 v[136:137], v[60:61]
	v_mov_b64_e32 v[140:141], v[56:57]
	v_mov_b64_e32 v[144:145], v[52:53]
	v_mov_b64_e32 v[100:101], v[96:97]
	v_mov_b64_e32 v[104:105], v[92:93]
	v_mov_b64_e32 v[108:109], v[88:89]
	v_mov_b64_e32 v[112:113], v[84:85]
	v_mov_b64_e32 v[2:3], v[34:35]
	v_mov_b64_e32 v[114:115], v[78:79]
	v_mov_b64_e32 v[118:119], v[74:75]
	v_mov_b64_e32 v[122:123], v[70:71]
	v_mov_b64_e32 v[126:127], v[66:67]
	v_mov_b64_e32 v[130:131], v[62:63]
	v_mov_b64_e32 v[134:135], v[58:59]
	v_mov_b64_e32 v[138:139], v[54:55]
	v_mov_b64_e32 v[142:143], v[50:51]
	v_mov_b64_e32 v[98:99], v[94:95]
	v_mov_b64_e32 v[102:103], v[90:91]
	v_mov_b64_e32 v[106:107], v[86:87]
	v_mov_b64_e32 v[110:111], v[82:83]
	v_mov_b64_e32 v[210:211], v[194:195]
	v_mov_b64_e32 v[212:213], v[192:193]
	v_mov_b64_e32 v[214:215], v[190:191]
	v_mov_b64_e32 v[216:217], v[188:189]
	v_mov_b64_e32 v[4:5], v[36:37]
	v_mov_b64_e32 v[6:7], v[38:39]
	v_mov_b64_e32 v[8:9], v[40:41]
	v_mov_b64_e32 v[10:11], v[42:43]
	v_mov_b64_e32 v[12:13], v[44:45]
	v_mov_b64_e32 v[14:15], v[46:47]
	v_mov_b64_e32 v[16:17], v[48:49]
	v_mov_b32_e32 v204, v198
	s_mov_b64 s[0:1], -1
	s_and_b64 vcc, exec, s[6:7]
	s_cbranch_vccz .LBB0_522

.LBB0_519:
	v_mov_b64_e32 v[50:51], v[142:143]
	v_mov_b64_e32 v[54:55], v[138:139]
	v_mov_b64_e32 v[58:59], v[134:135]
	v_mov_b64_e32 v[62:63], v[130:131]
	v_mov_b64_e32 v[66:67], v[126:127]
	v_mov_b64_e32 v[70:71], v[122:123]
	v_mov_b64_e32 v[74:75], v[118:119]
	v_mov_b64_e32 v[78:79], v[114:115]
	s_andn2_b64 vcc, exec, s[0:1]
	v_mov_b64_e32 v[52:53], v[144:145]
	v_mov_b64_e32 v[56:57], v[140:141]
	v_mov_b64_e32 v[60:61], v[136:137]
	v_mov_b64_e32 v[64:65], v[132:133]
	v_mov_b64_e32 v[68:69], v[128:129]
	v_mov_b64_e32 v[72:73], v[124:125]
	v_mov_b64_e32 v[76:77], v[120:121]
	v_mov_b64_e32 v[80:81], v[116:117]
	s_cbranch_vccnz .LBB0_521
	v_lshl_add_u64 v[18:19], s[58:59], 0, v[206:207]
	v_add_co_u32_e32 v18, vcc, 0xf880000, v18
	s_waitcnt vmcnt(2) lgkmcnt(0)
	v_mov_b32_e32 v198, v204
	v_addc_co_u32_e32 v19, vcc, 0, v19, vcc
	global_load_dwordx4 v[50:53], v[18:19], off
	global_load_dwordx4 v[54:57], v[18:19], off offset:32
	global_load_dwordx4 v[58:61], v[18:19], off offset:64
	global_load_dwordx4 v[62:65], v[18:19], off offset:96
	global_load_dwordx4 v[66:69], v[18:19], off offset:128
	global_load_dwordx4 v[70:73], v[18:19], off offset:160
	global_load_dwordx4 v[74:77], v[18:19], off offset:192
	global_load_dwordx4 v[78:81], v[18:19], off offset:224
	v_lshl_add_u64 v[18:19], s[58:59], 0, v[200:201]
	v_add_co_u32_e32 v18, vcc, 0x23802000, v18
	s_nop 1
	v_addc_co_u32_e32 v19, vcc, 0, v19, vcc
	global_load_dwordx4 v[82:85], v[18:19], off
	global_load_dwordx4 v[86:89], v[18:19], off offset:32
	global_load_dwordx4 v[90:93], v[18:19], off offset:64
	global_load_dwordx4 v[94:97], v[18:19], off offset:96
